# GEMM k-loops (21 instances): next-next tile global prefetch woven into the preceding 32-MFMA block instead of a burst between MFMA blocks
# speedup vs baseline: 1.0905x; 1.0100x over previous
; #define LD_AF(dst, ks_) _Pragma("unroll") for (int i = 0; i < 8; ++i) dst[i] = *(const h8*)(sA + i * 16 * G_LD + (ks_) * 32)
; #define LD_BF(dst, ks_, nh_) _Pragma("unroll") for (int i = 0; i < 4; ++i) dst[i] = *(const h8*)(sB + ((nh_) * 4 + i) * 16 * G_LD + (ks_) * 32)
; #define MMA_BLK(afx, bfx, nh_) _Pragma("unroll") for (int mi = 0; mi < 8; ++mi) _Pragma("unroll") for (int ni = 0; ni < 4; ++ni) mfma16_acc(acc[mi][(nh_) * 4 + ni], bfx[ni], afx[mi])
; template <class Epi>
; __device__ __forceinline__ void gemm_run(const GemmArgs g, Epi epi, char* smem) {
;     ...
;       LD_AF(afA, 0); LD_BF(bfA, 0, 0);
;       if (kt + 1 < nk) {
; #pragma unroll
;         for (int i = 0; i < 8; ++i) *(u4*)(st + (lr + 32 * i) * G_LD + lcw) = ra[i];
;       }
;       __builtin_amdgcn_sched_barrier(0);
;       LD_BF(bfB, 0, 1);
;       MMA_BLK(afA, bfA, 0);
;       __builtin_amdgcn_sched_barrier(0);
;       if (kt + 1 < nk) {
; #pragma unroll
;         for (int i = 0; i < 8; ++i) *(u4*)(st + (256 + lr + 32 * i) * G_LD + lcw) = rb[i];
;       }
;       LD_AF(afB, 1); LD_BF(bfA, 1, 0);
;       MMA_BLK(afA, bfB, 1);
.LBB0_197:
	s_bitcmp1_b32 s11, 0
	s_cselect_b32 s7, 0x12000, 0
	s_add_i32 s7, s7, 16
	v_add3_u32 v56, s7, v100, v109
	v_add3_u32 v94, s7, v101, v109
	ds_read_b128 v[4:7], v56 offset:13824
	ds_read_b128 v[16:19], v94 offset:36864
	ds_read_b128 v[12:15], v94 offset:39168
	ds_read_b128 v[8:11], v94 offset:41472
	ds_read_b128 v[0:3], v94 offset:43776
	ds_read_b128 v[76:79], v56
	ds_read_b128 v[72:75], v56 offset:2304
	ds_read_b128 v[52:55], v56 offset:4608
	ds_read_b128 v[44:47], v56 offset:6912
	ds_read_b128 v[48:51], v56 offset:9216
	ds_read_b128 v[40:43], v56 offset:11520
	ds_read_b128 v[32:35], v56 offset:16128
	s_mov_b32 s6, s11
	s_add_i32 s11, s11, 1
	s_bitcmp1_b32 s11, 0
	s_cselect_b32 s7, 0x12000, 0
	v_add_u32_e32 v20, s7, v99
	v_add_u32_e32 v21, v20, v104
	s_waitcnt vmcnt(15)
	ds_write_b128 v21, v[110:113]
	s_waitcnt vmcnt(13)
	ds_write_b128 v21, v[118:121] offset:4608
	s_waitcnt vmcnt(11)
	ds_write_b128 v21, v[126:129] offset:9216
	s_waitcnt vmcnt(9)
	ds_write_b128 v21, v[138:141] offset:13824
	s_waitcnt vmcnt(7)
	ds_write_b128 v21, v[146:149] offset:18432
	s_waitcnt vmcnt(5)
	ds_write_b128 v21, v[154:157] offset:23040
	s_waitcnt vmcnt(3)
	ds_write_b128 v21, v[162:165] offset:27648
	s_waitcnt vmcnt(1)
	ds_write_b128 v21, v[170:173] offset:32256
	ds_read_b128 v[178:181], v94 offset:46080
	ds_read_b128 v[88:91], v94 offset:48384
	ds_read_b128 v[84:87], v94 offset:50688
	ds_read_b128 v[80:83], v94 offset:52992
	s_waitcnt lgkmcnt(14)
	v_mfma_f32_16x16x32_f16 a[252:255], v[16:19], v[76:79], a[252:255]
	v_mfma_f32_16x16x32_f16 a[240:243], v[12:15], v[76:79], a[240:243]
	v_mfma_f32_16x16x32_f16 a[232:235], v[8:11], v[76:79], a[232:235]
	v_mfma_f32_16x16x32_f16 a[224:227], v[0:3], v[76:79], a[224:227]
	v_mfma_f32_16x16x32_f16 a[216:219], v[16:19], v[72:75], a[216:219]
	v_mfma_f32_16x16x32_f16 a[208:211], v[12:15], v[72:75], a[208:211]
	v_mfma_f32_16x16x32_f16 a[200:203], v[8:11], v[72:75], a[200:203]
	v_mfma_f32_16x16x32_f16 a[192:195], v[0:3], v[72:75], a[192:195]
	v_mfma_f32_16x16x32_f16 a[184:187], v[16:19], v[52:55], a[184:187]
	v_mfma_f32_16x16x32_f16 a[176:179], v[12:15], v[52:55], a[176:179]
	v_mfma_f32_16x16x32_f16 a[168:171], v[8:11], v[52:55], a[168:171]
	v_mfma_f32_16x16x32_f16 a[160:163], v[0:3], v[52:55], a[160:163]
	v_mfma_f32_16x16x32_f16 a[152:155], v[16:19], v[44:47], a[152:155]
	v_mfma_f32_16x16x32_f16 a[144:147], v[12:15], v[44:47], a[144:147]
	v_mfma_f32_16x16x32_f16 a[136:139], v[8:11], v[44:47], a[136:139]
	v_mfma_f32_16x16x32_f16 a[128:131], v[0:3], v[44:47], a[128:131]
	v_mfma_f32_16x16x32_f16 a[120:123], v[16:19], v[48:51], a[120:123]
	v_mfma_f32_16x16x32_f16 a[112:115], v[12:15], v[48:51], a[112:115]
	v_mfma_f32_16x16x32_f16 a[104:107], v[8:11], v[48:51], a[104:107]
	v_mfma_f32_16x16x32_f16 a[96:99], v[0:3], v[48:51], a[96:99]
	s_waitcnt lgkmcnt(13)
	v_mfma_f32_16x16x32_f16 a[88:91], v[16:19], v[40:43], a[88:91]
	v_mfma_f32_16x16x32_f16 a[80:83], v[12:15], v[40:43], a[80:83]
	v_mfma_f32_16x16x32_f16 a[72:75], v[8:11], v[40:43], a[72:75]
	v_mfma_f32_16x16x32_f16 a[64:67], v[0:3], v[40:43], a[64:67]
	v_mfma_f32_16x16x32_f16 a[56:59], v[16:19], v[4:7], a[56:59]
	v_mfma_f32_16x16x32_f16 a[48:51], v[12:15], v[4:7], a[48:51]
	v_mfma_f32_16x16x32_f16 a[40:43], v[8:11], v[4:7], a[40:43]
	v_mfma_f32_16x16x32_f16 a[32:35], v[0:3], v[4:7], a[32:35]
	s_waitcnt lgkmcnt(12)
	v_mfma_f32_16x16x32_f16 a[24:27], v[16:19], v[32:35], a[24:27]
	v_mfma_f32_16x16x32_f16 a[20:23], v[12:15], v[32:35], a[20:23]
	v_mfma_f32_16x16x32_f16 a[16:19], v[8:11], v[32:35], a[16:19]
	v_mfma_f32_16x16x32_f16 a[8:11], v[0:3], v[32:35], a[8:11]
	v_add_u32_e32 v0, v20, v105
	ds_write_b128 v21, v[114:117] offset:36864
	ds_write_b128 v21, v[122:125] offset:41472
	ds_write_b128 v21, v[134:137] offset:46080
	ds_write_b128 v21, v[142:145] offset:50688
	ds_write_b128 v21, v[150:153] offset:55296
	ds_write_b128 v21, v[158:161] offset:59904
	ds_write_b128 v21, v[166:169] offset:64512
	s_waitcnt vmcnt(0)
	ds_write_b128 v0, v[174:177]
	ds_read_b128 v[36:39], v56 offset:64
	ds_read_b128 v[28:31], v56 offset:2368
	ds_read_b128 v[24:27], v56 offset:4672
	ds_read_b128 v[20:23], v56 offset:6976
	ds_read_b128 v[16:19], v56 offset:9280
	ds_read_b128 v[12:15], v56 offset:11584
	ds_read_b128 v[8:11], v56 offset:13888
	ds_read_b128 v[0:3], v56 offset:16192
	ds_read_b128 v[56:59], v94 offset:36928
	ds_read_b128 v[60:63], v94 offset:39232
	ds_read_b128 v[64:67], v94 offset:41536
	ds_read_b128 v[68:71], v94 offset:43840
	s_cmp_gt_u32 s6, 29
	s_cbranch_scc1 .Lgw0_nl
; #define MMA_BLK(afx, bfx, nh_) _Pragma("unroll") for (int mi = 0; mi < 8; ++mi) _Pragma("unroll") for (int ni = 0; ni < 4; ++ni) mfma16_acc(acc[mi][(nh_) * 4 + ni], bfx[ni], afx[mi])
; template <class Epi>
; __device__ __forceinline__ void gemm_run(const GemmArgs g, Epi epi, char* smem) {
;     ...
;       MMA_BLK(afA, bfB, 1);
;       __builtin_amdgcn_sched_barrier(0);
;       if (kt + 2 < nk) {
;         const int ko = (kt + 2) * 64;
; #pragma unroll
;         for (int i = 0; i < 8; ++i) { ra[i] = __builtin_amdgcn_raw_buffer_load_b128(Ars, aoff, i * astep + ko * 2, 0); rb[i] = __builtin_amdgcn_raw_buffer_load_b128(Brs, boff, i * bstep + ko * 2, 0); }
;       }
	s_waitcnt lgkmcnt(14)
	v_mfma_f32_16x16x32_f16 a[248:251], v[178:181], v[76:79], a[248:251]
	v_mfma_f32_16x16x32_f16 a[244:247], v[88:91], v[76:79], a[244:247]
	v_mfma_f32_16x16x32_f16 a[236:239], v[84:87], v[76:79], a[236:239]
	s_add_i32 s12, s9, 0xfff20000
	v_mfma_f32_16x16x32_f16 a[228:231], v[80:83], v[76:79], a[228:231]
	s_mov_b32 s6, s22
	v_mfma_f32_16x16x32_f16 a[220:223], v[178:181], v[72:75], a[220:223]
	s_mov_b32 s7, s23
	v_mfma_f32_16x16x32_f16 a[212:215], v[88:91], v[72:75], a[212:215]
	buffer_load_dwordx4 v[110:113], v98, s[20:23], s12 offen
	v_mfma_f32_16x16x32_f16 a[204:207], v[84:87], v[72:75], a[204:207]
	buffer_load_dwordx4 v[114:117], v98, s[4:7], s12 offen
	v_mfma_f32_16x16x32_f16 a[196:199], v[80:83], v[72:75], a[196:199]
	s_add_i32 s12, s9, 0xfff40000
	v_mfma_f32_16x16x32_f16 a[188:191], v[178:181], v[52:55], a[188:191]
	buffer_load_dwordx4 v[118:121], v98, s[20:23], s12 offen
	v_mfma_f32_16x16x32_f16 a[180:183], v[88:91], v[52:55], a[180:183]
	buffer_load_dwordx4 v[122:125], v98, s[4:7], s12 offen
	v_mfma_f32_16x16x32_f16 a[172:175], v[84:87], v[52:55], a[172:175]
	s_add_i32 s12, s9, 0xfff60000
	v_mfma_f32_16x16x32_f16 a[164:167], v[80:83], v[52:55], a[164:167]
	buffer_load_dwordx4 v[126:129], v98, s[20:23], s12 offen
	v_mfma_f32_16x16x32_f16 a[156:159], v[178:181], v[44:47], a[156:159]
	buffer_load_dwordx4 v[134:137], v98, s[4:7], s12 offen
	v_mfma_f32_16x16x32_f16 a[148:151], v[88:91], v[44:47], a[148:151]
	s_add_i32 s12, s9, 0xfff80000
	v_mfma_f32_16x16x32_f16 a[140:143], v[84:87], v[44:47], a[140:143]
	buffer_load_dwordx4 v[138:141], v98, s[20:23], s12 offen
	v_mfma_f32_16x16x32_f16 a[132:135], v[80:83], v[44:47], a[132:135]
	buffer_load_dwordx4 v[142:145], v98, s[4:7], s12 offen
	v_mfma_f32_16x16x32_f16 a[124:127], v[178:181], v[48:51], a[124:127]
	s_add_i32 s12, s9, 0xfffa0000
	v_mfma_f32_16x16x32_f16 a[116:119], v[88:91], v[48:51], a[116:119]
	buffer_load_dwordx4 v[146:149], v98, s[20:23], s12 offen
	v_mfma_f32_16x16x32_f16 a[108:111], v[84:87], v[48:51], a[108:111]
	buffer_load_dwordx4 v[150:153], v98, s[4:7], s12 offen
	v_mfma_f32_16x16x32_f16 a[100:103], v[80:83], v[48:51], a[100:103]
	s_add_i32 s12, s9, 0xfffc0000
	v_mfma_f32_16x16x32_f16 a[92:95], v[178:181], v[40:43], a[92:95]
	buffer_load_dwordx4 v[154:157], v98, s[20:23], s12 offen
	v_mfma_f32_16x16x32_f16 a[84:87], v[88:91], v[40:43], a[84:87]
	buffer_load_dwordx4 v[158:161], v98, s[4:7], s12 offen
	v_mfma_f32_16x16x32_f16 a[76:79], v[84:87], v[40:43], a[76:79]
	s_add_i32 s12, s9, 0xfffe0000
	v_mfma_f32_16x16x32_f16 a[68:71], v[80:83], v[40:43], a[68:71]
	buffer_load_dwordx4 v[162:165], v98, s[20:23], s12 offen
	v_mfma_f32_16x16x32_f16 a[60:63], v[178:181], v[4:7], a[60:63]
	buffer_load_dwordx4 v[166:169], v98, s[4:7], s12 offen
	v_mfma_f32_16x16x32_f16 a[52:55], v[88:91], v[4:7], a[52:55]
	buffer_load_dwordx4 v[170:173], v98, s[20:23], s9 offen
	v_mfma_f32_16x16x32_f16 a[44:47], v[84:87], v[4:7], a[44:47]
	buffer_load_dwordx4 v[174:177], v98, s[4:7], s9 offen
	v_mfma_f32_16x16x32_f16 a[36:39], v[80:83], v[4:7], a[36:39]
	v_mfma_f32_16x16x32_f16 a[28:31], v[178:181], v[32:35], a[28:31]
	v_mfma_f32_16x16x32_f16 a[12:15], v[88:91], v[32:35], a[12:15]
	v_mfma_f32_16x16x32_f16 a[4:7], v[84:87], v[32:35], a[4:7]
	v_mfma_f32_16x16x32_f16 a[0:3], v[80:83], v[32:35], a[0:3]
	s_branch .LBB0_196
.Lgw0_nl:
	s_waitcnt lgkmcnt(14)
	v_mfma_f32_16x16x32_f16 a[248:251], v[178:181], v[76:79], a[248:251]
	v_mfma_f32_16x16x32_f16 a[244:247], v[88:91], v[76:79], a[244:247]
	v_mfma_f32_16x16x32_f16 a[236:239], v[84:87], v[76:79], a[236:239]
	v_mfma_f32_16x16x32_f16 a[228:231], v[80:83], v[76:79], a[228:231]
	v_mfma_f32_16x16x32_f16 a[220:223], v[178:181], v[72:75], a[220:223]
	v_mfma_f32_16x16x32_f16 a[212:215], v[88:91], v[72:75], a[212:215]
	v_mfma_f32_16x16x32_f16 a[204:207], v[84:87], v[72:75], a[204:207]
	v_mfma_f32_16x16x32_f16 a[196:199], v[80:83], v[72:75], a[196:199]
	v_mfma_f32_16x16x32_f16 a[188:191], v[178:181], v[52:55], a[188:191]
	v_mfma_f32_16x16x32_f16 a[180:183], v[88:91], v[52:55], a[180:183]
	v_mfma_f32_16x16x32_f16 a[172:175], v[84:87], v[52:55], a[172:175]
	v_mfma_f32_16x16x32_f16 a[164:167], v[80:83], v[52:55], a[164:167]
	v_mfma_f32_16x16x32_f16 a[156:159], v[178:181], v[44:47], a[156:159]
	v_mfma_f32_16x16x32_f16 a[148:151], v[88:91], v[44:47], a[148:151]
	v_mfma_f32_16x16x32_f16 a[140:143], v[84:87], v[44:47], a[140:143]
	v_mfma_f32_16x16x32_f16 a[132:135], v[80:83], v[44:47], a[132:135]
	v_mfma_f32_16x16x32_f16 a[124:127], v[178:181], v[48:51], a[124:127]
	v_mfma_f32_16x16x32_f16 a[116:119], v[88:91], v[48:51], a[116:119]
	v_mfma_f32_16x16x32_f16 a[108:111], v[84:87], v[48:51], a[108:111]
	v_mfma_f32_16x16x32_f16 a[100:103], v[80:83], v[48:51], a[100:103]
	v_mfma_f32_16x16x32_f16 a[92:95], v[178:181], v[40:43], a[92:95]
	v_mfma_f32_16x16x32_f16 a[84:87], v[88:91], v[40:43], a[84:87]
	v_mfma_f32_16x16x32_f16 a[76:79], v[84:87], v[40:43], a[76:79]
	v_mfma_f32_16x16x32_f16 a[68:71], v[80:83], v[40:43], a[68:71]
	v_mfma_f32_16x16x32_f16 a[60:63], v[178:181], v[4:7], a[60:63]
	v_mfma_f32_16x16x32_f16 a[52:55], v[88:91], v[4:7], a[52:55]
	v_mfma_f32_16x16x32_f16 a[44:47], v[84:87], v[4:7], a[44:47]
	v_mfma_f32_16x16x32_f16 a[36:39], v[80:83], v[4:7], a[36:39]
	v_mfma_f32_16x16x32_f16 a[28:31], v[178:181], v[32:35], a[28:31]
	v_mfma_f32_16x16x32_f16 a[12:15], v[88:91], v[32:35], a[12:15]
	v_mfma_f32_16x16x32_f16 a[4:7], v[84:87], v[32:35], a[4:7]
	v_mfma_f32_16x16x32_f16 a[0:3], v[80:83], v[32:35], a[0:3]
	s_branch .LBB0_196

; #define LD_AF(dst, ks_) _Pragma("unroll") for (int i = 0; i < 8; ++i) dst[i] = *(const h8*)(sA + i * 16 * G_LD + (ks_) * 32)
; #define LD_BF(dst, ks_, nh_) _Pragma("unroll") for (int i = 0; i < 4; ++i) dst[i] = *(const h8*)(sB + ((nh_) * 4 + i) * 16 * G_LD + (ks_) * 32)
; #define MMA_BLK(afx, bfx, nh_) _Pragma("unroll") for (int mi = 0; mi < 8; ++mi) _Pragma("unroll") for (int ni = 0; ni < 4; ++ni) mfma16_acc(acc[mi][(nh_) * 4 + ni], bfx[ni], afx[mi])
; template <class Epi>
; __device__ __forceinline__ void gemm_run(const GemmArgs g, Epi epi, char* smem) {
;     ...
;       LD_AF(afA, 0); LD_BF(bfA, 0, 0);
;       if (kt + 1 < nk) {
; #pragma unroll
;         for (int i = 0; i < 8; ++i) *(u4*)(st + (lr + 32 * i) * G_LD + lcw) = ra[i];
;       }
;       __builtin_amdgcn_sched_barrier(0);
;       LD_BF(bfB, 0, 1);
;       MMA_BLK(afA, bfA, 0);
;       __builtin_amdgcn_sched_barrier(0);
;       if (kt + 1 < nk) {
; #pragma unroll
;         for (int i = 0; i < 8; ++i) *(u4*)(st + (256 + lr + 32 * i) * G_LD + lcw) = rb[i];
;       }
;       LD_AF(afB, 1); LD_BF(bfA, 1, 0);
;       MMA_BLK(afA, bfB, 1);
.LBB0_599:
	s_bitcmp1_b32 s17, 0
	s_cselect_b32 s11, 0x12000, 0
	s_add_i32 s11, s11, 16
	v_add3_u32 v56, s11, v96, v104
	v_add3_u32 v106, s11, v97, v104
	ds_read_b128 v[8:11], v56 offset:13824
	ds_read_b128 v[16:19], v106 offset:36864
	ds_read_b128 v[12:15], v106 offset:39168
	ds_read_b128 v[4:7], v106 offset:41472
	ds_read_b128 v[0:3], v106 offset:43776
	ds_read_b128 v[76:79], v56
	ds_read_b128 v[72:75], v56 offset:2304
	ds_read_b128 v[52:55], v56 offset:4608
	ds_read_b128 v[44:47], v56 offset:6912
	ds_read_b128 v[48:51], v56 offset:9216
	ds_read_b128 v[40:43], v56 offset:11520
	ds_read_b128 v[36:39], v56 offset:16128
	s_mov_b32 s10, s17
	s_add_i32 s17, s17, 1
	s_bitcmp1_b32 s17, 0
	s_cselect_b32 s11, 0x12000, 0
	v_add_u32_e32 v20, s11, v94
	v_add_u32_e32 v21, v20, v99
	s_waitcnt vmcnt(15)
	ds_write_b128 v21, v[108:111]
	s_waitcnt vmcnt(13)
	ds_write_b128 v21, v[112:115] offset:4608
	s_waitcnt vmcnt(10)
	ds_write_b128 v21, v[116:119] offset:9216
	s_waitcnt vmcnt(9)
	ds_write_b128 v21, v[128:131] offset:13824
	s_waitcnt vmcnt(6)
	ds_write_b128 v21, v[134:137] offset:18432
	s_waitcnt vmcnt(5)
	ds_write_b128 v21, v[146:149] offset:23040
	s_waitcnt vmcnt(3)
	ds_write_b128 v21, v[154:157] offset:27648
	s_waitcnt vmcnt(1)
	ds_write_b128 v21, v[162:165] offset:32256
	ds_read_b128 v[174:177], v106 offset:46080
	ds_read_b128 v[88:91], v106 offset:48384
	ds_read_b128 v[84:87], v106 offset:50688
	ds_read_b128 v[80:83], v106 offset:52992
	s_waitcnt lgkmcnt(14)
	v_mfma_f32_16x16x32_f16 a[0:3], v[16:19], v[76:79], a[0:3]
	v_mfma_f32_16x16x32_f16 a[4:7], v[12:15], v[76:79], a[4:7]
	v_mfma_f32_16x16x32_f16 a[8:11], v[4:7], v[76:79], a[8:11]
	v_mfma_f32_16x16x32_f16 a[24:27], v[0:3], v[76:79], a[24:27]
	v_mfma_f32_16x16x32_f16 a[12:15], v[16:19], v[72:75], a[12:15]
	v_mfma_f32_16x16x32_f16 a[16:19], v[12:15], v[72:75], a[16:19]
	v_mfma_f32_16x16x32_f16 a[28:31], v[4:7], v[72:75], a[28:31]
	v_mfma_f32_16x16x32_f16 a[44:47], v[0:3], v[72:75], a[44:47]
	v_mfma_f32_16x16x32_f16 a[20:23], v[16:19], v[52:55], a[20:23]
	v_mfma_f32_16x16x32_f16 a[36:39], v[12:15], v[52:55], a[36:39]
	v_mfma_f32_16x16x32_f16 a[48:51], v[4:7], v[52:55], a[48:51]
	v_mfma_f32_16x16x32_f16 a[60:63], v[0:3], v[52:55], a[60:63]
	v_mfma_f32_16x16x32_f16 a[32:35], v[16:19], v[44:47], a[32:35]
	v_mfma_f32_16x16x32_f16 a[52:55], v[12:15], v[44:47], a[52:55]
	v_mfma_f32_16x16x32_f16 a[64:67], v[4:7], v[44:47], a[64:67]
	v_mfma_f32_16x16x32_f16 a[76:79], v[0:3], v[44:47], a[76:79]
	v_mfma_f32_16x16x32_f16 a[40:43], v[16:19], v[48:51], a[40:43]
	v_mfma_f32_16x16x32_f16 a[68:71], v[12:15], v[48:51], a[68:71]
	v_mfma_f32_16x16x32_f16 a[80:83], v[4:7], v[48:51], a[80:83]
	v_mfma_f32_16x16x32_f16 a[92:95], v[0:3], v[48:51], a[92:95]
	s_waitcnt lgkmcnt(13)
	v_mfma_f32_16x16x32_f16 a[56:59], v[16:19], v[40:43], a[56:59]
	v_mfma_f32_16x16x32_f16 a[84:87], v[12:15], v[40:43], a[84:87]
	v_mfma_f32_16x16x32_f16 a[96:99], v[4:7], v[40:43], a[96:99]
	v_mfma_f32_16x16x32_f16 a[104:107], v[0:3], v[40:43], a[104:107]
	v_mfma_f32_16x16x32_f16 a[72:75], v[16:19], v[8:11], a[72:75]
	v_mfma_f32_16x16x32_f16 a[100:103], v[12:15], v[8:11], a[100:103]
	v_mfma_f32_16x16x32_f16 a[108:111], v[4:7], v[8:11], a[108:111]
	v_mfma_f32_16x16x32_f16 a[124:127], v[0:3], v[8:11], a[124:127]
	s_waitcnt lgkmcnt(12)
	v_mfma_f32_16x16x32_f16 a[88:91], v[16:19], v[36:39], a[88:91]
	v_mfma_f32_16x16x32_f16 a[112:115], v[12:15], v[36:39], a[112:115]
	v_mfma_f32_16x16x32_f16 a[116:119], v[4:7], v[36:39], a[116:119]
	v_mfma_f32_16x16x32_f16 a[120:123], v[0:3], v[36:39], a[120:123]
	v_add_u32_e32 v0, v20, v100
	s_waitcnt vmcnt(7)
	ds_write_b128 v21, v[120:123] offset:36864
	s_waitcnt vmcnt(6)
	ds_write_b128 v21, v[124:127] offset:41472
	s_waitcnt vmcnt(2)
	ds_write_b128 v21, v[138:141] offset:46080
	ds_write_b128 v21, v[142:145] offset:50688
	ds_write_b128 v21, v[150:153] offset:55296
	ds_write_b128 v21, v[158:161] offset:59904
	s_waitcnt vmcnt(1)
	ds_write_b128 v21, v[166:169] offset:64512
	s_waitcnt vmcnt(0)
	ds_write_b128 v0, v[170:173]
	ds_read_b128 v[32:35], v56 offset:64
	ds_read_b128 v[28:31], v56 offset:2368
	ds_read_b128 v[24:27], v56 offset:4672
	ds_read_b128 v[20:23], v56 offset:6976
	ds_read_b128 v[16:19], v56 offset:9280
	ds_read_b128 v[12:15], v56 offset:11584
	ds_read_b128 v[4:7], v56 offset:13888
	ds_read_b128 v[0:3], v56 offset:16192
	ds_read_b128 v[56:59], v106 offset:36928
	ds_read_b128 v[60:63], v106 offset:39232
	ds_read_b128 v[64:67], v106 offset:41536
	ds_read_b128 v[68:71], v106 offset:43840
	s_cmp_gt_u32 s10, 5
	s_cbranch_scc1 .Lgw1_nl
; #define MMA_BLK(afx, bfx, nh_) _Pragma("unroll") for (int mi = 0; mi < 8; ++mi) _Pragma("unroll") for (int ni = 0; ni < 4; ++ni) mfma16_acc(acc[mi][(nh_) * 4 + ni], bfx[ni], afx[mi])
; template <class Epi>
; __device__ __forceinline__ void gemm_run(const GemmArgs g, Epi epi, char* smem) {
;     ...
;       MMA_BLK(afA, bfB, 1);
;       __builtin_amdgcn_sched_barrier(0);
;       if (kt + 2 < nk) {
;         const int ko = (kt + 2) * 64;
; #pragma unroll
;         for (int i = 0; i < 8; ++i) { ra[i] = __builtin_amdgcn_raw_buffer_load_b128(Ars, aoff, i * astep + ko * 2, 0); rb[i] = __builtin_amdgcn_raw_buffer_load_b128(Brs, boff, i * bstep + ko * 2, 0); }
;       }
	s_waitcnt lgkmcnt(14)
	v_mfma_f32_16x16x32_f16 a[132:135], v[174:177], v[76:79], a[132:135]
	v_mfma_f32_16x16x32_f16 a[136:139], v[88:91], v[76:79], a[136:139]
	v_mfma_f32_16x16x32_f16 a[144:147], v[84:87], v[76:79], a[144:147]
	s_add_i32 s23, s15, 0xfffac000
	v_mfma_f32_16x16x32_f16 a[156:159], v[80:83], v[76:79], a[156:159]
	s_mov_b32 s10, s6
	v_mfma_f32_16x16x32_f16 a[140:143], v[174:177], v[72:75], a[140:143]
	s_mov_b32 s11, s7
	v_mfma_f32_16x16x32_f16 a[148:151], v[88:91], v[72:75], a[148:151]
	buffer_load_dwordx4 v[108:111], v92, s[4:7], s23 offen
	v_mfma_f32_16x16x32_f16 a[164:167], v[84:87], v[72:75], a[164:167]
	buffer_load_dwordx4 v[120:123], v93, s[8:11], s23 offen
	v_mfma_f32_16x16x32_f16 a[184:187], v[80:83], v[72:75], a[184:187]
	s_add_i32 s23, s15, 0xfffb8000
	v_mfma_f32_16x16x32_f16 a[152:155], v[174:177], v[52:55], a[152:155]
	s_add_i32 s26, s15, 0xfffbc000
	v_mfma_f32_16x16x32_f16 a[168:171], v[88:91], v[52:55], a[168:171]
	buffer_load_dwordx4 v[112:115], v92, s[4:7], s23 offen
	v_mfma_f32_16x16x32_f16 a[180:183], v[84:87], v[52:55], a[180:183]
	buffer_load_dwordx4 v[138:141], v93, s[8:11], s26 offen
	v_mfma_f32_16x16x32_f16 a[200:203], v[80:83], v[52:55], a[200:203]
	s_add_i32 s23, s15, 0xfffb4000
	v_mfma_f32_16x16x32_f16 a[160:163], v[174:177], v[44:47], a[160:163]
	buffer_load_dwordx4 v[124:127], v93, s[8:11], s23 offen
	v_mfma_f32_16x16x32_f16 a[176:179], v[88:91], v[44:47], a[176:179]
	s_add_i32 s23, s15, 0xfffc4000
	v_mfma_f32_16x16x32_f16 a[196:199], v[84:87], v[44:47], a[196:199]
	s_add_i32 s26, s15, 0xfffd0000
	v_mfma_f32_16x16x32_f16 a[216:219], v[80:83], v[44:47], a[216:219]
	buffer_load_dwordx4 v[116:119], v92, s[4:7], s23 offen
	v_mfma_f32_16x16x32_f16 a[172:175], v[174:177], v[48:51], a[172:175]
	buffer_load_dwordx4 v[128:131], v92, s[4:7], s26 offen
	v_mfma_f32_16x16x32_f16 a[192:195], v[88:91], v[48:51], a[192:195]
	buffer_load_dwordx4 v[142:145], v93, s[8:11], s23 offen
	v_mfma_f32_16x16x32_f16 a[212:215], v[84:87], v[48:51], a[212:215]
	s_add_i32 s26, s15, 0xfffcc000
	v_mfma_f32_16x16x32_f16 a[232:235], v[80:83], v[48:51], a[232:235]
	s_add_i32 s23, s15, 0xfffdc000
	v_mfma_f32_16x16x32_f16 a[188:191], v[174:177], v[40:43], a[188:191]
	buffer_load_dwordx4 v[150:153], v93, s[8:11], s26 offen
	v_mfma_f32_16x16x32_f16 a[208:211], v[88:91], v[40:43], a[208:211]
	s_add_i32 s26, s15, 0xfffe8000
	v_mfma_f32_16x16x32_f16 a[228:231], v[84:87], v[40:43], a[228:231]
	buffer_load_dwordx4 v[134:137], v92, s[4:7], s23 offen
	v_mfma_f32_16x16x32_f16 a[244:247], v[80:83], v[40:43], a[244:247]
	buffer_load_dwordx4 v[146:149], v92, s[4:7], s26 offen
	v_mfma_f32_16x16x32_f16 a[204:207], v[174:177], v[8:11], a[204:207]
	s_add_i32 s26, s15, 0xfffd4000
	v_mfma_f32_16x16x32_f16 a[224:227], v[88:91], v[8:11], a[224:227]
	buffer_load_dwordx4 v[158:161], v93, s[8:11], s26 offen
	v_mfma_f32_16x16x32_f16 a[240:243], v[84:87], v[8:11], a[240:243]
	s_add_i32 s26, s15, 0xffff4000
	v_mfma_f32_16x16x32_f16 a[252:255], v[80:83], v[8:11], a[252:255]
	buffer_load_dwordx4 v[154:157], v92, s[4:7], s26 offen
	v_mfma_f32_16x16x32_f16 a[220:223], v[174:177], v[36:39], a[220:223]
	buffer_load_dwordx4 v[166:169], v93, s[8:11], s23 offen
	v_mfma_f32_16x16x32_f16 a[236:239], v[88:91], v[36:39], a[236:239]
	buffer_load_dwordx4 v[162:165], v92, s[4:7], s15 offen
	v_mfma_f32_16x16x32_f16 a[248:251], v[84:87], v[36:39], a[248:251]
	s_add_i32 s23, s15, 0xfffe4000
	v_mfma_f32_16x16x32_f16 a[128:131], v[80:83], v[36:39], a[128:131]
	buffer_load_dwordx4 v[170:173], v93, s[8:11], s23 offen
	s_branch .LBB0_598
.Lgw1_nl:
	s_waitcnt lgkmcnt(14)
	v_mfma_f32_16x16x32_f16 a[132:135], v[174:177], v[76:79], a[132:135]
	v_mfma_f32_16x16x32_f16 a[136:139], v[88:91], v[76:79], a[136:139]
	v_mfma_f32_16x16x32_f16 a[144:147], v[84:87], v[76:79], a[144:147]
	v_mfma_f32_16x16x32_f16 a[156:159], v[80:83], v[76:79], a[156:159]
	v_mfma_f32_16x16x32_f16 a[140:143], v[174:177], v[72:75], a[140:143]
	v_mfma_f32_16x16x32_f16 a[148:151], v[88:91], v[72:75], a[148:151]
	v_mfma_f32_16x16x32_f16 a[164:167], v[84:87], v[72:75], a[164:167]
	v_mfma_f32_16x16x32_f16 a[184:187], v[80:83], v[72:75], a[184:187]
	v_mfma_f32_16x16x32_f16 a[152:155], v[174:177], v[52:55], a[152:155]
	v_mfma_f32_16x16x32_f16 a[168:171], v[88:91], v[52:55], a[168:171]
	v_mfma_f32_16x16x32_f16 a[180:183], v[84:87], v[52:55], a[180:183]
	v_mfma_f32_16x16x32_f16 a[200:203], v[80:83], v[52:55], a[200:203]
	v_mfma_f32_16x16x32_f16 a[160:163], v[174:177], v[44:47], a[160:163]
	v_mfma_f32_16x16x32_f16 a[176:179], v[88:91], v[44:47], a[176:179]
	v_mfma_f32_16x16x32_f16 a[196:199], v[84:87], v[44:47], a[196:199]
	v_mfma_f32_16x16x32_f16 a[216:219], v[80:83], v[44:47], a[216:219]
	v_mfma_f32_16x16x32_f16 a[172:175], v[174:177], v[48:51], a[172:175]
	v_mfma_f32_16x16x32_f16 a[192:195], v[88:91], v[48:51], a[192:195]
	v_mfma_f32_16x16x32_f16 a[212:215], v[84:87], v[48:51], a[212:215]
	v_mfma_f32_16x16x32_f16 a[232:235], v[80:83], v[48:51], a[232:235]
	v_mfma_f32_16x16x32_f16 a[188:191], v[174:177], v[40:43], a[188:191]
	v_mfma_f32_16x16x32_f16 a[208:211], v[88:91], v[40:43], a[208:211]
	v_mfma_f32_16x16x32_f16 a[228:231], v[84:87], v[40:43], a[228:231]
	v_mfma_f32_16x16x32_f16 a[244:247], v[80:83], v[40:43], a[244:247]
	v_mfma_f32_16x16x32_f16 a[204:207], v[174:177], v[8:11], a[204:207]
	v_mfma_f32_16x16x32_f16 a[224:227], v[88:91], v[8:11], a[224:227]
	v_mfma_f32_16x16x32_f16 a[240:243], v[84:87], v[8:11], a[240:243]
	v_mfma_f32_16x16x32_f16 a[252:255], v[80:83], v[8:11], a[252:255]
	v_mfma_f32_16x16x32_f16 a[220:223], v[174:177], v[36:39], a[220:223]
	v_mfma_f32_16x16x32_f16 a[236:239], v[88:91], v[36:39], a[236:239]
	v_mfma_f32_16x16x32_f16 a[248:251], v[84:87], v[36:39], a[248:251]
	v_mfma_f32_16x16x32_f16 a[128:131], v[80:83], v[36:39], a[128:131]
	s_branch .LBB0_598

; #define LD_AF(dst, ks_) _Pragma("unroll") for (int i = 0; i < 8; ++i) dst[i] = *(const h8*)(sA + i * 16 * G_LD + (ks_) * 32)
; #define LD_BF(dst, ks_, nh_) _Pragma("unroll") for (int i = 0; i < 4; ++i) dst[i] = *(const h8*)(sB + ((nh_) * 4 + i) * 16 * G_LD + (ks_) * 32)
; #define MMA_BLK(afx, bfx, nh_) _Pragma("unroll") for (int mi = 0; mi < 8; ++mi) _Pragma("unroll") for (int ni = 0; ni < 4; ++ni) mfma16_acc(acc[mi][(nh_) * 4 + ni], bfx[ni], afx[mi])
; template <class Epi>
; __device__ __forceinline__ void gemm_run(const GemmArgs g, Epi epi, char* smem) {
;     ...
;       LD_AF(afA, 0); LD_BF(bfA, 0, 0);
;       if (kt + 1 < nk) {
; #pragma unroll
;         for (int i = 0; i < 8; ++i) *(u4*)(st + (lr + 32 * i) * G_LD + lcw) = ra[i];
;       }
;       __builtin_amdgcn_sched_barrier(0);
;       LD_BF(bfB, 0, 1);
;       MMA_BLK(afA, bfA, 0);
;       __builtin_amdgcn_sched_barrier(0);
;       if (kt + 1 < nk) {
; #pragma unroll
;         for (int i = 0; i < 8; ++i) *(u4*)(st + (256 + lr + 32 * i) * G_LD + lcw) = rb[i];
;       }
;       LD_AF(afB, 1); LD_BF(bfA, 1, 0);
;       MMA_BLK(afA, bfB, 1);
.LBB0_631:
	s_bitcmp1_b32 s75, 0
	s_cselect_b32 s11, 0x12000, 0
	s_add_i32 s11, s11, 16
	v_add3_u32 v56, s11, v136, v145
	v_add3_u32 v94, s11, v138, v145
	ds_read_b128 v[4:7], v56 offset:13824
	ds_read_b128 v[16:19], v94 offset:36864
	ds_read_b128 v[12:15], v94 offset:39168
	ds_read_b128 v[8:11], v94 offset:41472
	ds_read_b128 v[0:3], v94 offset:43776
	ds_read_b128 v[76:79], v56
	ds_read_b128 v[72:75], v56 offset:2304
	ds_read_b128 v[52:55], v56 offset:4608
	ds_read_b128 v[44:47], v56 offset:6912
	ds_read_b128 v[48:51], v56 offset:9216
	ds_read_b128 v[40:43], v56 offset:11520
	ds_read_b128 v[32:35], v56 offset:16128
	s_mov_b32 s10, s75
	s_add_i32 s75, s75, 1
	s_bitcmp1_b32 s75, 0
	s_cselect_b32 s11, 0x12000, 0
	v_add_u32_e32 v20, s11, v135
	v_add_u32_e32 v21, v20, v140
	s_waitcnt vmcnt(15)
	ds_write_b128 v21, v[96:99]
	s_waitcnt vmcnt(13)
	ds_write_b128 v21, v[104:107] offset:4608
	s_waitcnt vmcnt(11)
	ds_write_b128 v21, v[108:111] offset:9216
	s_waitcnt vmcnt(9)
	ds_write_b128 v21, v[120:123] offset:13824
	s_waitcnt vmcnt(7)
	ds_write_b128 v21, v[124:127] offset:18432
	s_waitcnt vmcnt(5)
	ds_write_b128 v21, v[150:153] offset:23040
	s_waitcnt vmcnt(3)
	ds_write_b128 v21, v[154:157] offset:27648
	s_waitcnt vmcnt(1)
	ds_write_b128 v21, v[162:165] offset:32256
	ds_read_b128 v[174:177], v94 offset:46080
	ds_read_b128 v[88:91], v94 offset:48384
	ds_read_b128 v[84:87], v94 offset:50688
	ds_read_b128 v[80:83], v94 offset:52992
	s_waitcnt lgkmcnt(14)
	v_mfma_f32_16x16x32_f16 a[252:255], v[16:19], v[76:79], a[252:255]
	v_mfma_f32_16x16x32_f16 a[248:251], v[12:15], v[76:79], a[248:251]
	v_mfma_f32_16x16x32_f16 a[244:247], v[8:11], v[76:79], a[244:247]
	v_mfma_f32_16x16x32_f16 a[236:239], v[0:3], v[76:79], a[236:239]
	v_mfma_f32_16x16x32_f16 a[220:223], v[16:19], v[72:75], a[220:223]
	v_mfma_f32_16x16x32_f16 a[216:219], v[12:15], v[72:75], a[216:219]
	v_mfma_f32_16x16x32_f16 a[212:215], v[8:11], v[72:75], a[212:215]
	v_mfma_f32_16x16x32_f16 a[204:207], v[0:3], v[72:75], a[204:207]
	v_mfma_f32_16x16x32_f16 a[188:191], v[16:19], v[52:55], a[188:191]
	v_mfma_f32_16x16x32_f16 a[184:187], v[12:15], v[52:55], a[184:187]
	v_mfma_f32_16x16x32_f16 a[180:183], v[8:11], v[52:55], a[180:183]
	v_mfma_f32_16x16x32_f16 a[172:175], v[0:3], v[52:55], a[172:175]
	v_mfma_f32_16x16x32_f16 a[156:159], v[16:19], v[44:47], a[156:159]
	v_mfma_f32_16x16x32_f16 a[152:155], v[12:15], v[44:47], a[152:155]
	v_mfma_f32_16x16x32_f16 a[148:151], v[8:11], v[44:47], a[148:151]
	v_mfma_f32_16x16x32_f16 a[140:143], v[0:3], v[44:47], a[140:143]
	v_mfma_f32_16x16x32_f16 a[124:127], v[16:19], v[48:51], a[124:127]
	v_mfma_f32_16x16x32_f16 a[120:123], v[12:15], v[48:51], a[120:123]
	v_mfma_f32_16x16x32_f16 a[116:119], v[8:11], v[48:51], a[116:119]
	v_mfma_f32_16x16x32_f16 a[108:111], v[0:3], v[48:51], a[108:111]
	s_waitcnt lgkmcnt(13)
	v_mfma_f32_16x16x32_f16 a[92:95], v[16:19], v[40:43], a[92:95]
	v_mfma_f32_16x16x32_f16 a[88:91], v[12:15], v[40:43], a[88:91]
	v_mfma_f32_16x16x32_f16 a[84:87], v[8:11], v[40:43], a[84:87]
	v_mfma_f32_16x16x32_f16 a[76:79], v[0:3], v[40:43], a[76:79]
	v_mfma_f32_16x16x32_f16 a[60:63], v[16:19], v[4:7], a[60:63]
	v_mfma_f32_16x16x32_f16 a[56:59], v[12:15], v[4:7], a[56:59]
	v_mfma_f32_16x16x32_f16 a[52:55], v[8:11], v[4:7], a[52:55]
	v_mfma_f32_16x16x32_f16 a[44:47], v[0:3], v[4:7], a[44:47]
	s_waitcnt lgkmcnt(12)
	v_mfma_f32_16x16x32_f16 a[28:31], v[16:19], v[32:35], a[28:31]
	v_mfma_f32_16x16x32_f16 a[24:27], v[12:15], v[32:35], a[24:27]
	v_mfma_f32_16x16x32_f16 a[20:23], v[8:11], v[32:35], a[20:23]
	v_mfma_f32_16x16x32_f16 a[12:15], v[0:3], v[32:35], a[12:15]
	v_add_u32_e32 v0, v20, v141
	s_waitcnt vmcnt(7)
	ds_write_b128 v21, v[100:103] offset:36864
	s_waitcnt vmcnt(6)
	ds_write_b128 v21, v[112:115] offset:41472
	s_waitcnt vmcnt(5)
	ds_write_b128 v21, v[116:119] offset:46080
	s_waitcnt vmcnt(4)
	ds_write_b128 v21, v[128:131] offset:50688
	s_waitcnt vmcnt(3)
	ds_write_b128 v21, v[146:149] offset:55296
	s_waitcnt vmcnt(2)
	ds_write_b128 v21, v[158:161] offset:59904
	s_waitcnt vmcnt(1)
	ds_write_b128 v21, v[166:169] offset:64512
	s_waitcnt vmcnt(0)
	ds_write_b128 v0, v[170:173]
	ds_read_b128 v[36:39], v56 offset:64
	ds_read_b128 v[28:31], v56 offset:2368
	ds_read_b128 v[24:27], v56 offset:4672
	ds_read_b128 v[20:23], v56 offset:6976
	ds_read_b128 v[16:19], v56 offset:9280
	ds_read_b128 v[12:15], v56 offset:11584
	ds_read_b128 v[8:11], v56 offset:13888
	ds_read_b128 v[0:3], v56 offset:16192
	ds_read_b128 v[56:59], v94 offset:36928
	ds_read_b128 v[60:63], v94 offset:39232
	ds_read_b128 v[64:67], v94 offset:41536
	ds_read_b128 v[68:71], v94 offset:43840
	s_cmp_gt_u32 s10, 9
	s_cbranch_scc1 .Lgw2_nl
; #define MMA_BLK(afx, bfx, nh_) _Pragma("unroll") for (int mi = 0; mi < 8; ++mi) _Pragma("unroll") for (int ni = 0; ni < 4; ++ni) mfma16_acc(acc[mi][(nh_) * 4 + ni], bfx[ni], afx[mi])
; template <class Epi>
; __device__ __forceinline__ void gemm_run(const GemmArgs g, Epi epi, char* smem) {
;     ...
;       MMA_BLK(afA, bfB, 1);
;       __builtin_amdgcn_sched_barrier(0);
;       if (kt + 2 < nk) {
;         const int ko = (kt + 2) * 64;
; #pragma unroll
;         for (int i = 0; i < 8; ++i) { ra[i] = __builtin_amdgcn_raw_buffer_load_b128(Ars, aoff, i * astep + ko * 2, 0); rb[i] = __builtin_amdgcn_raw_buffer_load_b128(Brs, boff, i * bstep + ko * 2, 0); }
;       }
	s_waitcnt lgkmcnt(14)
	v_mfma_f32_16x16x32_f16 a[240:243], v[174:177], v[76:79], a[240:243]
	v_mfma_f32_16x16x32_f16 a[232:235], v[88:91], v[76:79], a[232:235]
	v_mfma_f32_16x16x32_f16 a[228:231], v[84:87], v[76:79], a[228:231]
	s_add_i32 s76, s74, 0xfffac000
	v_mfma_f32_16x16x32_f16 a[224:227], v[80:83], v[76:79], a[224:227]
	s_mov_b32 s10, s6
	v_mfma_f32_16x16x32_f16 a[208:211], v[174:177], v[72:75], a[208:211]
	s_mov_b32 s11, s7
	v_mfma_f32_16x16x32_f16 a[200:203], v[88:91], v[72:75], a[200:203]
	buffer_load_dwordx4 v[96:99], v134, s[4:7], s76 offen
	v_mfma_f32_16x16x32_f16 a[196:199], v[84:87], v[72:75], a[196:199]
	buffer_load_dwordx4 v[100:103], v134, s[8:11], s76 offen
	v_mfma_f32_16x16x32_f16 a[192:195], v[80:83], v[72:75], a[192:195]
	s_add_i32 s76, s74, 0xfffb8000
	v_mfma_f32_16x16x32_f16 a[176:179], v[174:177], v[52:55], a[176:179]
	buffer_load_dwordx4 v[104:107], v134, s[4:7], s76 offen
	v_mfma_f32_16x16x32_f16 a[168:171], v[88:91], v[52:55], a[168:171]
	buffer_load_dwordx4 v[112:115], v134, s[8:11], s76 offen
	v_mfma_f32_16x16x32_f16 a[164:167], v[84:87], v[52:55], a[164:167]
	s_add_i32 s76, s74, 0xfffc4000
	v_mfma_f32_16x16x32_f16 a[160:163], v[80:83], v[52:55], a[160:163]
	buffer_load_dwordx4 v[108:111], v134, s[4:7], s76 offen
	v_mfma_f32_16x16x32_f16 a[144:147], v[174:177], v[44:47], a[144:147]
	buffer_load_dwordx4 v[116:119], v134, s[8:11], s76 offen
	v_mfma_f32_16x16x32_f16 a[136:139], v[88:91], v[44:47], a[136:139]
	s_add_i32 s76, s74, 0xfffd0000
	v_mfma_f32_16x16x32_f16 a[132:135], v[84:87], v[44:47], a[132:135]
	buffer_load_dwordx4 v[120:123], v134, s[4:7], s76 offen
	v_mfma_f32_16x16x32_f16 a[128:131], v[80:83], v[44:47], a[128:131]
	buffer_load_dwordx4 v[128:131], v134, s[8:11], s76 offen
	v_mfma_f32_16x16x32_f16 a[112:115], v[174:177], v[48:51], a[112:115]
	s_add_i32 s76, s74, 0xfffdc000
	v_mfma_f32_16x16x32_f16 a[104:107], v[88:91], v[48:51], a[104:107]
	buffer_load_dwordx4 v[124:127], v134, s[4:7], s76 offen
	v_mfma_f32_16x16x32_f16 a[100:103], v[84:87], v[48:51], a[100:103]
	buffer_load_dwordx4 v[146:149], v134, s[8:11], s76 offen
	v_mfma_f32_16x16x32_f16 a[96:99], v[80:83], v[48:51], a[96:99]
	s_add_i32 s76, s74, 0xfffe8000
	v_mfma_f32_16x16x32_f16 a[80:83], v[174:177], v[40:43], a[80:83]
	buffer_load_dwordx4 v[150:153], v134, s[4:7], s76 offen
	v_mfma_f32_16x16x32_f16 a[72:75], v[88:91], v[40:43], a[72:75]
	buffer_load_dwordx4 v[158:161], v134, s[8:11], s76 offen
	v_mfma_f32_16x16x32_f16 a[68:71], v[84:87], v[40:43], a[68:71]
	s_add_i32 s76, s74, 0xffff4000
	v_mfma_f32_16x16x32_f16 a[64:67], v[80:83], v[40:43], a[64:67]
	buffer_load_dwordx4 v[154:157], v134, s[4:7], s76 offen
	v_mfma_f32_16x16x32_f16 a[48:51], v[174:177], v[4:7], a[48:51]
	buffer_load_dwordx4 v[166:169], v134, s[8:11], s76 offen
	v_mfma_f32_16x16x32_f16 a[40:43], v[88:91], v[4:7], a[40:43]
	buffer_load_dwordx4 v[162:165], v134, s[4:7], s74 offen
	v_mfma_f32_16x16x32_f16 a[36:39], v[84:87], v[4:7], a[36:39]
	buffer_load_dwordx4 v[170:173], v134, s[8:11], s74 offen
	v_mfma_f32_16x16x32_f16 a[32:35], v[80:83], v[4:7], a[32:35]
	v_mfma_f32_16x16x32_f16 a[16:19], v[174:177], v[32:35], a[16:19]
	v_mfma_f32_16x16x32_f16 a[8:11], v[88:91], v[32:35], a[8:11]
	v_mfma_f32_16x16x32_f16 a[4:7], v[84:87], v[32:35], a[4:7]
	v_mfma_f32_16x16x32_f16 a[0:3], v[80:83], v[32:35], a[0:3]
	s_branch .LBB0_630
.Lgw2_nl:
	s_waitcnt lgkmcnt(14)
	v_mfma_f32_16x16x32_f16 a[240:243], v[174:177], v[76:79], a[240:243]
	v_mfma_f32_16x16x32_f16 a[232:235], v[88:91], v[76:79], a[232:235]
	v_mfma_f32_16x16x32_f16 a[228:231], v[84:87], v[76:79], a[228:231]
	v_mfma_f32_16x16x32_f16 a[224:227], v[80:83], v[76:79], a[224:227]
	v_mfma_f32_16x16x32_f16 a[208:211], v[174:177], v[72:75], a[208:211]
	v_mfma_f32_16x16x32_f16 a[200:203], v[88:91], v[72:75], a[200:203]
	v_mfma_f32_16x16x32_f16 a[196:199], v[84:87], v[72:75], a[196:199]
	v_mfma_f32_16x16x32_f16 a[192:195], v[80:83], v[72:75], a[192:195]
	v_mfma_f32_16x16x32_f16 a[176:179], v[174:177], v[52:55], a[176:179]
	v_mfma_f32_16x16x32_f16 a[168:171], v[88:91], v[52:55], a[168:171]
	v_mfma_f32_16x16x32_f16 a[164:167], v[84:87], v[52:55], a[164:167]
	v_mfma_f32_16x16x32_f16 a[160:163], v[80:83], v[52:55], a[160:163]
	v_mfma_f32_16x16x32_f16 a[144:147], v[174:177], v[44:47], a[144:147]
	v_mfma_f32_16x16x32_f16 a[136:139], v[88:91], v[44:47], a[136:139]
	v_mfma_f32_16x16x32_f16 a[132:135], v[84:87], v[44:47], a[132:135]
	v_mfma_f32_16x16x32_f16 a[128:131], v[80:83], v[44:47], a[128:131]
	v_mfma_f32_16x16x32_f16 a[112:115], v[174:177], v[48:51], a[112:115]
	v_mfma_f32_16x16x32_f16 a[104:107], v[88:91], v[48:51], a[104:107]
	v_mfma_f32_16x16x32_f16 a[100:103], v[84:87], v[48:51], a[100:103]
	v_mfma_f32_16x16x32_f16 a[96:99], v[80:83], v[48:51], a[96:99]
	v_mfma_f32_16x16x32_f16 a[80:83], v[174:177], v[40:43], a[80:83]
	v_mfma_f32_16x16x32_f16 a[72:75], v[88:91], v[40:43], a[72:75]
	v_mfma_f32_16x16x32_f16 a[68:71], v[84:87], v[40:43], a[68:71]
	v_mfma_f32_16x16x32_f16 a[64:67], v[80:83], v[40:43], a[64:67]
	v_mfma_f32_16x16x32_f16 a[48:51], v[174:177], v[4:7], a[48:51]
	v_mfma_f32_16x16x32_f16 a[40:43], v[88:91], v[4:7], a[40:43]
	v_mfma_f32_16x16x32_f16 a[36:39], v[84:87], v[4:7], a[36:39]
	v_mfma_f32_16x16x32_f16 a[32:35], v[80:83], v[4:7], a[32:35]
	v_mfma_f32_16x16x32_f16 a[16:19], v[174:177], v[32:35], a[16:19]
	v_mfma_f32_16x16x32_f16 a[8:11], v[88:91], v[32:35], a[8:11]
	v_mfma_f32_16x16x32_f16 a[4:7], v[84:87], v[32:35], a[4:7]
	v_mfma_f32_16x16x32_f16 a[0:3], v[80:83], v[32:35], a[0:3]
	s_branch .LBB0_630

; #define LD_AF(dst, ks_) _Pragma("unroll") for (int i = 0; i < 8; ++i) dst[i] = *(const h8*)(sA + i * 16 * G_LD + (ks_) * 32)
; #define LD_BF(dst, ks_, nh_) _Pragma("unroll") for (int i = 0; i < 4; ++i) dst[i] = *(const h8*)(sB + ((nh_) * 4 + i) * 16 * G_LD + (ks_) * 32)
; #define MMA_BLK(afx, bfx, nh_) _Pragma("unroll") for (int mi = 0; mi < 8; ++mi) _Pragma("unroll") for (int ni = 0; ni < 4; ++ni) mfma16_acc(acc[mi][(nh_) * 4 + ni], bfx[ni], afx[mi])
; template <class Epi>
; __device__ __forceinline__ void gemm_run(const GemmArgs g, Epi epi, char* smem) {
;     ...
;       LD_AF(afA, 0); LD_BF(bfA, 0, 0);
;       if (kt + 1 < nk) {
; #pragma unroll
;         for (int i = 0; i < 8; ++i) *(u4*)(st + (lr + 32 * i) * G_LD + lcw) = ra[i];
;       }
;       __builtin_amdgcn_sched_barrier(0);
;       LD_BF(bfB, 0, 1);
;       MMA_BLK(afA, bfA, 0);
;       __builtin_amdgcn_sched_barrier(0);
;       if (kt + 1 < nk) {
; #pragma unroll
;         for (int i = 0; i < 8; ++i) *(u4*)(st + (256 + lr + 32 * i) * G_LD + lcw) = rb[i];
;       }
;       LD_AF(afB, 1); LD_BF(bfA, 1, 0);
;       MMA_BLK(afA, bfB, 1);
.LBB0_648:
	s_bitcmp1_b32 s21, 0
	s_cselect_b32 s15, 0x12000, 0
	s_add_i32 s15, s15, 16
	v_add3_u32 v56, s15, v95, v103
	v_add3_u32 v104, s15, v96, v103
	ds_read_b128 v[4:7], v56 offset:13824
	ds_read_b128 v[16:19], v104 offset:36864
	ds_read_b128 v[12:15], v104 offset:39168
	ds_read_b128 v[8:11], v104 offset:41472
	ds_read_b128 v[0:3], v104 offset:43776
	ds_read_b128 v[76:79], v56
	ds_read_b128 v[72:75], v56 offset:2304
	ds_read_b128 v[52:55], v56 offset:4608
	ds_read_b128 v[44:47], v56 offset:6912
	ds_read_b128 v[48:51], v56 offset:9216
	ds_read_b128 v[40:43], v56 offset:11520
	ds_read_b128 v[32:35], v56 offset:16128
	s_mov_b32 s14, s21
	s_add_i32 s21, s21, 1
	s_bitcmp1_b32 s21, 0
	s_cselect_b32 s15, 0x12000, 0
	v_add_u32_e32 v20, s15, v93
	v_add_u32_e32 v21, v20, v98
	s_waitcnt vmcnt(15)
	ds_write_b128 v21, v[106:109]
	s_waitcnt vmcnt(13)
	ds_write_b128 v21, v[114:117] offset:4608
	s_waitcnt vmcnt(11)
	ds_write_b128 v21, v[118:121] offset:9216
	s_waitcnt vmcnt(9)
	ds_write_b128 v21, v[134:137] offset:13824
	s_waitcnt vmcnt(7)
	ds_write_b128 v21, v[138:141] offset:18432
	s_waitcnt vmcnt(5)
	ds_write_b128 v21, v[150:153] offset:23040
	s_waitcnt vmcnt(3)
	ds_write_b128 v21, v[154:157] offset:27648
	s_waitcnt vmcnt(1)
	ds_write_b128 v21, v[162:165] offset:32256
	ds_read_b128 v[174:177], v104 offset:46080
	ds_read_b128 v[88:91], v104 offset:48384
	ds_read_b128 v[84:87], v104 offset:50688
	ds_read_b128 v[80:83], v104 offset:52992
	s_waitcnt lgkmcnt(14)
	v_mfma_f32_16x16x32_f16 a[252:255], v[16:19], v[76:79], a[252:255]
	v_mfma_f32_16x16x32_f16 a[248:251], v[12:15], v[76:79], a[248:251]
	v_mfma_f32_16x16x32_f16 a[244:247], v[8:11], v[76:79], a[244:247]
	v_mfma_f32_16x16x32_f16 a[240:243], v[0:3], v[76:79], a[240:243]
	v_mfma_f32_16x16x32_f16 a[220:223], v[16:19], v[72:75], a[220:223]
	v_mfma_f32_16x16x32_f16 a[216:219], v[12:15], v[72:75], a[216:219]
	v_mfma_f32_16x16x32_f16 a[212:215], v[8:11], v[72:75], a[212:215]
	v_mfma_f32_16x16x32_f16 a[208:211], v[0:3], v[72:75], a[208:211]
	v_mfma_f32_16x16x32_f16 a[188:191], v[16:19], v[52:55], a[188:191]
	v_mfma_f32_16x16x32_f16 a[184:187], v[12:15], v[52:55], a[184:187]
	v_mfma_f32_16x16x32_f16 a[180:183], v[8:11], v[52:55], a[180:183]
	v_mfma_f32_16x16x32_f16 a[176:179], v[0:3], v[52:55], a[176:179]
	v_mfma_f32_16x16x32_f16 a[156:159], v[16:19], v[44:47], a[156:159]
	v_mfma_f32_16x16x32_f16 a[152:155], v[12:15], v[44:47], a[152:155]
	v_mfma_f32_16x16x32_f16 a[148:151], v[8:11], v[44:47], a[148:151]
	v_mfma_f32_16x16x32_f16 a[144:147], v[0:3], v[44:47], a[144:147]
	v_mfma_f32_16x16x32_f16 a[124:127], v[16:19], v[48:51], a[124:127]
	v_mfma_f32_16x16x32_f16 a[120:123], v[12:15], v[48:51], a[120:123]
	v_mfma_f32_16x16x32_f16 a[116:119], v[8:11], v[48:51], a[116:119]
	v_mfma_f32_16x16x32_f16 a[112:115], v[0:3], v[48:51], a[112:115]
	s_waitcnt lgkmcnt(13)
	v_mfma_f32_16x16x32_f16 a[92:95], v[16:19], v[40:43], a[92:95]
	v_mfma_f32_16x16x32_f16 a[88:91], v[12:15], v[40:43], a[88:91]
	v_mfma_f32_16x16x32_f16 a[84:87], v[8:11], v[40:43], a[84:87]
	v_mfma_f32_16x16x32_f16 a[80:83], v[0:3], v[40:43], a[80:83]
	v_mfma_f32_16x16x32_f16 a[60:63], v[16:19], v[4:7], a[60:63]
	v_mfma_f32_16x16x32_f16 a[56:59], v[12:15], v[4:7], a[56:59]
	v_mfma_f32_16x16x32_f16 a[52:55], v[8:11], v[4:7], a[52:55]
	v_mfma_f32_16x16x32_f16 a[48:51], v[0:3], v[4:7], a[48:51]
	s_waitcnt lgkmcnt(12)
	v_mfma_f32_16x16x32_f16 a[28:31], v[16:19], v[32:35], a[28:31]
	v_mfma_f32_16x16x32_f16 a[24:27], v[12:15], v[32:35], a[24:27]
	v_mfma_f32_16x16x32_f16 a[20:23], v[8:11], v[32:35], a[20:23]
	v_mfma_f32_16x16x32_f16 a[16:19], v[0:3], v[32:35], a[16:19]
	v_add_u32_e32 v0, v20, v99
	s_waitcnt vmcnt(7)
	ds_write_b128 v21, v[110:113] offset:36864
	s_waitcnt vmcnt(6)
	ds_write_b128 v21, v[122:125] offset:41472
	s_waitcnt vmcnt(5)
	ds_write_b128 v21, v[126:129] offset:46080
	s_waitcnt vmcnt(4)
	ds_write_b128 v21, v[142:145] offset:50688
	s_waitcnt vmcnt(3)
	ds_write_b128 v21, v[146:149] offset:55296
	s_waitcnt vmcnt(2)
	ds_write_b128 v21, v[158:161] offset:59904
	s_waitcnt vmcnt(1)
	ds_write_b128 v21, v[166:169] offset:64512
	s_waitcnt vmcnt(0)
	ds_write_b128 v0, v[170:173]
	ds_read_b128 v[36:39], v56 offset:64
	ds_read_b128 v[28:31], v56 offset:2368
	ds_read_b128 v[24:27], v56 offset:4672
	ds_read_b128 v[20:23], v56 offset:6976
	ds_read_b128 v[16:19], v56 offset:9280
	ds_read_b128 v[12:15], v56 offset:11584
	ds_read_b128 v[8:11], v56 offset:13888
	ds_read_b128 v[0:3], v56 offset:16192
	ds_read_b128 v[56:59], v104 offset:36928
	ds_read_b128 v[60:63], v104 offset:39232
	ds_read_b128 v[64:67], v104 offset:41536
	ds_read_b128 v[68:71], v104 offset:43840
	s_cmp_gt_u32 s14, 13
	s_cbranch_scc1 .Lgw3_nl
; #define MMA_BLK(afx, bfx, nh_) _Pragma("unroll") for (int mi = 0; mi < 8; ++mi) _Pragma("unroll") for (int ni = 0; ni < 4; ++ni) mfma16_acc(acc[mi][(nh_) * 4 + ni], bfx[ni], afx[mi])
; template <class Epi>
; __device__ __forceinline__ void gemm_run(const GemmArgs g, Epi epi, char* smem) {
;     ...
;       MMA_BLK(afA, bfB, 1);
;       __builtin_amdgcn_sched_barrier(0);
;       if (kt + 2 < nk) {
;         const int ko = (kt + 2) * 64;
; #pragma unroll
;         for (int i = 0; i < 8; ++i) { ra[i] = __builtin_amdgcn_raw_buffer_load_b128(Ars, aoff, i * astep + ko * 2, 0); rb[i] = __builtin_amdgcn_raw_buffer_load_b128(Brs, boff, i * bstep + ko * 2, 0); }
;       }
	s_waitcnt lgkmcnt(14)
	v_mfma_f32_16x16x32_f16 a[236:239], v[174:177], v[76:79], a[236:239]
	v_mfma_f32_16x16x32_f16 a[232:235], v[88:91], v[76:79], a[232:235]
	v_mfma_f32_16x16x32_f16 a[228:231], v[84:87], v[76:79], a[228:231]
	s_add_i32 s23, s3, 0xfff90000
	v_mfma_f32_16x16x32_f16 a[224:227], v[80:83], v[76:79], a[224:227]
	s_mov_b32 s14, s10
	v_mfma_f32_16x16x32_f16 a[204:207], v[174:177], v[72:75], a[204:207]
	s_mov_b32 s15, s11
	v_mfma_f32_16x16x32_f16 a[200:203], v[88:91], v[72:75], a[200:203]
	buffer_load_dwordx4 v[106:109], v92, s[8:11], s23 offen
	v_mfma_f32_16x16x32_f16 a[196:199], v[84:87], v[72:75], a[196:199]
	buffer_load_dwordx4 v[110:113], v92, s[12:15], s23 offen
	v_mfma_f32_16x16x32_f16 a[192:195], v[80:83], v[72:75], a[192:195]
	s_add_i32 s23, s3, 0xfffa0000
	v_mfma_f32_16x16x32_f16 a[172:175], v[174:177], v[52:55], a[172:175]
	buffer_load_dwordx4 v[114:117], v92, s[8:11], s23 offen
	v_mfma_f32_16x16x32_f16 a[168:171], v[88:91], v[52:55], a[168:171]
	buffer_load_dwordx4 v[122:125], v92, s[12:15], s23 offen
	v_mfma_f32_16x16x32_f16 a[164:167], v[84:87], v[52:55], a[164:167]
	s_add_i32 s23, s3, 0xfffb0000
	v_mfma_f32_16x16x32_f16 a[160:163], v[80:83], v[52:55], a[160:163]
	buffer_load_dwordx4 v[118:121], v92, s[8:11], s23 offen
	v_mfma_f32_16x16x32_f16 a[140:143], v[174:177], v[44:47], a[140:143]
	buffer_load_dwordx4 v[126:129], v92, s[12:15], s23 offen
	v_mfma_f32_16x16x32_f16 a[136:139], v[88:91], v[44:47], a[136:139]
	s_add_i32 s23, s3, 0xfffc0000
	v_mfma_f32_16x16x32_f16 a[132:135], v[84:87], v[44:47], a[132:135]
	buffer_load_dwordx4 v[134:137], v92, s[8:11], s23 offen
	v_mfma_f32_16x16x32_f16 a[128:131], v[80:83], v[44:47], a[128:131]
	buffer_load_dwordx4 v[142:145], v92, s[12:15], s23 offen
	v_mfma_f32_16x16x32_f16 a[108:111], v[174:177], v[48:51], a[108:111]
	s_add_i32 s23, s3, 0xfffd0000
	v_mfma_f32_16x16x32_f16 a[104:107], v[88:91], v[48:51], a[104:107]
	buffer_load_dwordx4 v[138:141], v92, s[8:11], s23 offen
	v_mfma_f32_16x16x32_f16 a[100:103], v[84:87], v[48:51], a[100:103]
	buffer_load_dwordx4 v[146:149], v92, s[12:15], s23 offen
	v_mfma_f32_16x16x32_f16 a[96:99], v[80:83], v[48:51], a[96:99]
	s_add_i32 s23, s3, 0xfffe0000
	v_mfma_f32_16x16x32_f16 a[76:79], v[174:177], v[40:43], a[76:79]
	buffer_load_dwordx4 v[150:153], v92, s[8:11], s23 offen
	v_mfma_f32_16x16x32_f16 a[72:75], v[88:91], v[40:43], a[72:75]
	buffer_load_dwordx4 v[158:161], v92, s[12:15], s23 offen
	v_mfma_f32_16x16x32_f16 a[68:71], v[84:87], v[40:43], a[68:71]
	s_add_i32 s23, s3, 0xffff0000
	v_mfma_f32_16x16x32_f16 a[64:67], v[80:83], v[40:43], a[64:67]
	buffer_load_dwordx4 v[154:157], v92, s[8:11], s23 offen
	v_mfma_f32_16x16x32_f16 a[44:47], v[174:177], v[4:7], a[44:47]
	buffer_load_dwordx4 v[166:169], v92, s[12:15], s23 offen
	v_mfma_f32_16x16x32_f16 a[40:43], v[88:91], v[4:7], a[40:43]
	buffer_load_dwordx4 v[162:165], v92, s[8:11], s3 offen
	v_mfma_f32_16x16x32_f16 a[36:39], v[84:87], v[4:7], a[36:39]
	buffer_load_dwordx4 v[170:173], v92, s[12:15], s3 offen
	v_mfma_f32_16x16x32_f16 a[32:35], v[80:83], v[4:7], a[32:35]
	v_mfma_f32_16x16x32_f16 a[12:15], v[174:177], v[32:35], a[12:15]
	v_mfma_f32_16x16x32_f16 a[8:11], v[88:91], v[32:35], a[8:11]
	v_mfma_f32_16x16x32_f16 a[4:7], v[84:87], v[32:35], a[4:7]
	v_mfma_f32_16x16x32_f16 a[0:3], v[80:83], v[32:35], a[0:3]
	s_branch .LBB0_647
.Lgw3_nl:
	s_waitcnt lgkmcnt(14)
	v_mfma_f32_16x16x32_f16 a[236:239], v[174:177], v[76:79], a[236:239]
	v_mfma_f32_16x16x32_f16 a[232:235], v[88:91], v[76:79], a[232:235]
	v_mfma_f32_16x16x32_f16 a[228:231], v[84:87], v[76:79], a[228:231]
	v_mfma_f32_16x16x32_f16 a[224:227], v[80:83], v[76:79], a[224:227]
	v_mfma_f32_16x16x32_f16 a[204:207], v[174:177], v[72:75], a[204:207]
	v_mfma_f32_16x16x32_f16 a[200:203], v[88:91], v[72:75], a[200:203]
	v_mfma_f32_16x16x32_f16 a[196:199], v[84:87], v[72:75], a[196:199]
	v_mfma_f32_16x16x32_f16 a[192:195], v[80:83], v[72:75], a[192:195]
	v_mfma_f32_16x16x32_f16 a[172:175], v[174:177], v[52:55], a[172:175]
	v_mfma_f32_16x16x32_f16 a[168:171], v[88:91], v[52:55], a[168:171]
	v_mfma_f32_16x16x32_f16 a[164:167], v[84:87], v[52:55], a[164:167]
	v_mfma_f32_16x16x32_f16 a[160:163], v[80:83], v[52:55], a[160:163]
	v_mfma_f32_16x16x32_f16 a[140:143], v[174:177], v[44:47], a[140:143]
	v_mfma_f32_16x16x32_f16 a[136:139], v[88:91], v[44:47], a[136:139]
	v_mfma_f32_16x16x32_f16 a[132:135], v[84:87], v[44:47], a[132:135]
	v_mfma_f32_16x16x32_f16 a[128:131], v[80:83], v[44:47], a[128:131]
	v_mfma_f32_16x16x32_f16 a[108:111], v[174:177], v[48:51], a[108:111]
	v_mfma_f32_16x16x32_f16 a[104:107], v[88:91], v[48:51], a[104:107]
	v_mfma_f32_16x16x32_f16 a[100:103], v[84:87], v[48:51], a[100:103]
	v_mfma_f32_16x16x32_f16 a[96:99], v[80:83], v[48:51], a[96:99]
	v_mfma_f32_16x16x32_f16 a[76:79], v[174:177], v[40:43], a[76:79]
	v_mfma_f32_16x16x32_f16 a[72:75], v[88:91], v[40:43], a[72:75]
	v_mfma_f32_16x16x32_f16 a[68:71], v[84:87], v[40:43], a[68:71]
	v_mfma_f32_16x16x32_f16 a[64:67], v[80:83], v[40:43], a[64:67]
	v_mfma_f32_16x16x32_f16 a[44:47], v[174:177], v[4:7], a[44:47]
	v_mfma_f32_16x16x32_f16 a[40:43], v[88:91], v[4:7], a[40:43]
	v_mfma_f32_16x16x32_f16 a[36:39], v[84:87], v[4:7], a[36:39]
	v_mfma_f32_16x16x32_f16 a[32:35], v[80:83], v[4:7], a[32:35]
	v_mfma_f32_16x16x32_f16 a[12:15], v[174:177], v[32:35], a[12:15]
	v_mfma_f32_16x16x32_f16 a[8:11], v[88:91], v[32:35], a[8:11]
	v_mfma_f32_16x16x32_f16 a[4:7], v[84:87], v[32:35], a[4:7]
	v_mfma_f32_16x16x32_f16 a[0:3], v[80:83], v[32:35], a[0:3]
	s_branch .LBB0_647

; #define LD_AF(dst, ks_) _Pragma("unroll") for (int i = 0; i < 8; ++i) dst[i] = *(const h8*)(sA + i * 16 * G_LD + (ks_) * 32)
; #define LD_BF(dst, ks_, nh_) _Pragma("unroll") for (int i = 0; i < 4; ++i) dst[i] = *(const h8*)(sB + ((nh_) * 4 + i) * 16 * G_LD + (ks_) * 32)
; #define MMA_BLK(afx, bfx, nh_) _Pragma("unroll") for (int mi = 0; mi < 8; ++mi) _Pragma("unroll") for (int ni = 0; ni < 4; ++ni) mfma16_acc(acc[mi][(nh_) * 4 + ni], bfx[ni], afx[mi])
; template <class Epi>
; __device__ __forceinline__ void gemm_run(const GemmArgs g, Epi epi, char* smem) {
;     ...
;       const hf* sA = sbase + (kt & 1) * G_STAGE + (wm * 128 + fr) * G_LD + fqs;
;       const hf* sB = sbase + (kt & 1) * G_STAGE + (256 + wn * 128 + fr) * G_LD + fqs;
;       hf* st = sbase + ((kt + 1) & 1) * G_STAGE;
;       h8 afA[8], afB[8], bfA[4], bfB[4];
;     ...
;       LD_AF(afA, 0); LD_BF(bfA, 0, 0);
;       if (kt + 1 < nk) {
; #pragma unroll
;         for (int i = 0; i < 8; ++i) *(u4*)(st + (lr + 32 * i) * G_LD + lcw) = ra[i];
;       }
;       __builtin_amdgcn_sched_barrier(0);
;       LD_BF(bfB, 0, 1);
;       MMA_BLK(afA, bfA, 0);
;       __builtin_amdgcn_sched_barrier(0);
;       if (kt + 1 < nk) {
; #pragma unroll
;         for (int i = 0; i < 8; ++i) *(u4*)(st + (256 + lr + 32 * i) * G_LD + lcw) = rb[i];
;       }
;       LD_AF(afB, 1); LD_BF(bfA, 1, 0);
.LBB0_921:
	s_bitcmp1_b32 s21, 0
	s_cselect_b32 s11, 0x12000, 0
	s_add_i32 s11, s11, 16
	v_add3_u32 v56, s11, v131, v141
	v_add3_u32 v92, s11, v134, v141
	ds_read_b128 v[0:3], v56 offset:13824
	ds_read_b128 v[16:19], v92 offset:36864
	ds_read_b128 v[12:15], v92 offset:39168
	ds_read_b128 v[8:11], v92 offset:41472
	ds_read_b128 v[4:7], v92 offset:43776
	ds_read_b128 v[76:79], v56
	ds_read_b128 v[72:75], v56 offset:2304
	ds_read_b128 v[52:55], v56 offset:4608
	ds_read_b128 v[40:43], v56 offset:6912
	ds_read_b128 v[48:51], v56 offset:9216
	ds_read_b128 v[36:39], v56 offset:11520
	ds_read_b128 v[20:23], v56 offset:16128
	s_mov_b32 s10, s21
	s_add_i32 s21, s21, 1
	s_bitcmp1_b32 s21, 0
	s_cselect_b32 s11, 0x12000, 0
	v_add_u32_e32 v24, s11, v129
	v_add_u32_e32 v25, v24, v136
	s_waitcnt vmcnt(15)
	ds_write_b128 v25, v[94:97]
	s_waitcnt vmcnt(13)
	ds_write_b128 v25, v[102:105] offset:4608
	s_waitcnt vmcnt(11)
	ds_write_b128 v25, v[106:109] offset:9216
	s_waitcnt vmcnt(9)
	ds_write_b128 v25, v[118:121] offset:13824
	s_waitcnt vmcnt(7)
	ds_write_b128 v25, v[122:125] offset:18432
	s_waitcnt vmcnt(5)
	ds_write_b128 v25, v[150:153] offset:23040
	s_waitcnt vmcnt(3)
	ds_write_b128 v25, v[154:157] offset:27648
	s_waitcnt vmcnt(1)
	ds_write_b128 v25, v[162:165] offset:32256
	ds_read_b128 v[174:177], v92 offset:46080
	ds_read_b128 v[88:91], v92 offset:48384
	ds_read_b128 v[84:87], v92 offset:50688
	ds_read_b128 v[80:83], v92 offset:52992
	s_waitcnt lgkmcnt(14)
	v_mfma_f32_16x16x32_f16 a[208:211], v[16:19], v[76:79], a[208:211]
	v_mfma_f32_16x16x32_f16 a[200:203], v[12:15], v[76:79], a[200:203]
	v_mfma_f32_16x16x32_f16 a[196:199], v[8:11], v[76:79], a[196:199]
	v_mfma_f32_16x16x32_f16 a[192:195], v[4:7], v[76:79], a[192:195]
	v_mfma_f32_16x16x32_f16 a[188:191], v[16:19], v[72:75], a[188:191]
	v_mfma_f32_16x16x32_f16 a[184:187], v[12:15], v[72:75], a[184:187]
	v_mfma_f32_16x16x32_f16 a[180:183], v[8:11], v[72:75], a[180:183]
	v_mfma_f32_16x16x32_f16 a[176:179], v[4:7], v[72:75], a[176:179]
	v_mfma_f32_16x16x32_f16 a[156:159], v[16:19], v[52:55], a[156:159]
	v_mfma_f32_16x16x32_f16 a[152:155], v[12:15], v[52:55], a[152:155]
	v_mfma_f32_16x16x32_f16 a[148:151], v[8:11], v[52:55], a[148:151]
	v_mfma_f32_16x16x32_f16 a[144:147], v[4:7], v[52:55], a[144:147]
	v_mfma_f32_16x16x32_f16 a[124:127], v[16:19], v[40:43], a[124:127]
	v_mfma_f32_16x16x32_f16 a[120:123], v[12:15], v[40:43], a[120:123]
	v_mfma_f32_16x16x32_f16 a[116:119], v[8:11], v[40:43], a[116:119]
	v_mfma_f32_16x16x32_f16 a[112:115], v[4:7], v[40:43], a[112:115]
	v_mfma_f32_16x16x32_f16 a[92:95], v[16:19], v[48:51], a[92:95]
	v_mfma_f32_16x16x32_f16 a[88:91], v[12:15], v[48:51], a[88:91]
	v_mfma_f32_16x16x32_f16 a[84:87], v[8:11], v[48:51], a[84:87]
	v_mfma_f32_16x16x32_f16 a[80:83], v[4:7], v[48:51], a[80:83]
	s_waitcnt lgkmcnt(13)
	v_mfma_f32_16x16x32_f16 a[60:63], v[16:19], v[36:39], a[60:63]
	v_mfma_f32_16x16x32_f16 a[56:59], v[12:15], v[36:39], a[56:59]
	v_mfma_f32_16x16x32_f16 a[52:55], v[8:11], v[36:39], a[52:55]
	v_mfma_f32_16x16x32_f16 a[48:51], v[4:7], v[36:39], a[48:51]
	v_mfma_f32_16x16x32_f16 a[32:35], v[16:19], v[0:3], a[32:35]
	v_mfma_f32_16x16x32_f16 a[28:31], v[12:15], v[0:3], a[28:31]
	v_mfma_f32_16x16x32_f16 a[24:27], v[8:11], v[0:3], a[24:27]
	v_mfma_f32_16x16x32_f16 a[20:23], v[4:7], v[0:3], a[20:23]
	s_waitcnt lgkmcnt(12)
	v_mfma_f32_16x16x32_f16 a[12:15], v[16:19], v[20:23], a[12:15]
	v_mfma_f32_16x16x32_f16 a[8:11], v[12:15], v[20:23], a[8:11]
	v_mfma_f32_16x16x32_f16 a[4:7], v[8:11], v[20:23], a[4:7]
	v_mfma_f32_16x16x32_f16 a[0:3], v[4:7], v[20:23], a[0:3]
	v_add_u32_e32 v4, v24, v137
	s_waitcnt vmcnt(7)
	ds_write_b128 v25, v[98:101] offset:36864
	s_waitcnt vmcnt(6)
	ds_write_b128 v25, v[110:113] offset:41472
	s_waitcnt vmcnt(5)
	ds_write_b128 v25, v[114:117] offset:46080
	s_waitcnt vmcnt(4)
	ds_write_b128 v25, v[142:145] offset:50688
	s_waitcnt vmcnt(3)
	ds_write_b128 v25, v[146:149] offset:55296
	s_waitcnt vmcnt(2)
	ds_write_b128 v25, v[158:161] offset:59904
	s_waitcnt vmcnt(1)
	ds_write_b128 v25, v[166:169] offset:64512
	s_waitcnt vmcnt(0)
	ds_write_b128 v4, v[170:173]
	ds_read_b128 v[44:47], v56 offset:64
	ds_read_b128 v[32:35], v56 offset:2368
	ds_read_b128 v[28:31], v56 offset:4672
	ds_read_b128 v[24:27], v56 offset:6976
	ds_read_b128 v[16:19], v56 offset:9280
	ds_read_b128 v[12:15], v56 offset:11584
	ds_read_b128 v[8:11], v56 offset:13888
	ds_read_b128 v[4:7], v56 offset:16192
	ds_read_b128 v[56:59], v92 offset:36928
	ds_read_b128 v[60:63], v92 offset:39232
	ds_read_b128 v[64:67], v92 offset:41536
	ds_read_b128 v[68:71], v92 offset:43840
	s_cmp_gt_u32 s10, 29
	s_cbranch_scc1 .Lgw4_nl
; #define MMA_BLK(afx, bfx, nh_) _Pragma("unroll") for (int mi = 0; mi < 8; ++mi) _Pragma("unroll") for (int ni = 0; ni < 4; ++ni) mfma16_acc(acc[mi][(nh_) * 4 + ni], bfx[ni], afx[mi])
; template <class Epi>
; __device__ __forceinline__ void gemm_run(const GemmArgs g, Epi epi, char* smem) {
;     ...
;       MMA_BLK(afA, bfB, 1);
;       __builtin_amdgcn_sched_barrier(0);
;       if (kt + 2 < nk) {
;         const int ko = (kt + 2) * 64;
; #pragma unroll
;         for (int i = 0; i < 8; ++i) { ra[i] = __builtin_amdgcn_raw_buffer_load_b128(Ars, aoff, i * astep + ko * 2, 0); rb[i] = __builtin_amdgcn_raw_buffer_load_b128(Brs, boff, i * bstep + ko * 2, 0); }
;       }
	s_waitcnt lgkmcnt(14)
	v_mfma_f32_16x16x32_f16 a[240:243], v[174:177], v[76:79], a[240:243]
	v_mfma_f32_16x16x32_f16 a[252:255], v[88:91], v[76:79], a[252:255]
	v_mfma_f32_16x16x32_f16 a[248:251], v[84:87], v[76:79], a[248:251]
	s_add_i32 s78, s19, 0xfff20000
	v_mfma_f32_16x16x32_f16 a[244:247], v[80:83], v[76:79], a[244:247]
	s_mov_b32 s10, s6
	v_mfma_f32_16x16x32_f16 a[236:239], v[174:177], v[72:75], a[236:239]
	s_mov_b32 s11, s7
	v_mfma_f32_16x16x32_f16 a[232:235], v[88:91], v[72:75], a[232:235]
	buffer_load_dwordx4 v[94:97], v128, s[4:7], s78 offen
	v_mfma_f32_16x16x32_f16 a[228:231], v[84:87], v[72:75], a[228:231]
	buffer_load_dwordx4 v[98:101], v128, s[8:11], s78 offen
	v_mfma_f32_16x16x32_f16 a[224:227], v[80:83], v[72:75], a[224:227]
	s_add_i32 s78, s19, 0xfff40000
	v_mfma_f32_16x16x32_f16 a[220:223], v[174:177], v[52:55], a[220:223]
	buffer_load_dwordx4 v[102:105], v128, s[4:7], s78 offen
	v_mfma_f32_16x16x32_f16 a[216:219], v[88:91], v[52:55], a[216:219]
	buffer_load_dwordx4 v[110:113], v128, s[8:11], s78 offen
	v_mfma_f32_16x16x32_f16 a[212:215], v[84:87], v[52:55], a[212:215]
	s_add_i32 s78, s19, 0xfff60000
	v_mfma_f32_16x16x32_f16 a[204:207], v[80:83], v[52:55], a[204:207]
	buffer_load_dwordx4 v[106:109], v128, s[4:7], s78 offen
	v_mfma_f32_16x16x32_f16 a[172:175], v[174:177], v[40:43], a[172:175]
	buffer_load_dwordx4 v[114:117], v128, s[8:11], s78 offen
	v_mfma_f32_16x16x32_f16 a[168:171], v[88:91], v[40:43], a[168:171]
	s_add_i32 s78, s19, 0xfff80000
	v_mfma_f32_16x16x32_f16 a[164:167], v[84:87], v[40:43], a[164:167]
	buffer_load_dwordx4 v[118:121], v128, s[4:7], s78 offen
	v_mfma_f32_16x16x32_f16 a[160:163], v[80:83], v[40:43], a[160:163]
	buffer_load_dwordx4 v[142:145], v128, s[8:11], s78 offen
	v_mfma_f32_16x16x32_f16 a[140:143], v[174:177], v[48:51], a[140:143]
	s_add_i32 s78, s19, 0xfffa0000
	v_mfma_f32_16x16x32_f16 a[136:139], v[88:91], v[48:51], a[136:139]
	buffer_load_dwordx4 v[122:125], v128, s[4:7], s78 offen
	v_mfma_f32_16x16x32_f16 a[132:135], v[84:87], v[48:51], a[132:135]
	buffer_load_dwordx4 v[146:149], v128, s[8:11], s78 offen
	v_mfma_f32_16x16x32_f16 a[128:131], v[80:83], v[48:51], a[128:131]
	s_add_i32 s78, s19, 0xfffc0000
	v_mfma_f32_16x16x32_f16 a[108:111], v[174:177], v[36:39], a[108:111]
	buffer_load_dwordx4 v[150:153], v128, s[4:7], s78 offen
	v_mfma_f32_16x16x32_f16 a[104:107], v[88:91], v[36:39], a[104:107]
	buffer_load_dwordx4 v[158:161], v128, s[8:11], s78 offen
	v_mfma_f32_16x16x32_f16 a[100:103], v[84:87], v[36:39], a[100:103]
	s_add_i32 s78, s19, 0xfffe0000
	v_mfma_f32_16x16x32_f16 a[96:99], v[80:83], v[36:39], a[96:99]
	buffer_load_dwordx4 v[154:157], v128, s[4:7], s78 offen
	v_mfma_f32_16x16x32_f16 a[76:79], v[174:177], v[0:3], a[76:79]
	buffer_load_dwordx4 v[166:169], v128, s[8:11], s78 offen
	v_mfma_f32_16x16x32_f16 a[72:75], v[88:91], v[0:3], a[72:75]
	buffer_load_dwordx4 v[162:165], v128, s[4:7], s19 offen
	v_mfma_f32_16x16x32_f16 a[68:71], v[84:87], v[0:3], a[68:71]
	buffer_load_dwordx4 v[170:173], v128, s[8:11], s19 offen
	v_mfma_f32_16x16x32_f16 a[64:67], v[80:83], v[0:3], a[64:67]
	v_mfma_f32_16x16x32_f16 a[44:47], v[174:177], v[20:23], a[44:47]
	v_mfma_f32_16x16x32_f16 a[40:43], v[88:91], v[20:23], a[40:43]
	v_mfma_f32_16x16x32_f16 a[36:39], v[84:87], v[20:23], a[36:39]
	v_mfma_f32_16x16x32_f16 a[16:19], v[80:83], v[20:23], a[16:19]
	s_branch .LBB0_920
.Lgw4_nl:
	s_waitcnt lgkmcnt(14)
	v_mfma_f32_16x16x32_f16 a[240:243], v[174:177], v[76:79], a[240:243]
	v_mfma_f32_16x16x32_f16 a[252:255], v[88:91], v[76:79], a[252:255]
	v_mfma_f32_16x16x32_f16 a[248:251], v[84:87], v[76:79], a[248:251]
	v_mfma_f32_16x16x32_f16 a[244:247], v[80:83], v[76:79], a[244:247]
	v_mfma_f32_16x16x32_f16 a[236:239], v[174:177], v[72:75], a[236:239]
	v_mfma_f32_16x16x32_f16 a[232:235], v[88:91], v[72:75], a[232:235]
	v_mfma_f32_16x16x32_f16 a[228:231], v[84:87], v[72:75], a[228:231]
	v_mfma_f32_16x16x32_f16 a[224:227], v[80:83], v[72:75], a[224:227]
	v_mfma_f32_16x16x32_f16 a[220:223], v[174:177], v[52:55], a[220:223]
	v_mfma_f32_16x16x32_f16 a[216:219], v[88:91], v[52:55], a[216:219]
	v_mfma_f32_16x16x32_f16 a[212:215], v[84:87], v[52:55], a[212:215]
	v_mfma_f32_16x16x32_f16 a[204:207], v[80:83], v[52:55], a[204:207]
	v_mfma_f32_16x16x32_f16 a[172:175], v[174:177], v[40:43], a[172:175]
	v_mfma_f32_16x16x32_f16 a[168:171], v[88:91], v[40:43], a[168:171]
	v_mfma_f32_16x16x32_f16 a[164:167], v[84:87], v[40:43], a[164:167]
	v_mfma_f32_16x16x32_f16 a[160:163], v[80:83], v[40:43], a[160:163]
	v_mfma_f32_16x16x32_f16 a[140:143], v[174:177], v[48:51], a[140:143]
	v_mfma_f32_16x16x32_f16 a[136:139], v[88:91], v[48:51], a[136:139]
	v_mfma_f32_16x16x32_f16 a[132:135], v[84:87], v[48:51], a[132:135]
	v_mfma_f32_16x16x32_f16 a[128:131], v[80:83], v[48:51], a[128:131]
	v_mfma_f32_16x16x32_f16 a[108:111], v[174:177], v[36:39], a[108:111]
	v_mfma_f32_16x16x32_f16 a[104:107], v[88:91], v[36:39], a[104:107]
	v_mfma_f32_16x16x32_f16 a[100:103], v[84:87], v[36:39], a[100:103]
	v_mfma_f32_16x16x32_f16 a[96:99], v[80:83], v[36:39], a[96:99]
	v_mfma_f32_16x16x32_f16 a[76:79], v[174:177], v[0:3], a[76:79]
	v_mfma_f32_16x16x32_f16 a[72:75], v[88:91], v[0:3], a[72:75]
	v_mfma_f32_16x16x32_f16 a[68:71], v[84:87], v[0:3], a[68:71]
	v_mfma_f32_16x16x32_f16 a[64:67], v[80:83], v[0:3], a[64:67]
	v_mfma_f32_16x16x32_f16 a[44:47], v[174:177], v[20:23], a[44:47]
	v_mfma_f32_16x16x32_f16 a[40:43], v[88:91], v[20:23], a[40:43]
	v_mfma_f32_16x16x32_f16 a[36:39], v[84:87], v[20:23], a[36:39]
	v_mfma_f32_16x16x32_f16 a[16:19], v[80:83], v[20:23], a[16:19]
	s_branch .LBB0_920

; #define LD_AF(dst, ks_) _Pragma("unroll") for (int i = 0; i < 8; ++i) dst[i] = *(const h8*)(sA + i * 16 * G_LD + (ks_) * 32)
; #define LD_BF(dst, ks_, nh_) _Pragma("unroll") for (int i = 0; i < 4; ++i) dst[i] = *(const h8*)(sB + ((nh_) * 4 + i) * 16 * G_LD + (ks_) * 32)
; #define MMA_BLK(afx, bfx, nh_) _Pragma("unroll") for (int mi = 0; mi < 8; ++mi) _Pragma("unroll") for (int ni = 0; ni < 4; ++ni) mfma16_acc(acc[mi][(nh_) * 4 + ni], bfx[ni], afx[mi])
; template <class Epi>
; __device__ __forceinline__ void gemm_run(const GemmArgs g, Epi epi, char* smem) {
;     ...
;       const hf* sA = sbase + (kt & 1) * G_STAGE + (wm * 128 + fr) * G_LD + fqs;
;       const hf* sB = sbase + (kt & 1) * G_STAGE + (256 + wn * 128 + fr) * G_LD + fqs;
;       hf* st = sbase + ((kt + 1) & 1) * G_STAGE;
;       h8 afA[8], afB[8], bfA[4], bfB[4];
;     ...
;       LD_AF(afA, 0); LD_BF(bfA, 0, 0);
;       if (kt + 1 < nk) {
; #pragma unroll
;         for (int i = 0; i < 8; ++i) *(u4*)(st + (lr + 32 * i) * G_LD + lcw) = ra[i];
;       }
;       __builtin_amdgcn_sched_barrier(0);
;       LD_BF(bfB, 0, 1);
;       MMA_BLK(afA, bfA, 0);
;       __builtin_amdgcn_sched_barrier(0);
;       if (kt + 1 < nk) {
; #pragma unroll
;         for (int i = 0; i < 8; ++i) *(u4*)(st + (256 + lr + 32 * i) * G_LD + lcw) = rb[i];
;       }
;       LD_AF(afB, 1); LD_BF(bfA, 1, 0);
.LBB0_950:
	s_bitcmp1_b32 s19, 0
	s_cselect_b32 s11, 0x12000, 0
	s_add_i32 s11, s11, 16
	v_add3_u32 v56, s11, v94, v105
	v_add3_u32 v106, s11, v96, v105
	ds_read_b128 v[0:3], v56 offset:13824
	ds_read_b128 v[16:19], v106 offset:36864
	ds_read_b128 v[12:15], v106 offset:39168
	ds_read_b128 v[8:11], v106 offset:41472
	ds_read_b128 v[4:7], v106 offset:43776
	ds_read_b128 v[76:79], v56
	ds_read_b128 v[72:75], v56 offset:2304
	ds_read_b128 v[52:55], v56 offset:4608
	ds_read_b128 v[40:43], v56 offset:6912
	ds_read_b128 v[48:51], v56 offset:9216
	ds_read_b128 v[36:39], v56 offset:11520
	ds_read_b128 v[20:23], v56 offset:16128
	s_mov_b32 s10, s19
	s_add_i32 s19, s19, 1
	s_bitcmp1_b32 s19, 0
	s_cselect_b32 s11, 0x12000, 0
	v_add_u32_e32 v24, s11, v93
	v_add_u32_e32 v25, v24, v98
	s_waitcnt vmcnt(15)
	ds_write_b128 v25, v[108:111]
	s_waitcnt vmcnt(13)
	ds_write_b128 v25, v[116:119] offset:4608
	s_waitcnt vmcnt(11)
	ds_write_b128 v25, v[120:123] offset:9216
	s_waitcnt vmcnt(9)
	ds_write_b128 v25, v[134:137] offset:13824
	s_waitcnt vmcnt(7)
	ds_write_b128 v25, v[138:141] offset:18432
	s_waitcnt vmcnt(5)
	ds_write_b128 v25, v[150:153] offset:23040
	s_waitcnt vmcnt(3)
	ds_write_b128 v25, v[154:157] offset:27648
	s_waitcnt vmcnt(1)
	ds_write_b128 v25, v[162:165] offset:32256
	ds_read_b128 v[174:177], v106 offset:46080
	ds_read_b128 v[88:91], v106 offset:48384
	ds_read_b128 v[84:87], v106 offset:50688
	ds_read_b128 v[80:83], v106 offset:52992
	s_waitcnt lgkmcnt(14)
	v_mfma_f32_16x16x32_f16 a[120:123], v[16:19], v[76:79], a[120:123]
	v_mfma_f32_16x16x32_f16 a[116:119], v[12:15], v[76:79], a[116:119]
	v_mfma_f32_16x16x32_f16 a[112:115], v[8:11], v[76:79], a[112:115]
	v_mfma_f32_16x16x32_f16 a[160:163], v[4:7], v[76:79], a[160:163]
	v_mfma_f32_16x16x32_f16 a[152:155], v[16:19], v[72:75], a[152:155]
	v_mfma_f32_16x16x32_f16 a[148:151], v[12:15], v[72:75], a[148:151]
	v_mfma_f32_16x16x32_f16 a[144:147], v[8:11], v[72:75], a[144:147]
	v_mfma_f32_16x16x32_f16 a[136:139], v[4:7], v[72:75], a[136:139]
	v_mfma_f32_16x16x32_f16 a[108:111], v[16:19], v[52:55], a[108:111]
	v_mfma_f32_16x16x32_f16 a[104:107], v[12:15], v[52:55], a[104:107]
	v_mfma_f32_16x16x32_f16 a[100:103], v[8:11], v[52:55], a[100:103]
	v_mfma_f32_16x16x32_f16 a[92:95], v[4:7], v[52:55], a[92:95]
	v_mfma_f32_16x16x32_f16 a[80:83], v[16:19], v[40:43], a[80:83]
	v_mfma_f32_16x16x32_f16 a[76:79], v[12:15], v[40:43], a[76:79]
	v_mfma_f32_16x16x32_f16 a[72:75], v[8:11], v[40:43], a[72:75]
	v_mfma_f32_16x16x32_f16 a[68:71], v[4:7], v[40:43], a[68:71]
	v_mfma_f32_16x16x32_f16 a[64:67], v[16:19], v[48:51], a[64:67]
	v_mfma_f32_16x16x32_f16 a[60:63], v[12:15], v[48:51], a[60:63]
	v_mfma_f32_16x16x32_f16 a[56:59], v[8:11], v[48:51], a[56:59]
	v_mfma_f32_16x16x32_f16 a[52:55], v[4:7], v[48:51], a[52:55]
	s_waitcnt lgkmcnt(13)
	v_mfma_f32_16x16x32_f16 a[44:47], v[16:19], v[36:39], a[44:47]
	v_mfma_f32_16x16x32_f16 a[40:43], v[12:15], v[36:39], a[40:43]
	v_mfma_f32_16x16x32_f16 a[36:39], v[8:11], v[36:39], a[36:39]
	v_mfma_f32_16x16x32_f16 a[32:35], v[4:7], v[36:39], a[32:35]
	v_mfma_f32_16x16x32_f16 a[28:31], v[16:19], v[0:3], a[28:31]
	v_mfma_f32_16x16x32_f16 a[24:27], v[12:15], v[0:3], a[24:27]
	v_mfma_f32_16x16x32_f16 a[20:23], v[8:11], v[0:3], a[20:23]
	v_mfma_f32_16x16x32_f16 a[16:19], v[4:7], v[0:3], a[16:19]
	s_waitcnt lgkmcnt(12)
	v_mfma_f32_16x16x32_f16 a[12:15], v[16:19], v[20:23], a[12:15]
	v_mfma_f32_16x16x32_f16 a[8:11], v[12:15], v[20:23], a[8:11]
	v_mfma_f32_16x16x32_f16 a[4:7], v[8:11], v[20:23], a[4:7]
	v_mfma_f32_16x16x32_f16 a[0:3], v[4:7], v[20:23], a[0:3]
	v_add_u32_e32 v4, v24, v99
	s_waitcnt vmcnt(7)
	ds_write_b128 v25, v[112:115] offset:36864
	s_waitcnt vmcnt(6)
	ds_write_b128 v25, v[124:127] offset:41472
	s_waitcnt vmcnt(5)
	ds_write_b128 v25, v[128:131] offset:46080
	s_waitcnt vmcnt(4)
	ds_write_b128 v25, v[142:145] offset:50688
	s_waitcnt vmcnt(3)
	ds_write_b128 v25, v[146:149] offset:55296
	s_waitcnt vmcnt(2)
	ds_write_b128 v25, v[158:161] offset:59904
	s_waitcnt vmcnt(1)
	ds_write_b128 v25, v[166:169] offset:64512
	s_waitcnt vmcnt(0)
	ds_write_b128 v4, v[170:173]
	ds_read_b128 v[44:47], v56 offset:64
	ds_read_b128 v[32:35], v56 offset:2368
	ds_read_b128 v[28:31], v56 offset:4672
	ds_read_b128 v[24:27], v56 offset:6976
	ds_read_b128 v[16:19], v56 offset:9280
	ds_read_b128 v[12:15], v56 offset:11584
	ds_read_b128 v[8:11], v56 offset:13888
	ds_read_b128 v[4:7], v56 offset:16192
	ds_read_b128 v[56:59], v106 offset:36928
	ds_read_b128 v[60:63], v106 offset:39232
	ds_read_b128 v[64:67], v106 offset:41536
	ds_read_b128 v[68:71], v106 offset:43840
	s_cmp_gt_u32 s10, 29
	s_cbranch_scc1 .Lgw5_nl
; #define MMA_BLK(afx, bfx, nh_) _Pragma("unroll") for (int mi = 0; mi < 8; ++mi) _Pragma("unroll") for (int ni = 0; ni < 4; ++ni) mfma16_acc(acc[mi][(nh_) * 4 + ni], bfx[ni], afx[mi])
; template <class Epi>
; __device__ __forceinline__ void gemm_run(const GemmArgs g, Epi epi, char* smem) {
;     ...
;       MMA_BLK(afA, bfB, 1);
;       __builtin_amdgcn_sched_barrier(0);
;       if (kt + 2 < nk) {
;         const int ko = (kt + 2) * 64;
; #pragma unroll
;         for (int i = 0; i < 8; ++i) { ra[i] = __builtin_amdgcn_raw_buffer_load_b128(Ars, aoff, i * astep + ko * 2, 0); rb[i] = __builtin_amdgcn_raw_buffer_load_b128(Brs, boff, i * bstep + ko * 2, 0); }
;       }
	s_waitcnt lgkmcnt(14)
	v_mfma_f32_16x16x32_f16 a[252:255], v[174:177], v[76:79], a[252:255]
	v_mfma_f32_16x16x32_f16 a[248:251], v[88:91], v[76:79], a[248:251]
	v_mfma_f32_16x16x32_f16 a[244:247], v[84:87], v[76:79], a[244:247]
	s_add_i32 s75, s17, 0xfff20000
	v_mfma_f32_16x16x32_f16 a[240:243], v[80:83], v[76:79], a[240:243]
	s_mov_b32 s10, s6
	v_mfma_f32_16x16x32_f16 a[236:239], v[174:177], v[72:75], a[236:239]
	s_mov_b32 s11, s7
	v_mfma_f32_16x16x32_f16 a[232:235], v[88:91], v[72:75], a[232:235]
	buffer_load_dwordx4 v[108:111], v92, s[4:7], s75 offen
	v_mfma_f32_16x16x32_f16 a[228:231], v[84:87], v[72:75], a[228:231]
	buffer_load_dwordx4 v[112:115], v92, s[8:11], s75 offen
	v_mfma_f32_16x16x32_f16 a[224:227], v[80:83], v[72:75], a[224:227]
	s_add_i32 s75, s17, 0xfff40000
	v_mfma_f32_16x16x32_f16 a[220:223], v[174:177], v[52:55], a[220:223]
	buffer_load_dwordx4 v[116:119], v92, s[4:7], s75 offen
	v_mfma_f32_16x16x32_f16 a[216:219], v[88:91], v[52:55], a[216:219]
	buffer_load_dwordx4 v[124:127], v92, s[8:11], s75 offen
	v_mfma_f32_16x16x32_f16 a[212:215], v[84:87], v[52:55], a[212:215]
	s_add_i32 s75, s17, 0xfff60000
	v_mfma_f32_16x16x32_f16 a[208:211], v[80:83], v[52:55], a[208:211]
	buffer_load_dwordx4 v[120:123], v92, s[4:7], s75 offen
	v_mfma_f32_16x16x32_f16 a[204:207], v[174:177], v[40:43], a[204:207]
	buffer_load_dwordx4 v[128:131], v92, s[8:11], s75 offen
	v_mfma_f32_16x16x32_f16 a[200:203], v[88:91], v[40:43], a[200:203]
	s_add_i32 s75, s17, 0xfff80000
	v_mfma_f32_16x16x32_f16 a[196:199], v[84:87], v[40:43], a[196:199]
	buffer_load_dwordx4 v[134:137], v92, s[4:7], s75 offen
	v_mfma_f32_16x16x32_f16 a[192:195], v[80:83], v[40:43], a[192:195]
	buffer_load_dwordx4 v[142:145], v92, s[8:11], s75 offen
	v_mfma_f32_16x16x32_f16 a[188:191], v[174:177], v[48:51], a[188:191]
	s_add_i32 s75, s17, 0xfffa0000
	v_mfma_f32_16x16x32_f16 a[184:187], v[88:91], v[48:51], a[184:187]
	buffer_load_dwordx4 v[138:141], v92, s[4:7], s75 offen
	v_mfma_f32_16x16x32_f16 a[180:183], v[84:87], v[48:51], a[180:183]
	buffer_load_dwordx4 v[146:149], v92, s[8:11], s75 offen
	v_mfma_f32_16x16x32_f16 a[176:179], v[80:83], v[48:51], a[176:179]
	s_add_i32 s75, s17, 0xfffc0000
	v_mfma_f32_16x16x32_f16 a[172:175], v[174:177], v[36:39], a[172:175]
	buffer_load_dwordx4 v[150:153], v92, s[4:7], s75 offen
	v_mfma_f32_16x16x32_f16 a[168:171], v[88:91], v[36:39], a[168:171]
	buffer_load_dwordx4 v[158:161], v92, s[8:11], s75 offen
	v_mfma_f32_16x16x32_f16 a[164:167], v[84:87], v[36:39], a[164:167]
	s_add_i32 s75, s17, 0xfffe0000
	v_mfma_f32_16x16x32_f16 a[156:159], v[80:83], v[36:39], a[156:159]
	buffer_load_dwordx4 v[154:157], v92, s[4:7], s75 offen
	v_mfma_f32_16x16x32_f16 a[140:143], v[174:177], v[0:3], a[140:143]
	buffer_load_dwordx4 v[166:169], v92, s[8:11], s75 offen
	v_mfma_f32_16x16x32_f16 a[132:135], v[88:91], v[0:3], a[132:135]
	buffer_load_dwordx4 v[162:165], v92, s[4:7], s17 offen
	v_mfma_f32_16x16x32_f16 a[128:131], v[84:87], v[0:3], a[128:131]
	buffer_load_dwordx4 v[170:173], v92, s[8:11], s17 offen
	v_mfma_f32_16x16x32_f16 a[124:127], v[80:83], v[0:3], a[124:127]
	v_mfma_f32_16x16x32_f16 a[96:99], v[174:177], v[20:23], a[96:99]
	v_mfma_f32_16x16x32_f16 a[88:91], v[88:91], v[20:23], a[88:91]
	v_mfma_f32_16x16x32_f16 a[84:87], v[84:87], v[20:23], a[84:87]
	v_mfma_f32_16x16x32_f16 a[48:51], v[80:83], v[20:23], a[48:51]
	s_branch .LBB0_949
.Lgw5_nl:
	s_waitcnt lgkmcnt(14)
	v_mfma_f32_16x16x32_f16 a[252:255], v[174:177], v[76:79], a[252:255]
	v_mfma_f32_16x16x32_f16 a[248:251], v[88:91], v[76:79], a[248:251]
	v_mfma_f32_16x16x32_f16 a[244:247], v[84:87], v[76:79], a[244:247]
	v_mfma_f32_16x16x32_f16 a[240:243], v[80:83], v[76:79], a[240:243]
	v_mfma_f32_16x16x32_f16 a[236:239], v[174:177], v[72:75], a[236:239]
	v_mfma_f32_16x16x32_f16 a[232:235], v[88:91], v[72:75], a[232:235]
	v_mfma_f32_16x16x32_f16 a[228:231], v[84:87], v[72:75], a[228:231]
	v_mfma_f32_16x16x32_f16 a[224:227], v[80:83], v[72:75], a[224:227]
	v_mfma_f32_16x16x32_f16 a[220:223], v[174:177], v[52:55], a[220:223]
	v_mfma_f32_16x16x32_f16 a[216:219], v[88:91], v[52:55], a[216:219]
	v_mfma_f32_16x16x32_f16 a[212:215], v[84:87], v[52:55], a[212:215]
	v_mfma_f32_16x16x32_f16 a[208:211], v[80:83], v[52:55], a[208:211]
	v_mfma_f32_16x16x32_f16 a[204:207], v[174:177], v[40:43], a[204:207]
	v_mfma_f32_16x16x32_f16 a[200:203], v[88:91], v[40:43], a[200:203]
	v_mfma_f32_16x16x32_f16 a[196:199], v[84:87], v[40:43], a[196:199]
	v_mfma_f32_16x16x32_f16 a[192:195], v[80:83], v[40:43], a[192:195]
	v_mfma_f32_16x16x32_f16 a[188:191], v[174:177], v[48:51], a[188:191]
	v_mfma_f32_16x16x32_f16 a[184:187], v[88:91], v[48:51], a[184:187]
	v_mfma_f32_16x16x32_f16 a[180:183], v[84:87], v[48:51], a[180:183]
	v_mfma_f32_16x16x32_f16 a[176:179], v[80:83], v[48:51], a[176:179]
	v_mfma_f32_16x16x32_f16 a[172:175], v[174:177], v[36:39], a[172:175]
	v_mfma_f32_16x16x32_f16 a[168:171], v[88:91], v[36:39], a[168:171]
	v_mfma_f32_16x16x32_f16 a[164:167], v[84:87], v[36:39], a[164:167]
	v_mfma_f32_16x16x32_f16 a[156:159], v[80:83], v[36:39], a[156:159]
	v_mfma_f32_16x16x32_f16 a[140:143], v[174:177], v[0:3], a[140:143]
	v_mfma_f32_16x16x32_f16 a[132:135], v[88:91], v[0:3], a[132:135]
	v_mfma_f32_16x16x32_f16 a[128:131], v[84:87], v[0:3], a[128:131]
	v_mfma_f32_16x16x32_f16 a[124:127], v[80:83], v[0:3], a[124:127]
	v_mfma_f32_16x16x32_f16 a[96:99], v[174:177], v[20:23], a[96:99]
	v_mfma_f32_16x16x32_f16 a[88:91], v[88:91], v[20:23], a[88:91]
	v_mfma_f32_16x16x32_f16 a[84:87], v[84:87], v[20:23], a[84:87]
	v_mfma_f32_16x16x32_f16 a[48:51], v[80:83], v[20:23], a[48:51]
	s_branch .LBB0_949

; #define LD_AF(dst, ks_) _Pragma("unroll") for (int i = 0; i < 8; ++i) dst[i] = *(const h8*)(sA + i * 16 * G_LD + (ks_) * 32)
; #define LD_BF(dst, ks_, nh_) _Pragma("unroll") for (int i = 0; i < 4; ++i) dst[i] = *(const h8*)(sB + ((nh_) * 4 + i) * 16 * G_LD + (ks_) * 32)
; #define MMA_BLK(afx, bfx, nh_) _Pragma("unroll") for (int mi = 0; mi < 8; ++mi) _Pragma("unroll") for (int ni = 0; ni < 4; ++ni) mfma16_acc(acc[mi][(nh_) * 4 + ni], bfx[ni], afx[mi])
; template <class Epi>
; __device__ __forceinline__ void gemm_run(const GemmArgs g, Epi epi, char* smem) {
;     ...
;       const hf* sA = sbase + (kt & 1) * G_STAGE + (wm * 128 + fr) * G_LD + fqs;
;       const hf* sB = sbase + (kt & 1) * G_STAGE + (256 + wn * 128 + fr) * G_LD + fqs;
;       hf* st = sbase + ((kt + 1) & 1) * G_STAGE;
;       h8 afA[8], afB[8], bfA[4], bfB[4];
;     ...
;       LD_AF(afA, 0); LD_BF(bfA, 0, 0);
;       if (kt + 1 < nk) {
; #pragma unroll
;         for (int i = 0; i < 8; ++i) *(u4*)(st + (lr + 32 * i) * G_LD + lcw) = ra[i];
;       }
;       __builtin_amdgcn_sched_barrier(0);
;       LD_BF(bfB, 0, 1);
;       MMA_BLK(afA, bfA, 0);
;       __builtin_amdgcn_sched_barrier(0);
;       if (kt + 1 < nk) {
; #pragma unroll
;         for (int i = 0; i < 8; ++i) *(u4*)(st + (256 + lr + 32 * i) * G_LD + lcw) = rb[i];
;       }
;       LD_AF(afB, 1); LD_BF(bfA, 1, 0);
.LBB0_1002:
	s_bitcmp1_b32 s85, 0
	s_cselect_b32 s11, 0x12000, 0
	s_add_i32 s11, s11, 16
	v_add3_u32 v56, s11, v133, v141
	v_add3_u32 v92, s11, v134, v141
	ds_read_b128 v[4:7], v56 offset:13824
	ds_read_b128 v[16:19], v92 offset:36864
	ds_read_b128 v[12:15], v92 offset:39168
	ds_read_b128 v[8:11], v92 offset:41472
	ds_read_b128 v[0:3], v92 offset:43776
	ds_read_b128 v[76:79], v56
	ds_read_b128 v[72:75], v56 offset:2304
	ds_read_b128 v[52:55], v56 offset:4608
	ds_read_b128 v[44:47], v56 offset:6912
	ds_read_b128 v[48:51], v56 offset:9216
	ds_read_b128 v[40:43], v56 offset:11520
	ds_read_b128 v[32:35], v56 offset:16128
	s_mov_b32 s10, s85
	s_add_i32 s85, s85, 1
	s_bitcmp1_b32 s85, 0
	s_cselect_b32 s11, 0x12000, 0
	v_add_u32_e32 v20, s11, v131
	v_add_u32_e32 v21, v20, v136
	s_waitcnt vmcnt(15)
	ds_write_b128 v21, v[94:97]
	s_waitcnt vmcnt(13)
	ds_write_b128 v21, v[102:105] offset:4608
	s_waitcnt vmcnt(11)
	ds_write_b128 v21, v[106:109] offset:9216
	s_waitcnt vmcnt(9)
	ds_write_b128 v21, v[118:121] offset:13824
	s_waitcnt vmcnt(7)
	ds_write_b128 v21, v[122:125] offset:18432
	s_waitcnt vmcnt(5)
	ds_write_b128 v21, v[146:149] offset:23040
	s_waitcnt vmcnt(3)
	ds_write_b128 v21, v[150:153] offset:27648
	s_waitcnt vmcnt(1)
	ds_write_b128 v21, v[158:161] offset:32256
	ds_read_b128 v[170:173], v92 offset:46080
	ds_read_b128 v[88:91], v92 offset:48384
	ds_read_b128 v[84:87], v92 offset:50688
	ds_read_b128 v[80:83], v92 offset:52992
	s_waitcnt lgkmcnt(14)
	v_mfma_f32_16x16x32_f16 a[204:207], v[16:19], v[76:79], a[204:207]
	v_mfma_f32_16x16x32_f16 a[200:203], v[12:15], v[76:79], a[200:203]
	v_mfma_f32_16x16x32_f16 a[196:199], v[8:11], v[76:79], a[196:199]
	v_mfma_f32_16x16x32_f16 a[188:191], v[0:3], v[76:79], a[188:191]
	v_mfma_f32_16x16x32_f16 a[192:195], v[16:19], v[72:75], a[192:195]
	v_mfma_f32_16x16x32_f16 a[184:187], v[12:15], v[72:75], a[184:187]
	v_mfma_f32_16x16x32_f16 a[180:183], v[8:11], v[72:75], a[180:183]
	v_mfma_f32_16x16x32_f16 a[176:179], v[0:3], v[72:75], a[176:179]
	v_mfma_f32_16x16x32_f16 a[156:159], v[16:19], v[52:55], a[156:159]
	v_mfma_f32_16x16x32_f16 a[152:155], v[12:15], v[52:55], a[152:155]
	v_mfma_f32_16x16x32_f16 a[148:151], v[8:11], v[52:55], a[148:151]
	v_mfma_f32_16x16x32_f16 a[144:147], v[0:3], v[52:55], a[144:147]
	v_mfma_f32_16x16x32_f16 a[124:127], v[16:19], v[44:47], a[124:127]
	v_mfma_f32_16x16x32_f16 a[120:123], v[12:15], v[44:47], a[120:123]
	v_mfma_f32_16x16x32_f16 a[116:119], v[8:11], v[44:47], a[116:119]
	v_mfma_f32_16x16x32_f16 a[112:115], v[0:3], v[44:47], a[112:115]
	v_mfma_f32_16x16x32_f16 a[92:95], v[16:19], v[48:51], a[92:95]
	v_mfma_f32_16x16x32_f16 a[88:91], v[12:15], v[48:51], a[88:91]
	v_mfma_f32_16x16x32_f16 a[84:87], v[8:11], v[48:51], a[84:87]
	v_mfma_f32_16x16x32_f16 a[80:83], v[0:3], v[48:51], a[80:83]
	s_waitcnt lgkmcnt(13)
	v_mfma_f32_16x16x32_f16 a[60:63], v[16:19], v[40:43], a[60:63]
	v_mfma_f32_16x16x32_f16 a[56:59], v[12:15], v[40:43], a[56:59]
	v_mfma_f32_16x16x32_f16 a[52:55], v[8:11], v[40:43], a[52:55]
	v_mfma_f32_16x16x32_f16 a[48:51], v[0:3], v[40:43], a[48:51]
	v_mfma_f32_16x16x32_f16 a[32:35], v[16:19], v[4:7], a[32:35]
	v_mfma_f32_16x16x32_f16 a[28:31], v[12:15], v[4:7], a[28:31]
	v_mfma_f32_16x16x32_f16 a[24:27], v[8:11], v[4:7], a[24:27]
	v_mfma_f32_16x16x32_f16 a[20:23], v[0:3], v[4:7], a[20:23]
	s_waitcnt lgkmcnt(12)
	v_mfma_f32_16x16x32_f16 a[12:15], v[16:19], v[32:35], a[12:15]
	v_mfma_f32_16x16x32_f16 a[8:11], v[12:15], v[32:35], a[8:11]
	v_mfma_f32_16x16x32_f16 a[4:7], v[8:11], v[32:35], a[4:7]
	v_mfma_f32_16x16x32_f16 a[0:3], v[0:3], v[32:35], a[0:3]
	v_add_u32_e32 v0, v20, v137
	s_waitcnt vmcnt(7)
	ds_write_b128 v21, v[98:101] offset:36864
	s_waitcnt vmcnt(6)
	ds_write_b128 v21, v[110:113] offset:41472
	s_waitcnt vmcnt(5)
	ds_write_b128 v21, v[114:117] offset:46080
	s_waitcnt vmcnt(4)
	ds_write_b128 v21, v[126:129] offset:50688
	s_waitcnt vmcnt(3)
	ds_write_b128 v21, v[142:145] offset:55296
	s_waitcnt vmcnt(2)
	ds_write_b128 v21, v[154:157] offset:59904
	s_waitcnt vmcnt(1)
	ds_write_b128 v21, v[162:165] offset:64512
	s_waitcnt vmcnt(0)
	ds_write_b128 v0, v[166:169]
	ds_read_b128 v[36:39], v56 offset:64
	ds_read_b128 v[28:31], v56 offset:2368
	ds_read_b128 v[24:27], v56 offset:4672
	ds_read_b128 v[20:23], v56 offset:6976
	ds_read_b128 v[16:19], v56 offset:9280
	ds_read_b128 v[12:15], v56 offset:11584
	ds_read_b128 v[8:11], v56 offset:13888
	ds_read_b128 v[0:3], v56 offset:16192
	ds_read_b128 v[56:59], v92 offset:36928
	ds_read_b128 v[60:63], v92 offset:39232
	ds_read_b128 v[64:67], v92 offset:41536
	ds_read_b128 v[68:71], v92 offset:43840
	s_cmpk_gt_u32 s10, 0x55
	s_cbranch_scc1 .Lgw6_nl
; #define MMA_BLK(afx, bfx, nh_) _Pragma("unroll") for (int mi = 0; mi < 8; ++mi) _Pragma("unroll") for (int ni = 0; ni < 4; ++ni) mfma16_acc(acc[mi][(nh_) * 4 + ni], bfx[ni], afx[mi])
; template <class Epi>
; __device__ __forceinline__ void gemm_run(const GemmArgs g, Epi epi, char* smem) {
;     ...
;       MMA_BLK(afA, bfB, 1);
;       __builtin_amdgcn_sched_barrier(0);
;       if (kt + 2 < nk) {
;         const int ko = (kt + 2) * 64;
; #pragma unroll
;         for (int i = 0; i < 8; ++i) { ra[i] = __builtin_amdgcn_raw_buffer_load_b128(Ars, aoff, i * astep + ko * 2, 0); rb[i] = __builtin_amdgcn_raw_buffer_load_b128(Brs, boff, i * bstep + ko * 2, 0); }
;       }
	s_waitcnt lgkmcnt(14)
	v_mfma_f32_16x16x32_f16 a[240:243], v[170:173], v[76:79], a[240:243]
	v_mfma_f32_16x16x32_f16 a[252:255], v[88:91], v[76:79], a[252:255]
	v_mfma_f32_16x16x32_f16 a[248:251], v[84:87], v[76:79], a[248:251]
	s_add_i32 s86, s84, 0xffd98000
	v_mfma_f32_16x16x32_f16 a[244:247], v[80:83], v[76:79], a[244:247]
	s_mov_b32 s10, s6
	v_mfma_f32_16x16x32_f16 a[236:239], v[170:173], v[72:75], a[236:239]
	s_mov_b32 s11, s7
	v_mfma_f32_16x16x32_f16 a[232:235], v[88:91], v[72:75], a[232:235]
	buffer_load_dwordx4 v[94:97], v130, s[4:7], s86 offen
	v_mfma_f32_16x16x32_f16 a[228:231], v[84:87], v[72:75], a[228:231]
	buffer_load_dwordx4 v[98:101], v130, s[8:11], s86 offen
	v_mfma_f32_16x16x32_f16 a[224:227], v[80:83], v[72:75], a[224:227]
	s_add_i32 s86, s84, 0xffdf0000
	v_mfma_f32_16x16x32_f16 a[220:223], v[170:173], v[52:55], a[220:223]
	buffer_load_dwordx4 v[102:105], v130, s[4:7], s86 offen
	v_mfma_f32_16x16x32_f16 a[216:219], v[88:91], v[52:55], a[216:219]
	buffer_load_dwordx4 v[110:113], v130, s[8:11], s86 offen
	v_mfma_f32_16x16x32_f16 a[212:215], v[84:87], v[52:55], a[212:215]
	s_add_i32 s86, s84, 0xffe48000
	v_mfma_f32_16x16x32_f16 a[208:211], v[80:83], v[52:55], a[208:211]
	buffer_load_dwordx4 v[106:109], v130, s[4:7], s86 offen
	v_mfma_f32_16x16x32_f16 a[172:175], v[170:173], v[44:47], a[172:175]
	buffer_load_dwordx4 v[114:117], v130, s[8:11], s86 offen
	v_mfma_f32_16x16x32_f16 a[168:171], v[88:91], v[44:47], a[168:171]
	s_add_i32 s86, s84, 0xffea0000
	v_mfma_f32_16x16x32_f16 a[164:167], v[84:87], v[44:47], a[164:167]
	buffer_load_dwordx4 v[118:121], v130, s[4:7], s86 offen
	v_mfma_f32_16x16x32_f16 a[160:163], v[80:83], v[44:47], a[160:163]
	buffer_load_dwordx4 v[126:129], v130, s[8:11], s86 offen
	v_mfma_f32_16x16x32_f16 a[140:143], v[170:173], v[48:51], a[140:143]
	s_add_i32 s86, s84, 0xffef8000
	v_mfma_f32_16x16x32_f16 a[136:139], v[88:91], v[48:51], a[136:139]
	buffer_load_dwordx4 v[122:125], v130, s[4:7], s86 offen
	v_mfma_f32_16x16x32_f16 a[132:135], v[84:87], v[48:51], a[132:135]
	buffer_load_dwordx4 v[142:145], v130, s[8:11], s86 offen
	v_mfma_f32_16x16x32_f16 a[128:131], v[80:83], v[48:51], a[128:131]
	s_add_i32 s86, s84, 0xfff50000
	v_mfma_f32_16x16x32_f16 a[108:111], v[170:173], v[40:43], a[108:111]
	buffer_load_dwordx4 v[146:149], v130, s[4:7], s86 offen
	v_mfma_f32_16x16x32_f16 a[104:107], v[88:91], v[40:43], a[104:107]
	buffer_load_dwordx4 v[154:157], v130, s[8:11], s86 offen
	v_mfma_f32_16x16x32_f16 a[100:103], v[84:87], v[40:43], a[100:103]
	s_add_i32 s86, s84, 0xfffa8000
	v_mfma_f32_16x16x32_f16 a[96:99], v[80:83], v[40:43], a[96:99]
	buffer_load_dwordx4 v[150:153], v130, s[4:7], s86 offen
	v_mfma_f32_16x16x32_f16 a[76:79], v[170:173], v[4:7], a[76:79]
	buffer_load_dwordx4 v[162:165], v130, s[8:11], s86 offen
	v_mfma_f32_16x16x32_f16 a[72:75], v[88:91], v[4:7], a[72:75]
	buffer_load_dwordx4 v[158:161], v130, s[4:7], s84 offen
	v_mfma_f32_16x16x32_f16 a[68:71], v[84:87], v[4:7], a[68:71]
	buffer_load_dwordx4 v[166:169], v130, s[8:11], s84 offen
	v_mfma_f32_16x16x32_f16 a[64:67], v[80:83], v[4:7], a[64:67]
	v_mfma_f32_16x16x32_f16 a[44:47], v[170:173], v[32:35], a[44:47]
	v_mfma_f32_16x16x32_f16 a[40:43], v[88:91], v[32:35], a[40:43]
	v_mfma_f32_16x16x32_f16 a[36:39], v[84:87], v[32:35], a[36:39]
	v_mfma_f32_16x16x32_f16 a[16:19], v[80:83], v[32:35], a[16:19]
	s_branch .LBB0_1001
.Lgw6_nl:
	s_waitcnt lgkmcnt(14)
	v_mfma_f32_16x16x32_f16 a[240:243], v[170:173], v[76:79], a[240:243]
	v_mfma_f32_16x16x32_f16 a[252:255], v[88:91], v[76:79], a[252:255]
	v_mfma_f32_16x16x32_f16 a[248:251], v[84:87], v[76:79], a[248:251]
	v_mfma_f32_16x16x32_f16 a[244:247], v[80:83], v[76:79], a[244:247]
	v_mfma_f32_16x16x32_f16 a[236:239], v[170:173], v[72:75], a[236:239]
	v_mfma_f32_16x16x32_f16 a[232:235], v[88:91], v[72:75], a[232:235]
	v_mfma_f32_16x16x32_f16 a[228:231], v[84:87], v[72:75], a[228:231]
	v_mfma_f32_16x16x32_f16 a[224:227], v[80:83], v[72:75], a[224:227]
	v_mfma_f32_16x16x32_f16 a[220:223], v[170:173], v[52:55], a[220:223]
	v_mfma_f32_16x16x32_f16 a[216:219], v[88:91], v[52:55], a[216:219]
	v_mfma_f32_16x16x32_f16 a[212:215], v[84:87], v[52:55], a[212:215]
	v_mfma_f32_16x16x32_f16 a[208:211], v[80:83], v[52:55], a[208:211]
	v_mfma_f32_16x16x32_f16 a[172:175], v[170:173], v[44:47], a[172:175]
	v_mfma_f32_16x16x32_f16 a[168:171], v[88:91], v[44:47], a[168:171]
	v_mfma_f32_16x16x32_f16 a[164:167], v[84:87], v[44:47], a[164:167]
	v_mfma_f32_16x16x32_f16 a[160:163], v[80:83], v[44:47], a[160:163]
	v_mfma_f32_16x16x32_f16 a[140:143], v[170:173], v[48:51], a[140:143]
	v_mfma_f32_16x16x32_f16 a[136:139], v[88:91], v[48:51], a[136:139]
	v_mfma_f32_16x16x32_f16 a[132:135], v[84:87], v[48:51], a[132:135]
	v_mfma_f32_16x16x32_f16 a[128:131], v[80:83], v[48:51], a[128:131]
	v_mfma_f32_16x16x32_f16 a[108:111], v[170:173], v[40:43], a[108:111]
	v_mfma_f32_16x16x32_f16 a[104:107], v[88:91], v[40:43], a[104:107]
	v_mfma_f32_16x16x32_f16 a[100:103], v[84:87], v[40:43], a[100:103]
	v_mfma_f32_16x16x32_f16 a[96:99], v[80:83], v[40:43], a[96:99]
	v_mfma_f32_16x16x32_f16 a[76:79], v[170:173], v[4:7], a[76:79]
	v_mfma_f32_16x16x32_f16 a[72:75], v[88:91], v[4:7], a[72:75]
	v_mfma_f32_16x16x32_f16 a[68:71], v[84:87], v[4:7], a[68:71]
	v_mfma_f32_16x16x32_f16 a[64:67], v[80:83], v[4:7], a[64:67]
	v_mfma_f32_16x16x32_f16 a[44:47], v[170:173], v[32:35], a[44:47]
	v_mfma_f32_16x16x32_f16 a[40:43], v[88:91], v[32:35], a[40:43]
	v_mfma_f32_16x16x32_f16 a[36:39], v[84:87], v[32:35], a[36:39]
	v_mfma_f32_16x16x32_f16 a[16:19], v[80:83], v[32:35], a[16:19]
	s_branch .LBB0_1001

; #define LD_AF(dst, ks_) _Pragma("unroll") for (int i = 0; i < 8; ++i) dst[i] = *(const h8*)(sA + i * 16 * G_LD + (ks_) * 32)
; #define LD_BF(dst, ks_, nh_) _Pragma("unroll") for (int i = 0; i < 4; ++i) dst[i] = *(const h8*)(sB + ((nh_) * 4 + i) * 16 * G_LD + (ks_) * 32)
; #define MMA_BLK(afx, bfx, nh_) _Pragma("unroll") for (int mi = 0; mi < 8; ++mi) _Pragma("unroll") for (int ni = 0; ni < 4; ++ni) mfma16_acc(acc[mi][(nh_) * 4 + ni], bfx[ni], afx[mi])
; template <class Epi>
; __device__ __forceinline__ void gemm_run(const GemmArgs g, Epi epi, char* smem) {
;     ...
;       const hf* sA = sbase + (kt & 1) * G_STAGE + (wm * 128 + fr) * G_LD + fqs;
;       const hf* sB = sbase + (kt & 1) * G_STAGE + (256 + wn * 128 + fr) * G_LD + fqs;
;       hf* st = sbase + ((kt + 1) & 1) * G_STAGE;
;       h8 afA[8], afB[8], bfA[4], bfB[4];
;     ...
;       LD_AF(afA, 0); LD_BF(bfA, 0, 0);
;       if (kt + 1 < nk) {
; #pragma unroll
;         for (int i = 0; i < 8; ++i) *(u4*)(st + (lr + 32 * i) * G_LD + lcw) = ra[i];
;       }
;       __builtin_amdgcn_sched_barrier(0);
;       LD_BF(bfB, 0, 1);
;       MMA_BLK(afA, bfA, 0);
;       __builtin_amdgcn_sched_barrier(0);
;       if (kt + 1 < nk) {
; #pragma unroll
;         for (int i = 0; i < 8; ++i) *(u4*)(st + (256 + lr + 32 * i) * G_LD + lcw) = rb[i];
;       }
;       LD_AF(afB, 1); LD_BF(bfA, 1, 0);
.LBB0_1008:
	s_bitcmp1_b32 s23, 0
	s_cselect_b32 s15, 0x12000, 0
	s_add_i32 s15, s15, 16
	v_add3_u32 v56, s15, v94, v105
	v_add3_u32 v106, s15, v96, v105
	ds_read_b128 v[4:7], v56 offset:13824
	ds_read_b128 v[16:19], v106 offset:36864
	ds_read_b128 v[12:15], v106 offset:39168
	ds_read_b128 v[8:11], v106 offset:41472
	ds_read_b128 v[0:3], v106 offset:43776
	ds_read_b128 v[76:79], v56
	ds_read_b128 v[72:75], v56 offset:2304
	ds_read_b128 v[52:55], v56 offset:4608
	ds_read_b128 v[44:47], v56 offset:6912
	ds_read_b128 v[48:51], v56 offset:9216
	ds_read_b128 v[40:43], v56 offset:11520
	ds_read_b128 v[32:35], v56 offset:16128
	s_mov_b32 s14, s23
	s_add_i32 s23, s23, 1
	s_bitcmp1_b32 s23, 0
	s_cselect_b32 s15, 0x12000, 0
	v_add_u32_e32 v20, s15, v93
	v_add_u32_e32 v21, v20, v98
	s_waitcnt vmcnt(15)
	ds_write_b128 v21, v[108:111]
	s_waitcnt vmcnt(13)
	ds_write_b128 v21, v[116:119] offset:4608
	s_waitcnt vmcnt(11)
	ds_write_b128 v21, v[120:123] offset:9216
	s_waitcnt vmcnt(9)
	ds_write_b128 v21, v[132:135] offset:13824
	s_waitcnt vmcnt(7)
	ds_write_b128 v21, v[136:139] offset:18432
	s_waitcnt vmcnt(5)
	ds_write_b128 v21, v[148:151] offset:23040
	s_waitcnt vmcnt(3)
	ds_write_b128 v21, v[152:155] offset:27648
	s_waitcnt vmcnt(1)
	ds_write_b128 v21, v[160:163] offset:32256
	ds_read_b128 v[172:175], v106 offset:46080
	ds_read_b128 v[88:91], v106 offset:48384
	ds_read_b128 v[84:87], v106 offset:50688
	ds_read_b128 v[80:83], v106 offset:52992
	s_waitcnt lgkmcnt(14)
	v_mfma_f32_16x16x32_f16 a[116:119], v[16:19], v[76:79], a[116:119]
	v_mfma_f32_16x16x32_f16 a[108:111], v[12:15], v[76:79], a[108:111]
	v_mfma_f32_16x16x32_f16 a[100:103], v[8:11], v[76:79], a[100:103]
	v_mfma_f32_16x16x32_f16 a[160:163], v[0:3], v[76:79], a[160:163]
	v_mfma_f32_16x16x32_f16 a[152:155], v[16:19], v[72:75], a[152:155]
	v_mfma_f32_16x16x32_f16 a[148:151], v[12:15], v[72:75], a[148:151]
	v_mfma_f32_16x16x32_f16 a[144:147], v[8:11], v[72:75], a[144:147]
	v_mfma_f32_16x16x32_f16 a[136:139], v[0:3], v[72:75], a[136:139]
	v_mfma_f32_16x16x32_f16 a[120:123], v[16:19], v[52:55], a[120:123]
	v_mfma_f32_16x16x32_f16 a[112:115], v[12:15], v[52:55], a[112:115]
	v_mfma_f32_16x16x32_f16 a[104:107], v[8:11], v[52:55], a[104:107]
	v_mfma_f32_16x16x32_f16 a[92:95], v[0:3], v[52:55], a[92:95]
	v_mfma_f32_16x16x32_f16 a[80:83], v[16:19], v[44:47], a[80:83]
	v_mfma_f32_16x16x32_f16 a[76:79], v[12:15], v[44:47], a[76:79]
	v_mfma_f32_16x16x32_f16 a[72:75], v[8:11], v[44:47], a[72:75]
	v_mfma_f32_16x16x32_f16 a[68:71], v[0:3], v[44:47], a[68:71]
	v_mfma_f32_16x16x32_f16 a[64:67], v[16:19], v[48:51], a[64:67]
	v_mfma_f32_16x16x32_f16 a[60:63], v[12:15], v[48:51], a[60:63]
	v_mfma_f32_16x16x32_f16 a[56:59], v[8:11], v[48:51], a[56:59]
	v_mfma_f32_16x16x32_f16 a[52:55], v[0:3], v[48:51], a[52:55]
	s_waitcnt lgkmcnt(13)
	v_mfma_f32_16x16x32_f16 a[44:47], v[16:19], v[40:43], a[44:47]
	v_mfma_f32_16x16x32_f16 a[40:43], v[12:15], v[40:43], a[40:43]
	v_mfma_f32_16x16x32_f16 a[36:39], v[8:11], v[40:43], a[36:39]
	v_mfma_f32_16x16x32_f16 a[32:35], v[0:3], v[40:43], a[32:35]
	v_mfma_f32_16x16x32_f16 a[28:31], v[16:19], v[4:7], a[28:31]
	v_mfma_f32_16x16x32_f16 a[24:27], v[12:15], v[4:7], a[24:27]
	v_mfma_f32_16x16x32_f16 a[20:23], v[8:11], v[4:7], a[20:23]
	v_mfma_f32_16x16x32_f16 a[16:19], v[0:3], v[4:7], a[16:19]
	s_waitcnt lgkmcnt(12)
	v_mfma_f32_16x16x32_f16 a[12:15], v[16:19], v[32:35], a[12:15]
	v_mfma_f32_16x16x32_f16 a[8:11], v[12:15], v[32:35], a[8:11]
	v_mfma_f32_16x16x32_f16 a[4:7], v[8:11], v[32:35], a[4:7]
	v_mfma_f32_16x16x32_f16 a[0:3], v[0:3], v[32:35], a[0:3]
	v_add_u32_e32 v0, v20, v99
	s_waitcnt vmcnt(7)
	ds_write_b128 v21, v[112:115] offset:36864
	s_waitcnt vmcnt(6)
	ds_write_b128 v21, v[124:127] offset:41472
	s_waitcnt vmcnt(5)
	ds_write_b128 v21, v[128:131] offset:46080
	s_waitcnt vmcnt(4)
	ds_write_b128 v21, v[140:143] offset:50688
	s_waitcnt vmcnt(3)
	ds_write_b128 v21, v[144:147] offset:55296
	s_waitcnt vmcnt(2)
	ds_write_b128 v21, v[156:159] offset:59904
	s_waitcnt vmcnt(1)
	ds_write_b128 v21, v[164:167] offset:64512
	s_waitcnt vmcnt(0)
	ds_write_b128 v0, v[168:171]
	ds_read_b128 v[36:39], v56 offset:64
	ds_read_b128 v[28:31], v56 offset:2368
	ds_read_b128 v[24:27], v56 offset:4672
	ds_read_b128 v[20:23], v56 offset:6976
	ds_read_b128 v[16:19], v56 offset:9280
	ds_read_b128 v[12:15], v56 offset:11584
	ds_read_b128 v[8:11], v56 offset:13888
	ds_read_b128 v[0:3], v56 offset:16192
	ds_read_b128 v[56:59], v106 offset:36928
	ds_read_b128 v[60:63], v106 offset:39232
	ds_read_b128 v[64:67], v106 offset:41536
	ds_read_b128 v[68:71], v106 offset:43840
	s_cmp_gt_u32 s14, 29
	s_cbranch_scc1 .Lgw7_nl
; #define MMA_BLK(afx, bfx, nh_) _Pragma("unroll") for (int mi = 0; mi < 8; ++mi) _Pragma("unroll") for (int ni = 0; ni < 4; ++ni) mfma16_acc(acc[mi][(nh_) * 4 + ni], bfx[ni], afx[mi])
; template <class Epi>
; __device__ __forceinline__ void gemm_run(const GemmArgs g, Epi epi, char* smem) {
;     ...
;       MMA_BLK(afA, bfB, 1);
;       __builtin_amdgcn_sched_barrier(0);
;       if (kt + 2 < nk) {
;         const int ko = (kt + 2) * 64;
; #pragma unroll
;         for (int i = 0; i < 8; ++i) { ra[i] = __builtin_amdgcn_raw_buffer_load_b128(Ars, aoff, i * astep + ko * 2, 0); rb[i] = __builtin_amdgcn_raw_buffer_load_b128(Brs, boff, i * bstep + ko * 2, 0); }
;       }
	s_waitcnt lgkmcnt(14)
	v_mfma_f32_16x16x32_f16 a[252:255], v[172:175], v[76:79], a[252:255]
	v_mfma_f32_16x16x32_f16 a[248:251], v[88:91], v[76:79], a[248:251]
	v_mfma_f32_16x16x32_f16 a[244:247], v[84:87], v[76:79], a[244:247]
	s_add_i32 s87, s7, 0xfff20000
	v_mfma_f32_16x16x32_f16 a[240:243], v[80:83], v[76:79], a[240:243]
	s_mov_b32 s14, s10
	v_mfma_f32_16x16x32_f16 a[236:239], v[172:175], v[72:75], a[236:239]
	s_mov_b32 s15, s11
	v_mfma_f32_16x16x32_f16 a[232:235], v[88:91], v[72:75], a[232:235]
	buffer_load_dwordx4 v[108:111], v92, s[8:11], s87 offen
	v_mfma_f32_16x16x32_f16 a[228:231], v[84:87], v[72:75], a[228:231]
	buffer_load_dwordx4 v[112:115], v92, s[12:15], s87 offen
	v_mfma_f32_16x16x32_f16 a[224:227], v[80:83], v[72:75], a[224:227]
	s_add_i32 s87, s7, 0xfff40000
	v_mfma_f32_16x16x32_f16 a[220:223], v[172:175], v[52:55], a[220:223]
	buffer_load_dwordx4 v[116:119], v92, s[8:11], s87 offen
	v_mfma_f32_16x16x32_f16 a[216:219], v[88:91], v[52:55], a[216:219]
	buffer_load_dwordx4 v[124:127], v92, s[12:15], s87 offen
	v_mfma_f32_16x16x32_f16 a[212:215], v[84:87], v[52:55], a[212:215]
	s_add_i32 s87, s7, 0xfff60000
	v_mfma_f32_16x16x32_f16 a[208:211], v[80:83], v[52:55], a[208:211]
	buffer_load_dwordx4 v[120:123], v92, s[8:11], s87 offen
	v_mfma_f32_16x16x32_f16 a[204:207], v[172:175], v[44:47], a[204:207]
	buffer_load_dwordx4 v[128:131], v92, s[12:15], s87 offen
	v_mfma_f32_16x16x32_f16 a[200:203], v[88:91], v[44:47], a[200:203]
	s_add_i32 s87, s7, 0xfff80000
	v_mfma_f32_16x16x32_f16 a[196:199], v[84:87], v[44:47], a[196:199]
	buffer_load_dwordx4 v[132:135], v92, s[8:11], s87 offen
	v_mfma_f32_16x16x32_f16 a[192:195], v[80:83], v[44:47], a[192:195]
	buffer_load_dwordx4 v[140:143], v92, s[12:15], s87 offen
	v_mfma_f32_16x16x32_f16 a[188:191], v[172:175], v[48:51], a[188:191]
	s_add_i32 s87, s7, 0xfffa0000
	v_mfma_f32_16x16x32_f16 a[184:187], v[88:91], v[48:51], a[184:187]
	buffer_load_dwordx4 v[136:139], v92, s[8:11], s87 offen
	v_mfma_f32_16x16x32_f16 a[180:183], v[84:87], v[48:51], a[180:183]
	buffer_load_dwordx4 v[144:147], v92, s[12:15], s87 offen
	v_mfma_f32_16x16x32_f16 a[176:179], v[80:83], v[48:51], a[176:179]
	s_add_i32 s87, s7, 0xfffc0000
	v_mfma_f32_16x16x32_f16 a[172:175], v[172:175], v[40:43], a[172:175]
	buffer_load_dwordx4 v[148:151], v92, s[8:11], s87 offen
	v_mfma_f32_16x16x32_f16 a[168:171], v[88:91], v[40:43], a[168:171]
	buffer_load_dwordx4 v[156:159], v92, s[12:15], s87 offen
	v_mfma_f32_16x16x32_f16 a[164:167], v[84:87], v[40:43], a[164:167]
	s_add_i32 s87, s7, 0xfffe0000
	v_mfma_f32_16x16x32_f16 a[156:159], v[80:83], v[40:43], a[156:159]
	buffer_load_dwordx4 v[152:155], v92, s[8:11], s87 offen
	v_mfma_f32_16x16x32_f16 a[140:143], v[172:175], v[4:7], a[140:143]
	buffer_load_dwordx4 v[164:167], v92, s[12:15], s87 offen
	v_mfma_f32_16x16x32_f16 a[132:135], v[88:91], v[4:7], a[132:135]
	buffer_load_dwordx4 v[160:163], v92, s[8:11], s7 offen
	v_mfma_f32_16x16x32_f16 a[128:131], v[84:87], v[4:7], a[128:131]
	buffer_load_dwordx4 v[168:171], v92, s[12:15], s7 offen
	v_mfma_f32_16x16x32_f16 a[124:127], v[80:83], v[4:7], a[124:127]
	v_mfma_f32_16x16x32_f16 a[96:99], v[172:175], v[32:35], a[96:99]
	v_mfma_f32_16x16x32_f16 a[88:91], v[88:91], v[32:35], a[88:91]
	v_mfma_f32_16x16x32_f16 a[84:87], v[84:87], v[32:35], a[84:87]
	v_mfma_f32_16x16x32_f16 a[48:51], v[80:83], v[32:35], a[48:51]
	s_branch .LBB0_1007
.Lgw7_nl:
	s_waitcnt lgkmcnt(14)
	v_mfma_f32_16x16x32_f16 a[252:255], v[172:175], v[76:79], a[252:255]
	v_mfma_f32_16x16x32_f16 a[248:251], v[88:91], v[76:79], a[248:251]
	v_mfma_f32_16x16x32_f16 a[244:247], v[84:87], v[76:79], a[244:247]
	v_mfma_f32_16x16x32_f16 a[240:243], v[80:83], v[76:79], a[240:243]
	v_mfma_f32_16x16x32_f16 a[236:239], v[172:175], v[72:75], a[236:239]
	v_mfma_f32_16x16x32_f16 a[232:235], v[88:91], v[72:75], a[232:235]
	v_mfma_f32_16x16x32_f16 a[228:231], v[84:87], v[72:75], a[228:231]
	v_mfma_f32_16x16x32_f16 a[224:227], v[80:83], v[72:75], a[224:227]
	v_mfma_f32_16x16x32_f16 a[220:223], v[172:175], v[52:55], a[220:223]
	v_mfma_f32_16x16x32_f16 a[216:219], v[88:91], v[52:55], a[216:219]
	v_mfma_f32_16x16x32_f16 a[212:215], v[84:87], v[52:55], a[212:215]
	v_mfma_f32_16x16x32_f16 a[208:211], v[80:83], v[52:55], a[208:211]
	v_mfma_f32_16x16x32_f16 a[204:207], v[172:175], v[44:47], a[204:207]
	v_mfma_f32_16x16x32_f16 a[200:203], v[88:91], v[44:47], a[200:203]
	v_mfma_f32_16x16x32_f16 a[196:199], v[84:87], v[44:47], a[196:199]
	v_mfma_f32_16x16x32_f16 a[192:195], v[80:83], v[44:47], a[192:195]
	v_mfma_f32_16x16x32_f16 a[188:191], v[172:175], v[48:51], a[188:191]
	v_mfma_f32_16x16x32_f16 a[184:187], v[88:91], v[48:51], a[184:187]
	v_mfma_f32_16x16x32_f16 a[180:183], v[84:87], v[48:51], a[180:183]
	v_mfma_f32_16x16x32_f16 a[176:179], v[80:83], v[48:51], a[176:179]
	v_mfma_f32_16x16x32_f16 a[172:175], v[172:175], v[40:43], a[172:175]
	v_mfma_f32_16x16x32_f16 a[168:171], v[88:91], v[40:43], a[168:171]
	v_mfma_f32_16x16x32_f16 a[164:167], v[84:87], v[40:43], a[164:167]
	v_mfma_f32_16x16x32_f16 a[156:159], v[80:83], v[40:43], a[156:159]
	v_mfma_f32_16x16x32_f16 a[140:143], v[172:175], v[4:7], a[140:143]
	v_mfma_f32_16x16x32_f16 a[132:135], v[88:91], v[4:7], a[132:135]
	v_mfma_f32_16x16x32_f16 a[128:131], v[84:87], v[4:7], a[128:131]
	v_mfma_f32_16x16x32_f16 a[124:127], v[80:83], v[4:7], a[124:127]
	v_mfma_f32_16x16x32_f16 a[96:99], v[172:175], v[32:35], a[96:99]
	v_mfma_f32_16x16x32_f16 a[88:91], v[88:91], v[32:35], a[88:91]
	v_mfma_f32_16x16x32_f16 a[84:87], v[84:87], v[32:35], a[84:87]
	v_mfma_f32_16x16x32_f16 a[48:51], v[80:83], v[32:35], a[48:51]
	s_branch .LBB0_1007

; #define LD_AF(dst, ks_) _Pragma("unroll") for (int i = 0; i < 8; ++i) dst[i] = *(const h8*)(sA + i * 16 * G_LD + (ks_) * 32)
; #define LD_BF(dst, ks_, nh_) _Pragma("unroll") for (int i = 0; i < 4; ++i) dst[i] = *(const h8*)(sB + ((nh_) * 4 + i) * 16 * G_LD + (ks_) * 32)
; #define MMA_BLK(afx, bfx, nh_) _Pragma("unroll") for (int mi = 0; mi < 8; ++mi) _Pragma("unroll") for (int ni = 0; ni < 4; ++ni) mfma16_acc(acc[mi][(nh_) * 4 + ni], bfx[ni], afx[mi])
; template <class Epi>
; __device__ __forceinline__ void gemm_run(const GemmArgs g, Epi epi, char* smem) {
;     ...
;       const hf* sA = sbase + (kt & 1) * G_STAGE + (wm * 128 + fr) * G_LD + fqs;
;       const hf* sB = sbase + (kt & 1) * G_STAGE + (256 + wn * 128 + fr) * G_LD + fqs;
;       hf* st = sbase + ((kt + 1) & 1) * G_STAGE;
;       h8 afA[8], afB[8], bfA[4], bfB[4];
;     ...
;       LD_AF(afA, 0); LD_BF(bfA, 0, 0);
;       if (kt + 1 < nk) {
; #pragma unroll
;         for (int i = 0; i < 8; ++i) *(u4*)(st + (lr + 32 * i) * G_LD + lcw) = ra[i];
;       }
;       __builtin_amdgcn_sched_barrier(0);
;       LD_BF(bfB, 0, 1);
;       MMA_BLK(afA, bfA, 0);
;       __builtin_amdgcn_sched_barrier(0);
;       if (kt + 1 < nk) {
; #pragma unroll
;         for (int i = 0; i < 8; ++i) *(u4*)(st + (256 + lr + 32 * i) * G_LD + lcw) = rb[i];
;       }
;       LD_AF(afB, 1); LD_BF(bfA, 1, 0);
.LBB0_1059:
	s_bitcmp1_b32 s87, 0
	s_cselect_b32 s15, 0x12000, 0
	s_add_i32 s15, s15, 16
	v_add3_u32 v56, s15, v133, v141
	v_add3_u32 v92, s15, v134, v141
	ds_read_b128 v[4:7], v56 offset:13824
	ds_read_b128 v[16:19], v92 offset:36864
	ds_read_b128 v[12:15], v92 offset:39168
	ds_read_b128 v[8:11], v92 offset:41472
	ds_read_b128 v[0:3], v92 offset:43776
	ds_read_b128 v[76:79], v56
	ds_read_b128 v[72:75], v56 offset:2304
	ds_read_b128 v[52:55], v56 offset:4608
	ds_read_b128 v[44:47], v56 offset:6912
	ds_read_b128 v[48:51], v56 offset:9216
	ds_read_b128 v[40:43], v56 offset:11520
	ds_read_b128 v[32:35], v56 offset:16128
	s_mov_b32 s14, s87
	s_add_i32 s87, s87, 1
	s_bitcmp1_b32 s87, 0
	s_cselect_b32 s15, 0x12000, 0
	v_add_u32_e32 v20, s15, v131
	v_add_u32_e32 v21, v20, v136
	s_waitcnt vmcnt(15)
	ds_write_b128 v21, v[94:97]
	s_waitcnt vmcnt(13)
	ds_write_b128 v21, v[102:105] offset:4608
	s_waitcnt vmcnt(11)
	ds_write_b128 v21, v[106:109] offset:9216
	s_waitcnt vmcnt(9)
	ds_write_b128 v21, v[118:121] offset:13824
	s_waitcnt vmcnt(7)
	ds_write_b128 v21, v[122:125] offset:18432
	s_waitcnt vmcnt(5)
	ds_write_b128 v21, v[146:149] offset:23040
	s_waitcnt vmcnt(3)
	ds_write_b128 v21, v[150:153] offset:27648
	s_waitcnt vmcnt(1)
	ds_write_b128 v21, v[158:161] offset:32256
	ds_read_b128 v[170:173], v92 offset:46080
	ds_read_b128 v[88:91], v92 offset:48384
	ds_read_b128 v[84:87], v92 offset:50688
	ds_read_b128 v[80:83], v92 offset:52992
	s_waitcnt lgkmcnt(14)
	v_mfma_f32_16x16x32_f16 a[220:223], v[16:19], v[76:79], a[220:223]
	v_mfma_f32_16x16x32_f16 a[216:219], v[12:15], v[76:79], a[216:219]
	v_mfma_f32_16x16x32_f16 a[212:215], v[8:11], v[76:79], a[212:215]
	v_mfma_f32_16x16x32_f16 a[208:211], v[0:3], v[76:79], a[208:211]
	v_mfma_f32_16x16x32_f16 a[200:203], v[16:19], v[72:75], a[200:203]
	v_mfma_f32_16x16x32_f16 a[196:199], v[12:15], v[72:75], a[196:199]
	v_mfma_f32_16x16x32_f16 a[188:191], v[8:11], v[72:75], a[188:191]
	v_mfma_f32_16x16x32_f16 a[180:183], v[0:3], v[72:75], a[180:183]
	v_mfma_f32_16x16x32_f16 a[172:175], v[16:19], v[52:55], a[172:175]
	v_mfma_f32_16x16x32_f16 a[164:167], v[12:15], v[52:55], a[164:167]
	v_mfma_f32_16x16x32_f16 a[156:159], v[8:11], v[52:55], a[156:159]
	v_mfma_f32_16x16x32_f16 a[148:151], v[0:3], v[52:55], a[148:151]
	v_mfma_f32_16x16x32_f16 a[140:143], v[16:19], v[44:47], a[140:143]
	v_mfma_f32_16x16x32_f16 a[132:135], v[12:15], v[44:47], a[132:135]
	v_mfma_f32_16x16x32_f16 a[124:127], v[8:11], v[44:47], a[124:127]
	v_mfma_f32_16x16x32_f16 a[116:119], v[0:3], v[44:47], a[116:119]
	v_mfma_f32_16x16x32_f16 a[108:111], v[16:19], v[48:51], a[108:111]
	v_mfma_f32_16x16x32_f16 a[100:103], v[12:15], v[48:51], a[100:103]
	v_mfma_f32_16x16x32_f16 a[92:95], v[8:11], v[48:51], a[92:95]
	v_mfma_f32_16x16x32_f16 a[84:87], v[0:3], v[48:51], a[84:87]
	s_waitcnt lgkmcnt(13)
	v_mfma_f32_16x16x32_f16 a[76:79], v[16:19], v[40:43], a[76:79]
	v_mfma_f32_16x16x32_f16 a[68:71], v[12:15], v[40:43], a[68:71]
	v_mfma_f32_16x16x32_f16 a[60:63], v[8:11], v[40:43], a[60:63]
	v_mfma_f32_16x16x32_f16 a[52:55], v[0:3], v[40:43], a[52:55]
	v_mfma_f32_16x16x32_f16 a[44:47], v[16:19], v[4:7], a[44:47]
	v_mfma_f32_16x16x32_f16 a[36:39], v[12:15], v[4:7], a[36:39]
	v_mfma_f32_16x16x32_f16 a[28:31], v[8:11], v[4:7], a[28:31]
	v_mfma_f32_16x16x32_f16 a[20:23], v[0:3], v[4:7], a[20:23]
	s_waitcnt lgkmcnt(12)
	v_mfma_f32_16x16x32_f16 a[12:15], v[16:19], v[32:35], a[12:15]
	v_mfma_f32_16x16x32_f16 a[8:11], v[12:15], v[32:35], a[8:11]
	v_mfma_f32_16x16x32_f16 a[4:7], v[8:11], v[32:35], a[4:7]
	v_mfma_f32_16x16x32_f16 a[0:3], v[0:3], v[32:35], a[0:3]
	v_add_u32_e32 v0, v20, v137
	s_waitcnt vmcnt(7)
	ds_write_b128 v21, v[98:101] offset:36864
	s_waitcnt vmcnt(6)
	ds_write_b128 v21, v[110:113] offset:41472
	s_waitcnt vmcnt(5)
	ds_write_b128 v21, v[114:117] offset:46080
	s_waitcnt vmcnt(4)
	ds_write_b128 v21, v[126:129] offset:50688
	s_waitcnt vmcnt(3)
	ds_write_b128 v21, v[142:145] offset:55296
	s_waitcnt vmcnt(2)
	ds_write_b128 v21, v[154:157] offset:59904
	s_waitcnt vmcnt(1)
	ds_write_b128 v21, v[162:165] offset:64512
	s_waitcnt vmcnt(0)
	ds_write_b128 v0, v[166:169]
	ds_read_b128 v[36:39], v56 offset:64
	ds_read_b128 v[28:31], v56 offset:2368
	ds_read_b128 v[24:27], v56 offset:4672
	ds_read_b128 v[20:23], v56 offset:6976
	ds_read_b128 v[16:19], v56 offset:9280
	ds_read_b128 v[12:15], v56 offset:11584
	ds_read_b128 v[8:11], v56 offset:13888
	ds_read_b128 v[0:3], v56 offset:16192
	ds_read_b128 v[56:59], v92 offset:36928
	ds_read_b128 v[60:63], v92 offset:39232
	ds_read_b128 v[64:67], v92 offset:41536
	ds_read_b128 v[68:71], v92 offset:43840
	s_cmpk_gt_u32 s14, 0x55
	s_cbranch_scc1 .Lgw8_nl
; #define MMA_BLK(afx, bfx, nh_) _Pragma("unroll") for (int mi = 0; mi < 8; ++mi) _Pragma("unroll") for (int ni = 0; ni < 4; ++ni) mfma16_acc(acc[mi][(nh_) * 4 + ni], bfx[ni], afx[mi])
; template <class Epi>
; __device__ __forceinline__ void gemm_run(const GemmArgs g, Epi epi, char* smem) {
;     ...
;       MMA_BLK(afA, bfB, 1);
;       __builtin_amdgcn_sched_barrier(0);
;       if (kt + 2 < nk) {
;         const int ko = (kt + 2) * 64;
; #pragma unroll
;         for (int i = 0; i < 8; ++i) { ra[i] = __builtin_amdgcn_raw_buffer_load_b128(Ars, aoff, i * astep + ko * 2, 0); rb[i] = __builtin_amdgcn_raw_buffer_load_b128(Brs, boff, i * bstep + ko * 2, 0); }
;       }
	s_waitcnt lgkmcnt(14)
	v_mfma_f32_16x16x32_f16 a[240:243], v[170:173], v[76:79], a[240:243]
	v_mfma_f32_16x16x32_f16 a[252:255], v[88:91], v[76:79], a[252:255]
	v_mfma_f32_16x16x32_f16 a[248:251], v[84:87], v[76:79], a[248:251]
	s_add_i32 s88, s86, 0xffd98000
	v_mfma_f32_16x16x32_f16 a[244:247], v[80:83], v[76:79], a[244:247]
	s_mov_b32 s14, s10
	v_mfma_f32_16x16x32_f16 a[236:239], v[170:173], v[72:75], a[236:239]
	s_mov_b32 s15, s11
	v_mfma_f32_16x16x32_f16 a[232:235], v[88:91], v[72:75], a[232:235]
	buffer_load_dwordx4 v[94:97], v130, s[8:11], s88 offen
	v_mfma_f32_16x16x32_f16 a[228:231], v[84:87], v[72:75], a[228:231]
	buffer_load_dwordx4 v[98:101], v130, s[12:15], s88 offen
	v_mfma_f32_16x16x32_f16 a[224:227], v[80:83], v[72:75], a[224:227]
	s_add_i32 s88, s86, 0xffdf0000
	v_mfma_f32_16x16x32_f16 a[204:207], v[170:173], v[52:55], a[204:207]
	buffer_load_dwordx4 v[102:105], v130, s[8:11], s88 offen
	v_mfma_f32_16x16x32_f16 a[192:195], v[88:91], v[52:55], a[192:195]
	buffer_load_dwordx4 v[110:113], v130, s[12:15], s88 offen
	v_mfma_f32_16x16x32_f16 a[184:187], v[84:87], v[52:55], a[184:187]
	s_add_i32 s88, s86, 0xffe48000
	v_mfma_f32_16x16x32_f16 a[176:179], v[80:83], v[52:55], a[176:179]
	buffer_load_dwordx4 v[106:109], v130, s[8:11], s88 offen
	v_mfma_f32_16x16x32_f16 a[168:171], v[170:173], v[44:47], a[168:171]
	buffer_load_dwordx4 v[114:117], v130, s[12:15], s88 offen
	v_mfma_f32_16x16x32_f16 a[160:163], v[88:91], v[44:47], a[160:163]
	s_add_i32 s88, s86, 0xffea0000
	v_mfma_f32_16x16x32_f16 a[152:155], v[84:87], v[44:47], a[152:155]
	buffer_load_dwordx4 v[118:121], v130, s[8:11], s88 offen
	v_mfma_f32_16x16x32_f16 a[144:147], v[80:83], v[44:47], a[144:147]
	buffer_load_dwordx4 v[126:129], v130, s[12:15], s88 offen
	v_mfma_f32_16x16x32_f16 a[136:139], v[170:173], v[48:51], a[136:139]
	s_add_i32 s88, s86, 0xffef8000
	v_mfma_f32_16x16x32_f16 a[128:131], v[88:91], v[48:51], a[128:131]
	buffer_load_dwordx4 v[122:125], v130, s[8:11], s88 offen
	v_mfma_f32_16x16x32_f16 a[120:123], v[84:87], v[48:51], a[120:123]
	buffer_load_dwordx4 v[142:145], v130, s[12:15], s88 offen
	v_mfma_f32_16x16x32_f16 a[112:115], v[80:83], v[48:51], a[112:115]
	s_add_i32 s88, s86, 0xfff50000
	v_mfma_f32_16x16x32_f16 a[104:107], v[170:173], v[40:43], a[104:107]
	buffer_load_dwordx4 v[146:149], v130, s[8:11], s88 offen
	v_mfma_f32_16x16x32_f16 a[96:99], v[88:91], v[40:43], a[96:99]
	buffer_load_dwordx4 v[154:157], v130, s[12:15], s88 offen
	v_mfma_f32_16x16x32_f16 a[88:91], v[84:87], v[40:43], a[88:91]
	s_add_i32 s88, s86, 0xfffa8000
	v_mfma_f32_16x16x32_f16 a[80:83], v[80:83], v[40:43], a[80:83]
	buffer_load_dwordx4 v[150:153], v130, s[8:11], s88 offen
	v_mfma_f32_16x16x32_f16 a[72:75], v[170:173], v[4:7], a[72:75]
	buffer_load_dwordx4 v[162:165], v130, s[12:15], s88 offen
	v_mfma_f32_16x16x32_f16 a[64:67], v[88:91], v[4:7], a[64:67]
	buffer_load_dwordx4 v[158:161], v130, s[8:11], s86 offen
	v_mfma_f32_16x16x32_f16 a[56:59], v[84:87], v[4:7], a[56:59]
	buffer_load_dwordx4 v[166:169], v130, s[12:15], s86 offen
	v_mfma_f32_16x16x32_f16 a[48:51], v[80:83], v[4:7], a[48:51]
	v_mfma_f32_16x16x32_f16 a[40:43], v[170:173], v[32:35], a[40:43]
	v_mfma_f32_16x16x32_f16 a[32:35], v[88:91], v[32:35], a[32:35]
	v_mfma_f32_16x16x32_f16 a[24:27], v[84:87], v[32:35], a[24:27]
	v_mfma_f32_16x16x32_f16 a[16:19], v[80:83], v[32:35], a[16:19]
	s_branch .LBB0_1058
.Lgw8_nl:
	s_waitcnt lgkmcnt(14)
	v_mfma_f32_16x16x32_f16 a[240:243], v[170:173], v[76:79], a[240:243]
	v_mfma_f32_16x16x32_f16 a[252:255], v[88:91], v[76:79], a[252:255]
	v_mfma_f32_16x16x32_f16 a[248:251], v[84:87], v[76:79], a[248:251]
	v_mfma_f32_16x16x32_f16 a[244:247], v[80:83], v[76:79], a[244:247]
	v_mfma_f32_16x16x32_f16 a[236:239], v[170:173], v[72:75], a[236:239]
	v_mfma_f32_16x16x32_f16 a[232:235], v[88:91], v[72:75], a[232:235]
	v_mfma_f32_16x16x32_f16 a[228:231], v[84:87], v[72:75], a[228:231]
	v_mfma_f32_16x16x32_f16 a[224:227], v[80:83], v[72:75], a[224:227]
	v_mfma_f32_16x16x32_f16 a[204:207], v[170:173], v[52:55], a[204:207]
	v_mfma_f32_16x16x32_f16 a[192:195], v[88:91], v[52:55], a[192:195]
	v_mfma_f32_16x16x32_f16 a[184:187], v[84:87], v[52:55], a[184:187]
	v_mfma_f32_16x16x32_f16 a[176:179], v[80:83], v[52:55], a[176:179]
	v_mfma_f32_16x16x32_f16 a[168:171], v[170:173], v[44:47], a[168:171]
	v_mfma_f32_16x16x32_f16 a[160:163], v[88:91], v[44:47], a[160:163]
	v_mfma_f32_16x16x32_f16 a[152:155], v[84:87], v[44:47], a[152:155]
	v_mfma_f32_16x16x32_f16 a[144:147], v[80:83], v[44:47], a[144:147]
	v_mfma_f32_16x16x32_f16 a[136:139], v[170:173], v[48:51], a[136:139]
	v_mfma_f32_16x16x32_f16 a[128:131], v[88:91], v[48:51], a[128:131]
	v_mfma_f32_16x16x32_f16 a[120:123], v[84:87], v[48:51], a[120:123]
	v_mfma_f32_16x16x32_f16 a[112:115], v[80:83], v[48:51], a[112:115]
	v_mfma_f32_16x16x32_f16 a[104:107], v[170:173], v[40:43], a[104:107]
	v_mfma_f32_16x16x32_f16 a[96:99], v[88:91], v[40:43], a[96:99]
	v_mfma_f32_16x16x32_f16 a[88:91], v[84:87], v[40:43], a[88:91]
	v_mfma_f32_16x16x32_f16 a[80:83], v[80:83], v[40:43], a[80:83]
	v_mfma_f32_16x16x32_f16 a[72:75], v[170:173], v[4:7], a[72:75]
	v_mfma_f32_16x16x32_f16 a[64:67], v[88:91], v[4:7], a[64:67]
	v_mfma_f32_16x16x32_f16 a[56:59], v[84:87], v[4:7], a[56:59]
	v_mfma_f32_16x16x32_f16 a[48:51], v[80:83], v[4:7], a[48:51]
	v_mfma_f32_16x16x32_f16 a[40:43], v[170:173], v[32:35], a[40:43]
	v_mfma_f32_16x16x32_f16 a[32:35], v[88:91], v[32:35], a[32:35]
	v_mfma_f32_16x16x32_f16 a[24:27], v[84:87], v[32:35], a[24:27]
	v_mfma_f32_16x16x32_f16 a[16:19], v[80:83], v[32:35], a[16:19]
	s_branch .LBB0_1058

; #define LD_AF(dst, ks_) _Pragma("unroll") for (int i = 0; i < 8; ++i) dst[i] = *(const h8*)(sA + i * 16 * G_LD + (ks_) * 32)
; #define LD_BF(dst, ks_, nh_) _Pragma("unroll") for (int i = 0; i < 4; ++i) dst[i] = *(const h8*)(sB + ((nh_) * 4 + i) * 16 * G_LD + (ks_) * 32)
; #define MMA_BLK(afx, bfx, nh_) _Pragma("unroll") for (int mi = 0; mi < 8; ++mi) _Pragma("unroll") for (int ni = 0; ni < 4; ++ni) mfma16_acc(acc[mi][(nh_) * 4 + ni], bfx[ni], afx[mi])
; template <class Epi>
; __device__ __forceinline__ void gemm_run(const GemmArgs g, Epi epi, char* smem) {
;     ...
;       const hf* sA = sbase + (kt & 1) * G_STAGE + (wm * 128 + fr) * G_LD + fqs;
;       const hf* sB = sbase + (kt & 1) * G_STAGE + (256 + wn * 128 + fr) * G_LD + fqs;
;       hf* st = sbase + ((kt + 1) & 1) * G_STAGE;
;       h8 afA[8], afB[8], bfA[4], bfB[4];
;     ...
;       LD_AF(afA, 0); LD_BF(bfA, 0, 0);
;       if (kt + 1 < nk) {
; #pragma unroll
;         for (int i = 0; i < 8; ++i) *(u4*)(st + (lr + 32 * i) * G_LD + lcw) = ra[i];
;       }
;       __builtin_amdgcn_sched_barrier(0);
;       LD_BF(bfB, 0, 1);
;       MMA_BLK(afA, bfA, 0);
;       __builtin_amdgcn_sched_barrier(0);
;       if (kt + 1 < nk) {
; #pragma unroll
;         for (int i = 0; i < 8; ++i) *(u4*)(st + (256 + lr + 32 * i) * G_LD + lcw) = rb[i];
;       }
;       LD_AF(afB, 1); LD_BF(bfA, 1, 0);
.LBB0_1066:
	s_bitcmp1_b32 s23, 0
	s_cselect_b32 s15, 0x12000, 0
	s_add_i32 s15, s15, 16
	v_add3_u32 v56, s15, v94, v105
	v_add3_u32 v106, s15, v96, v105
	ds_read_b128 v[4:7], v56 offset:13824
	ds_read_b128 v[16:19], v106 offset:36864
	ds_read_b128 v[12:15], v106 offset:39168
	ds_read_b128 v[8:11], v106 offset:41472
	ds_read_b128 v[0:3], v106 offset:43776
	ds_read_b128 v[76:79], v56
	ds_read_b128 v[72:75], v56 offset:2304
	ds_read_b128 v[52:55], v56 offset:4608
	ds_read_b128 v[44:47], v56 offset:6912
	ds_read_b128 v[48:51], v56 offset:9216
	ds_read_b128 v[40:43], v56 offset:11520
	ds_read_b128 v[32:35], v56 offset:16128
	s_mov_b32 s14, s23
	s_add_i32 s23, s23, 1
	s_bitcmp1_b32 s23, 0
	s_cselect_b32 s15, 0x12000, 0
	v_add_u32_e32 v20, s15, v93
	v_add_u32_e32 v21, v20, v98
	s_waitcnt vmcnt(15)
	ds_write_b128 v21, v[108:111]
	s_waitcnt vmcnt(13)
	ds_write_b128 v21, v[116:119] offset:4608
	s_waitcnt vmcnt(11)
	ds_write_b128 v21, v[120:123] offset:9216
	s_waitcnt vmcnt(9)
	ds_write_b128 v21, v[132:135] offset:13824
	s_waitcnt vmcnt(7)
	ds_write_b128 v21, v[136:139] offset:18432
	s_waitcnt vmcnt(5)
	ds_write_b128 v21, v[148:151] offset:23040
	s_waitcnt vmcnt(3)
	ds_write_b128 v21, v[152:155] offset:27648
	s_waitcnt vmcnt(1)
	ds_write_b128 v21, v[160:163] offset:32256
	ds_read_b128 v[172:175], v106 offset:46080
	ds_read_b128 v[88:91], v106 offset:48384
	ds_read_b128 v[84:87], v106 offset:50688
	ds_read_b128 v[80:83], v106 offset:52992
	s_waitcnt lgkmcnt(14)
	v_mfma_f32_16x16x32_f16 a[116:119], v[16:19], v[76:79], a[116:119]
	v_mfma_f32_16x16x32_f16 a[108:111], v[12:15], v[76:79], a[108:111]
	v_mfma_f32_16x16x32_f16 a[100:103], v[8:11], v[76:79], a[100:103]
	v_mfma_f32_16x16x32_f16 a[160:163], v[0:3], v[76:79], a[160:163]
	v_mfma_f32_16x16x32_f16 a[152:155], v[16:19], v[72:75], a[152:155]
	v_mfma_f32_16x16x32_f16 a[148:151], v[12:15], v[72:75], a[148:151]
	v_mfma_f32_16x16x32_f16 a[144:147], v[8:11], v[72:75], a[144:147]
	v_mfma_f32_16x16x32_f16 a[136:139], v[0:3], v[72:75], a[136:139]
	v_mfma_f32_16x16x32_f16 a[120:123], v[16:19], v[52:55], a[120:123]
	v_mfma_f32_16x16x32_f16 a[112:115], v[12:15], v[52:55], a[112:115]
	v_mfma_f32_16x16x32_f16 a[104:107], v[8:11], v[52:55], a[104:107]
	v_mfma_f32_16x16x32_f16 a[92:95], v[0:3], v[52:55], a[92:95]
	v_mfma_f32_16x16x32_f16 a[80:83], v[16:19], v[44:47], a[80:83]
	v_mfma_f32_16x16x32_f16 a[76:79], v[12:15], v[44:47], a[76:79]
	v_mfma_f32_16x16x32_f16 a[72:75], v[8:11], v[44:47], a[72:75]
	v_mfma_f32_16x16x32_f16 a[68:71], v[0:3], v[44:47], a[68:71]
	v_mfma_f32_16x16x32_f16 a[64:67], v[16:19], v[48:51], a[64:67]
	v_mfma_f32_16x16x32_f16 a[60:63], v[12:15], v[48:51], a[60:63]
	v_mfma_f32_16x16x32_f16 a[56:59], v[8:11], v[48:51], a[56:59]
	v_mfma_f32_16x16x32_f16 a[52:55], v[0:3], v[48:51], a[52:55]
	s_waitcnt lgkmcnt(13)
	v_mfma_f32_16x16x32_f16 a[44:47], v[16:19], v[40:43], a[44:47]
	v_mfma_f32_16x16x32_f16 a[40:43], v[12:15], v[40:43], a[40:43]
	v_mfma_f32_16x16x32_f16 a[36:39], v[8:11], v[40:43], a[36:39]
	v_mfma_f32_16x16x32_f16 a[32:35], v[0:3], v[40:43], a[32:35]
	v_mfma_f32_16x16x32_f16 a[28:31], v[16:19], v[4:7], a[28:31]
	v_mfma_f32_16x16x32_f16 a[24:27], v[12:15], v[4:7], a[24:27]
	v_mfma_f32_16x16x32_f16 a[20:23], v[8:11], v[4:7], a[20:23]
	v_mfma_f32_16x16x32_f16 a[16:19], v[0:3], v[4:7], a[16:19]
	s_waitcnt lgkmcnt(12)
	v_mfma_f32_16x16x32_f16 a[12:15], v[16:19], v[32:35], a[12:15]
	v_mfma_f32_16x16x32_f16 a[8:11], v[12:15], v[32:35], a[8:11]
	v_mfma_f32_16x16x32_f16 a[4:7], v[8:11], v[32:35], a[4:7]
	v_mfma_f32_16x16x32_f16 a[0:3], v[0:3], v[32:35], a[0:3]
	v_add_u32_e32 v0, v20, v99
	s_waitcnt vmcnt(7)
	ds_write_b128 v21, v[112:115] offset:36864
	s_waitcnt vmcnt(6)
	ds_write_b128 v21, v[124:127] offset:41472
	s_waitcnt vmcnt(5)
	ds_write_b128 v21, v[128:131] offset:46080
	s_waitcnt vmcnt(4)
	ds_write_b128 v21, v[140:143] offset:50688
	s_waitcnt vmcnt(3)
	ds_write_b128 v21, v[144:147] offset:55296
	s_waitcnt vmcnt(2)
	ds_write_b128 v21, v[156:159] offset:59904
	s_waitcnt vmcnt(1)
	ds_write_b128 v21, v[164:167] offset:64512
	s_waitcnt vmcnt(0)
	ds_write_b128 v0, v[168:171]
	ds_read_b128 v[36:39], v56 offset:64
	ds_read_b128 v[28:31], v56 offset:2368
	ds_read_b128 v[24:27], v56 offset:4672
	ds_read_b128 v[20:23], v56 offset:6976
	ds_read_b128 v[16:19], v56 offset:9280
	ds_read_b128 v[12:15], v56 offset:11584
	ds_read_b128 v[8:11], v56 offset:13888
	ds_read_b128 v[0:3], v56 offset:16192
	ds_read_b128 v[56:59], v106 offset:36928
	ds_read_b128 v[60:63], v106 offset:39232
	ds_read_b128 v[64:67], v106 offset:41536
	ds_read_b128 v[68:71], v106 offset:43840
	s_cmp_gt_u32 s14, 29
	s_cbranch_scc1 .Lgw9_nl
; #define MMA_BLK(afx, bfx, nh_) _Pragma("unroll") for (int mi = 0; mi < 8; ++mi) _Pragma("unroll") for (int ni = 0; ni < 4; ++ni) mfma16_acc(acc[mi][(nh_) * 4 + ni], bfx[ni], afx[mi])
; template <class Epi>
; __device__ __forceinline__ void gemm_run(const GemmArgs g, Epi epi, char* smem) {
;     ...
;       MMA_BLK(afA, bfB, 1);
;       __builtin_amdgcn_sched_barrier(0);
;       if (kt + 2 < nk) {
;         const int ko = (kt + 2) * 64;
; #pragma unroll
;         for (int i = 0; i < 8; ++i) { ra[i] = __builtin_amdgcn_raw_buffer_load_b128(Ars, aoff, i * astep + ko * 2, 0); rb[i] = __builtin_amdgcn_raw_buffer_load_b128(Brs, boff, i * bstep + ko * 2, 0); }
;       }
	s_waitcnt lgkmcnt(14)
	v_mfma_f32_16x16x32_f16 a[252:255], v[172:175], v[76:79], a[252:255]
	v_mfma_f32_16x16x32_f16 a[248:251], v[88:91], v[76:79], a[248:251]
	v_mfma_f32_16x16x32_f16 a[244:247], v[84:87], v[76:79], a[244:247]
	s_add_i32 s89, s21, 0xfff20000
	v_mfma_f32_16x16x32_f16 a[240:243], v[80:83], v[76:79], a[240:243]
	s_mov_b32 s14, s10
	v_mfma_f32_16x16x32_f16 a[236:239], v[172:175], v[72:75], a[236:239]
	s_mov_b32 s15, s11
	v_mfma_f32_16x16x32_f16 a[232:235], v[88:91], v[72:75], a[232:235]
	buffer_load_dwordx4 v[108:111], v92, s[8:11], s89 offen
	v_mfma_f32_16x16x32_f16 a[228:231], v[84:87], v[72:75], a[228:231]
	buffer_load_dwordx4 v[112:115], v92, s[12:15], s89 offen
	v_mfma_f32_16x16x32_f16 a[224:227], v[80:83], v[72:75], a[224:227]
	s_add_i32 s89, s21, 0xfff40000
	v_mfma_f32_16x16x32_f16 a[220:223], v[172:175], v[52:55], a[220:223]
	buffer_load_dwordx4 v[116:119], v92, s[8:11], s89 offen
	v_mfma_f32_16x16x32_f16 a[216:219], v[88:91], v[52:55], a[216:219]
	buffer_load_dwordx4 v[124:127], v92, s[12:15], s89 offen
	v_mfma_f32_16x16x32_f16 a[212:215], v[84:87], v[52:55], a[212:215]
	s_add_i32 s89, s21, 0xfff60000
	v_mfma_f32_16x16x32_f16 a[208:211], v[80:83], v[52:55], a[208:211]
	buffer_load_dwordx4 v[120:123], v92, s[8:11], s89 offen
	v_mfma_f32_16x16x32_f16 a[204:207], v[172:175], v[44:47], a[204:207]
	buffer_load_dwordx4 v[128:131], v92, s[12:15], s89 offen
	v_mfma_f32_16x16x32_f16 a[200:203], v[88:91], v[44:47], a[200:203]
	s_add_i32 s89, s21, 0xfff80000
	v_mfma_f32_16x16x32_f16 a[196:199], v[84:87], v[44:47], a[196:199]
	buffer_load_dwordx4 v[132:135], v92, s[8:11], s89 offen
	v_mfma_f32_16x16x32_f16 a[192:195], v[80:83], v[44:47], a[192:195]
	buffer_load_dwordx4 v[140:143], v92, s[12:15], s89 offen
	v_mfma_f32_16x16x32_f16 a[188:191], v[172:175], v[48:51], a[188:191]
	s_add_i32 s89, s21, 0xfffa0000
	v_mfma_f32_16x16x32_f16 a[184:187], v[88:91], v[48:51], a[184:187]
	buffer_load_dwordx4 v[136:139], v92, s[8:11], s89 offen
	v_mfma_f32_16x16x32_f16 a[180:183], v[84:87], v[48:51], a[180:183]
	buffer_load_dwordx4 v[144:147], v92, s[12:15], s89 offen
	v_mfma_f32_16x16x32_f16 a[176:179], v[80:83], v[48:51], a[176:179]
	s_add_i32 s89, s21, 0xfffc0000
	v_mfma_f32_16x16x32_f16 a[172:175], v[172:175], v[40:43], a[172:175]
	buffer_load_dwordx4 v[148:151], v92, s[8:11], s89 offen
	v_mfma_f32_16x16x32_f16 a[168:171], v[88:91], v[40:43], a[168:171]
	buffer_load_dwordx4 v[156:159], v92, s[12:15], s89 offen
	v_mfma_f32_16x16x32_f16 a[164:167], v[84:87], v[40:43], a[164:167]
	s_add_i32 s89, s21, 0xfffe0000
	v_mfma_f32_16x16x32_f16 a[156:159], v[80:83], v[40:43], a[156:159]
	buffer_load_dwordx4 v[152:155], v92, s[8:11], s89 offen
	v_mfma_f32_16x16x32_f16 a[140:143], v[172:175], v[4:7], a[140:143]
	buffer_load_dwordx4 v[164:167], v92, s[12:15], s89 offen
	v_mfma_f32_16x16x32_f16 a[132:135], v[88:91], v[4:7], a[132:135]
	buffer_load_dwordx4 v[160:163], v92, s[8:11], s21 offen
	v_mfma_f32_16x16x32_f16 a[128:131], v[84:87], v[4:7], a[128:131]
	buffer_load_dwordx4 v[168:171], v92, s[12:15], s21 offen
	v_mfma_f32_16x16x32_f16 a[124:127], v[80:83], v[4:7], a[124:127]
	v_mfma_f32_16x16x32_f16 a[96:99], v[172:175], v[32:35], a[96:99]
	v_mfma_f32_16x16x32_f16 a[88:91], v[88:91], v[32:35], a[88:91]
	v_mfma_f32_16x16x32_f16 a[84:87], v[84:87], v[32:35], a[84:87]
	v_mfma_f32_16x16x32_f16 a[48:51], v[80:83], v[32:35], a[48:51]
	s_branch .LBB0_1065

; #define LD_AF(dst, ks_) _Pragma("unroll") for (int i = 0; i < 8; ++i) dst[i] = *(const h8*)(sA + i * 16 * G_LD + (ks_) * 32)
; #define LD_BF(dst, ks_, nh_) _Pragma("unroll") for (int i = 0; i < 4; ++i) dst[i] = *(const h8*)(sB + ((nh_) * 4 + i) * 16 * G_LD + (ks_) * 32)
; #define MMA_BLK(afx, bfx, nh_) _Pragma("unroll") for (int mi = 0; mi < 8; ++mi) _Pragma("unroll") for (int ni = 0; ni < 4; ++ni) mfma16_acc(acc[mi][(nh_) * 4 + ni], bfx[ni], afx[mi])
; template <class Epi>
; __device__ __forceinline__ void gemm_run(const GemmArgs g, Epi epi, char* smem) {
;     ...
;       const hf* sA = sbase + (kt & 1) * G_STAGE + (wm * 128 + fr) * G_LD + fqs;
;       const hf* sB = sbase + (kt & 1) * G_STAGE + (256 + wn * 128 + fr) * G_LD + fqs;
;       hf* st = sbase + ((kt + 1) & 1) * G_STAGE;
;       h8 afA[8], afB[8], bfA[4], bfB[4];
;     ...
;       LD_AF(afA, 0); LD_BF(bfA, 0, 0);
;       if (kt + 1 < nk) {
; #pragma unroll
;         for (int i = 0; i < 8; ++i) *(u4*)(st + (lr + 32 * i) * G_LD + lcw) = ra[i];
;       }
;       __builtin_amdgcn_sched_barrier(0);
;       LD_BF(bfB, 0, 1);
;       MMA_BLK(afA, bfA, 0);
;       __builtin_amdgcn_sched_barrier(0);
;       if (kt + 1 < nk) {
; #pragma unroll
;         for (int i = 0; i < 8; ++i) *(u4*)(st + (256 + lr + 32 * i) * G_LD + lcw) = rb[i];
;       }
;       LD_AF(afB, 1); LD_BF(bfA, 1, 0);
.LBB0_1117:
	s_bitcmp1_b32 s85, 0
	s_cselect_b32 s15, 0x12000, 0
	s_add_i32 s15, s15, 16
	v_add3_u32 v56, s15, v131, v139
	v_add3_u32 v92, s15, v132, v139
	ds_read_b128 v[4:7], v56 offset:13824
	ds_read_b128 v[16:19], v92 offset:36864
	ds_read_b128 v[12:15], v92 offset:39168
	ds_read_b128 v[8:11], v92 offset:41472
	ds_read_b128 v[0:3], v92 offset:43776
	ds_read_b128 v[76:79], v56
	ds_read_b128 v[72:75], v56 offset:2304
	ds_read_b128 v[52:55], v56 offset:4608
	ds_read_b128 v[44:47], v56 offset:6912
	ds_read_b128 v[48:51], v56 offset:9216
	ds_read_b128 v[40:43], v56 offset:11520
	ds_read_b128 v[32:35], v56 offset:16128
	s_mov_b32 s14, s85
	s_add_i32 s85, s85, 1
	s_bitcmp1_b32 s85, 0
	s_cselect_b32 s15, 0x12000, 0
	v_add_u32_e32 v20, s15, v129
	v_add_u32_e32 v21, v20, v134
	s_waitcnt vmcnt(15)
	ds_write_b128 v21, v[94:97]
	s_waitcnt vmcnt(13)
	ds_write_b128 v21, v[102:105] offset:4608
	s_waitcnt vmcnt(11)
	ds_write_b128 v21, v[106:109] offset:9216
	s_waitcnt vmcnt(9)
	ds_write_b128 v21, v[118:121] offset:13824
	s_waitcnt vmcnt(7)
	ds_write_b128 v21, v[122:125] offset:18432
	s_waitcnt vmcnt(5)
	ds_write_b128 v21, v[148:151] offset:23040
	s_waitcnt vmcnt(3)
	ds_write_b128 v21, v[152:155] offset:27648
	s_waitcnt vmcnt(1)
	ds_write_b128 v21, v[160:163] offset:32256
	ds_read_b128 v[172:175], v92 offset:46080
	ds_read_b128 v[88:91], v92 offset:48384
	ds_read_b128 v[84:87], v92 offset:50688
	ds_read_b128 v[80:83], v92 offset:52992
	s_waitcnt lgkmcnt(14)
	v_mfma_f32_16x16x32_f16 a[204:207], v[16:19], v[76:79], a[204:207]
	v_mfma_f32_16x16x32_f16 a[200:203], v[12:15], v[76:79], a[200:203]
	v_mfma_f32_16x16x32_f16 a[196:199], v[8:11], v[76:79], a[196:199]
	v_mfma_f32_16x16x32_f16 a[188:191], v[0:3], v[76:79], a[188:191]
	v_mfma_f32_16x16x32_f16 a[192:195], v[16:19], v[72:75], a[192:195]
	v_mfma_f32_16x16x32_f16 a[184:187], v[12:15], v[72:75], a[184:187]
	v_mfma_f32_16x16x32_f16 a[180:183], v[8:11], v[72:75], a[180:183]
	v_mfma_f32_16x16x32_f16 a[176:179], v[0:3], v[72:75], a[176:179]
	v_mfma_f32_16x16x32_f16 a[156:159], v[16:19], v[52:55], a[156:159]
	v_mfma_f32_16x16x32_f16 a[152:155], v[12:15], v[52:55], a[152:155]
	v_mfma_f32_16x16x32_f16 a[148:151], v[8:11], v[52:55], a[148:151]
	v_mfma_f32_16x16x32_f16 a[144:147], v[0:3], v[52:55], a[144:147]
	v_mfma_f32_16x16x32_f16 a[124:127], v[16:19], v[44:47], a[124:127]
	v_mfma_f32_16x16x32_f16 a[120:123], v[12:15], v[44:47], a[120:123]
	v_mfma_f32_16x16x32_f16 a[116:119], v[8:11], v[44:47], a[116:119]
	v_mfma_f32_16x16x32_f16 a[112:115], v[0:3], v[44:47], a[112:115]
	v_mfma_f32_16x16x32_f16 a[92:95], v[16:19], v[48:51], a[92:95]
	v_mfma_f32_16x16x32_f16 a[88:91], v[12:15], v[48:51], a[88:91]
	v_mfma_f32_16x16x32_f16 a[84:87], v[8:11], v[48:51], a[84:87]
	v_mfma_f32_16x16x32_f16 a[80:83], v[0:3], v[48:51], a[80:83]
	s_waitcnt lgkmcnt(13)
	v_mfma_f32_16x16x32_f16 a[60:63], v[16:19], v[40:43], a[60:63]
	v_mfma_f32_16x16x32_f16 a[56:59], v[12:15], v[40:43], a[56:59]
	v_mfma_f32_16x16x32_f16 a[52:55], v[8:11], v[40:43], a[52:55]
	v_mfma_f32_16x16x32_f16 a[48:51], v[0:3], v[40:43], a[48:51]
	v_mfma_f32_16x16x32_f16 a[32:35], v[16:19], v[4:7], a[32:35]
	v_mfma_f32_16x16x32_f16 a[28:31], v[12:15], v[4:7], a[28:31]
	v_mfma_f32_16x16x32_f16 a[24:27], v[8:11], v[4:7], a[24:27]
	v_mfma_f32_16x16x32_f16 a[20:23], v[0:3], v[4:7], a[20:23]
	s_waitcnt lgkmcnt(12)
	v_mfma_f32_16x16x32_f16 a[12:15], v[16:19], v[32:35], a[12:15]
	v_mfma_f32_16x16x32_f16 a[8:11], v[12:15], v[32:35], a[8:11]
	v_mfma_f32_16x16x32_f16 a[4:7], v[8:11], v[32:35], a[4:7]
	v_mfma_f32_16x16x32_f16 a[0:3], v[0:3], v[32:35], a[0:3]
	v_add_u32_e32 v0, v20, v135
	s_waitcnt vmcnt(7)
	ds_write_b128 v21, v[98:101] offset:36864
	s_waitcnt vmcnt(6)
	ds_write_b128 v21, v[110:113] offset:41472
	s_waitcnt vmcnt(5)
	ds_write_b128 v21, v[114:117] offset:46080
	s_waitcnt vmcnt(4)
	ds_write_b128 v21, v[140:143] offset:50688
	s_waitcnt vmcnt(3)
	ds_write_b128 v21, v[144:147] offset:55296
	s_waitcnt vmcnt(2)
	ds_write_b128 v21, v[156:159] offset:59904
	s_waitcnt vmcnt(1)
	ds_write_b128 v21, v[164:167] offset:64512
	s_waitcnt vmcnt(0)
	ds_write_b128 v0, v[168:171]
	ds_read_b128 v[36:39], v56 offset:64
	ds_read_b128 v[28:31], v56 offset:2368
	ds_read_b128 v[24:27], v56 offset:4672
	ds_read_b128 v[20:23], v56 offset:6976
	ds_read_b128 v[16:19], v56 offset:9280
	ds_read_b128 v[12:15], v56 offset:11584
	ds_read_b128 v[8:11], v56 offset:13888
	ds_read_b128 v[0:3], v56 offset:16192
	ds_read_b128 v[56:59], v92 offset:36928
	ds_read_b128 v[60:63], v92 offset:39232
	ds_read_b128 v[64:67], v92 offset:41536
	ds_read_b128 v[68:71], v92 offset:43840
	s_cmpk_gt_u32 s14, 0x55
	s_cbranch_scc1 .Lgw10_nl
; #define MMA_BLK(afx, bfx, nh_) _Pragma("unroll") for (int mi = 0; mi < 8; ++mi) _Pragma("unroll") for (int ni = 0; ni < 4; ++ni) mfma16_acc(acc[mi][(nh_) * 4 + ni], bfx[ni], afx[mi])
; template <class Epi>
; __device__ __forceinline__ void gemm_run(const GemmArgs g, Epi epi, char* smem) {
;     ...
;       MMA_BLK(afA, bfB, 1);
;       __builtin_amdgcn_sched_barrier(0);
;       if (kt + 2 < nk) {
;         const int ko = (kt + 2) * 64;
; #pragma unroll
;         for (int i = 0; i < 8; ++i) { ra[i] = __builtin_amdgcn_raw_buffer_load_b128(Ars, aoff, i * astep + ko * 2, 0); rb[i] = __builtin_amdgcn_raw_buffer_load_b128(Brs, boff, i * bstep + ko * 2, 0); }
;       }
	s_waitcnt lgkmcnt(14)
	v_mfma_f32_16x16x32_f16 a[240:243], v[172:175], v[76:79], a[240:243]
	v_mfma_f32_16x16x32_f16 a[252:255], v[88:91], v[76:79], a[252:255]
	v_mfma_f32_16x16x32_f16 a[248:251], v[84:87], v[76:79], a[248:251]
	s_add_i32 s86, s84, 0xffd98000
	v_mfma_f32_16x16x32_f16 a[244:247], v[80:83], v[76:79], a[244:247]
	s_mov_b32 s14, s10
	v_mfma_f32_16x16x32_f16 a[236:239], v[172:175], v[72:75], a[236:239]
	s_mov_b32 s15, s11
	v_mfma_f32_16x16x32_f16 a[232:235], v[88:91], v[72:75], a[232:235]
	buffer_load_dwordx4 v[94:97], v128, s[8:11], s86 offen
	v_mfma_f32_16x16x32_f16 a[228:231], v[84:87], v[72:75], a[228:231]
	buffer_load_dwordx4 v[98:101], v128, s[12:15], s86 offen
	v_mfma_f32_16x16x32_f16 a[224:227], v[80:83], v[72:75], a[224:227]
	s_add_i32 s86, s84, 0xffdf0000
	v_mfma_f32_16x16x32_f16 a[220:223], v[172:175], v[52:55], a[220:223]
	buffer_load_dwordx4 v[102:105], v128, s[8:11], s86 offen
	v_mfma_f32_16x16x32_f16 a[216:219], v[88:91], v[52:55], a[216:219]
	buffer_load_dwordx4 v[110:113], v128, s[12:15], s86 offen
	v_mfma_f32_16x16x32_f16 a[212:215], v[84:87], v[52:55], a[212:215]
	s_add_i32 s86, s84, 0xffe48000
	v_mfma_f32_16x16x32_f16 a[208:211], v[80:83], v[52:55], a[208:211]
	buffer_load_dwordx4 v[106:109], v128, s[8:11], s86 offen
	v_mfma_f32_16x16x32_f16 a[172:175], v[172:175], v[44:47], a[172:175]
	buffer_load_dwordx4 v[114:117], v128, s[12:15], s86 offen
	v_mfma_f32_16x16x32_f16 a[168:171], v[88:91], v[44:47], a[168:171]
	s_add_i32 s86, s84, 0xffea0000
	v_mfma_f32_16x16x32_f16 a[164:167], v[84:87], v[44:47], a[164:167]
	buffer_load_dwordx4 v[118:121], v128, s[8:11], s86 offen
	v_mfma_f32_16x16x32_f16 a[160:163], v[80:83], v[44:47], a[160:163]
	buffer_load_dwordx4 v[140:143], v128, s[12:15], s86 offen
	v_mfma_f32_16x16x32_f16 a[140:143], v[172:175], v[48:51], a[140:143]
	s_add_i32 s86, s84, 0xffef8000
	v_mfma_f32_16x16x32_f16 a[136:139], v[88:91], v[48:51], a[136:139]
	buffer_load_dwordx4 v[122:125], v128, s[8:11], s86 offen
	v_mfma_f32_16x16x32_f16 a[132:135], v[84:87], v[48:51], a[132:135]
	buffer_load_dwordx4 v[144:147], v128, s[12:15], s86 offen
	v_mfma_f32_16x16x32_f16 a[128:131], v[80:83], v[48:51], a[128:131]
	s_add_i32 s86, s84, 0xfff50000
	v_mfma_f32_16x16x32_f16 a[108:111], v[172:175], v[40:43], a[108:111]
	buffer_load_dwordx4 v[148:151], v128, s[8:11], s86 offen
	v_mfma_f32_16x16x32_f16 a[104:107], v[88:91], v[40:43], a[104:107]
	buffer_load_dwordx4 v[156:159], v128, s[12:15], s86 offen
	v_mfma_f32_16x16x32_f16 a[100:103], v[84:87], v[40:43], a[100:103]
	s_add_i32 s86, s84, 0xfffa8000
	v_mfma_f32_16x16x32_f16 a[96:99], v[80:83], v[40:43], a[96:99]
	buffer_load_dwordx4 v[152:155], v128, s[8:11], s86 offen
	v_mfma_f32_16x16x32_f16 a[76:79], v[172:175], v[4:7], a[76:79]
	buffer_load_dwordx4 v[164:167], v128, s[12:15], s86 offen
	v_mfma_f32_16x16x32_f16 a[72:75], v[88:91], v[4:7], a[72:75]
	buffer_load_dwordx4 v[160:163], v128, s[8:11], s84 offen
	v_mfma_f32_16x16x32_f16 a[68:71], v[84:87], v[4:7], a[68:71]
	buffer_load_dwordx4 v[168:171], v128, s[12:15], s84 offen
	v_mfma_f32_16x16x32_f16 a[64:67], v[80:83], v[4:7], a[64:67]
	v_mfma_f32_16x16x32_f16 a[44:47], v[172:175], v[32:35], a[44:47]
	v_mfma_f32_16x16x32_f16 a[40:43], v[88:91], v[32:35], a[40:43]
	v_mfma_f32_16x16x32_f16 a[36:39], v[84:87], v[32:35], a[36:39]
	v_mfma_f32_16x16x32_f16 a[16:19], v[80:83], v[32:35], a[16:19]
	s_branch .LBB0_1116
.Lgw10_nl:
	s_waitcnt lgkmcnt(14)
	v_mfma_f32_16x16x32_f16 a[240:243], v[172:175], v[76:79], a[240:243]
	v_mfma_f32_16x16x32_f16 a[252:255], v[88:91], v[76:79], a[252:255]
	v_mfma_f32_16x16x32_f16 a[248:251], v[84:87], v[76:79], a[248:251]
	v_mfma_f32_16x16x32_f16 a[244:247], v[80:83], v[76:79], a[244:247]
	v_mfma_f32_16x16x32_f16 a[236:239], v[172:175], v[72:75], a[236:239]
	v_mfma_f32_16x16x32_f16 a[232:235], v[88:91], v[72:75], a[232:235]
	v_mfma_f32_16x16x32_f16 a[228:231], v[84:87], v[72:75], a[228:231]
	v_mfma_f32_16x16x32_f16 a[224:227], v[80:83], v[72:75], a[224:227]
	v_mfma_f32_16x16x32_f16 a[220:223], v[172:175], v[52:55], a[220:223]
	v_mfma_f32_16x16x32_f16 a[216:219], v[88:91], v[52:55], a[216:219]
	v_mfma_f32_16x16x32_f16 a[212:215], v[84:87], v[52:55], a[212:215]
	v_mfma_f32_16x16x32_f16 a[208:211], v[80:83], v[52:55], a[208:211]
	v_mfma_f32_16x16x32_f16 a[172:175], v[172:175], v[44:47], a[172:175]
	v_mfma_f32_16x16x32_f16 a[168:171], v[88:91], v[44:47], a[168:171]
	v_mfma_f32_16x16x32_f16 a[164:167], v[84:87], v[44:47], a[164:167]
	v_mfma_f32_16x16x32_f16 a[160:163], v[80:83], v[44:47], a[160:163]
	v_mfma_f32_16x16x32_f16 a[140:143], v[172:175], v[48:51], a[140:143]
	v_mfma_f32_16x16x32_f16 a[136:139], v[88:91], v[48:51], a[136:139]
	v_mfma_f32_16x16x32_f16 a[132:135], v[84:87], v[48:51], a[132:135]
	v_mfma_f32_16x16x32_f16 a[128:131], v[80:83], v[48:51], a[128:131]
	v_mfma_f32_16x16x32_f16 a[108:111], v[172:175], v[40:43], a[108:111]
	v_mfma_f32_16x16x32_f16 a[104:107], v[88:91], v[40:43], a[104:107]
	v_mfma_f32_16x16x32_f16 a[100:103], v[84:87], v[40:43], a[100:103]
	v_mfma_f32_16x16x32_f16 a[96:99], v[80:83], v[40:43], a[96:99]
	v_mfma_f32_16x16x32_f16 a[76:79], v[172:175], v[4:7], a[76:79]
	v_mfma_f32_16x16x32_f16 a[72:75], v[88:91], v[4:7], a[72:75]
	v_mfma_f32_16x16x32_f16 a[68:71], v[84:87], v[4:7], a[68:71]
	v_mfma_f32_16x16x32_f16 a[64:67], v[80:83], v[4:7], a[64:67]
	v_mfma_f32_16x16x32_f16 a[44:47], v[172:175], v[32:35], a[44:47]
	v_mfma_f32_16x16x32_f16 a[40:43], v[88:91], v[32:35], a[40:43]
	v_mfma_f32_16x16x32_f16 a[36:39], v[84:87], v[32:35], a[36:39]
	v_mfma_f32_16x16x32_f16 a[16:19], v[80:83], v[32:35], a[16:19]
	s_branch .LBB0_1116

; #define LD_AF(dst, ks_) _Pragma("unroll") for (int i = 0; i < 8; ++i) dst[i] = *(const h8*)(sA + i * 16 * G_LD + (ks_) * 32)
; #define LD_BF(dst, ks_, nh_) _Pragma("unroll") for (int i = 0; i < 4; ++i) dst[i] = *(const h8*)(sB + ((nh_) * 4 + i) * 16 * G_LD + (ks_) * 32)
; #define MMA_BLK(afx, bfx, nh_) _Pragma("unroll") for (int mi = 0; mi < 8; ++mi) _Pragma("unroll") for (int ni = 0; ni < 4; ++ni) mfma16_acc(acc[mi][(nh_) * 4 + ni], bfx[ni], afx[mi])
; template <class Epi>
; __device__ __forceinline__ void gemm_run(const GemmArgs g, Epi epi, char* smem) {
;     ...
;       const hf* sA = sbase + (kt & 1) * G_STAGE + (wm * 128 + fr) * G_LD + fqs;
;       const hf* sB = sbase + (kt & 1) * G_STAGE + (256 + wn * 128 + fr) * G_LD + fqs;
;       hf* st = sbase + ((kt + 1) & 1) * G_STAGE;
;       h8 afA[8], afB[8], bfA[4], bfB[4];
;     ...
;       LD_AF(afA, 0); LD_BF(bfA, 0, 0);
;       if (kt + 1 < nk) {
; #pragma unroll
;         for (int i = 0; i < 8; ++i) *(u4*)(st + (lr + 32 * i) * G_LD + lcw) = ra[i];
;       }
;       __builtin_amdgcn_sched_barrier(0);
;       LD_BF(bfB, 0, 1);
;       MMA_BLK(afA, bfA, 0);
;       __builtin_amdgcn_sched_barrier(0);
;       if (kt + 1 < nk) {
; #pragma unroll
;         for (int i = 0; i < 8; ++i) *(u4*)(st + (256 + lr + 32 * i) * G_LD + lcw) = rb[i];
;       }
;       LD_AF(afB, 1); LD_BF(bfA, 1, 0);
.LBB0_1201:
	s_bitcmp1_b32 s13, 0
	s_cselect_b32 s11, 0x12000, 0
	s_add_i32 s11, s11, 16
	v_add3_u32 v56, s11, v97, v105
	v_add3_u32 v92, s11, v98, v105
	ds_read_b128 v[4:7], v56 offset:13824
	ds_read_b128 v[16:19], v92 offset:36864
	ds_read_b128 v[12:15], v92 offset:39168
	ds_read_b128 v[8:11], v92 offset:41472
	ds_read_b128 v[0:3], v92 offset:43776
	ds_read_b128 v[76:79], v56
	ds_read_b128 v[72:75], v56 offset:2304
	ds_read_b128 v[52:55], v56 offset:4608
	ds_read_b128 v[44:47], v56 offset:6912
	ds_read_b128 v[48:51], v56 offset:9216
	ds_read_b128 v[40:43], v56 offset:11520
	ds_read_b128 v[32:35], v56 offset:16128
	s_mov_b32 s10, s13
	s_add_i32 s13, s13, 1
	s_bitcmp1_b32 s13, 0
	s_cselect_b32 s11, 0x12000, 0
	v_add_u32_e32 v20, s11, v95
	v_add_u32_e32 v21, v20, v100
	s_waitcnt vmcnt(15)
	ds_write_b128 v21, v[106:109]
	s_waitcnt vmcnt(13)
	ds_write_b128 v21, v[114:117] offset:4608
	s_waitcnt vmcnt(11)
	ds_write_b128 v21, v[122:125] offset:9216
	s_waitcnt vmcnt(9)
	ds_write_b128 v21, v[130:133] offset:13824
	s_waitcnt vmcnt(7)
	ds_write_b128 v21, v[138:141] offset:18432
	s_waitcnt vmcnt(5)
	ds_write_b128 v21, v[146:149] offset:23040
	s_waitcnt vmcnt(3)
	ds_write_b128 v21, v[154:157] offset:27648
	s_waitcnt vmcnt(1)
	ds_write_b128 v21, v[162:165] offset:32256
	ds_read_b128 v[170:173], v92 offset:46080
	ds_read_b128 v[88:91], v92 offset:48384
	ds_read_b128 v[84:87], v92 offset:50688
	ds_read_b128 v[80:83], v92 offset:52992
	s_waitcnt lgkmcnt(14)
	v_mfma_f32_16x16x32_f16 a[252:255], v[16:19], v[76:79], a[252:255]
	v_mfma_f32_16x16x32_f16 a[244:247], v[12:15], v[76:79], a[244:247]
	v_mfma_f32_16x16x32_f16 a[236:239], v[8:11], v[76:79], a[236:239]
	v_mfma_f32_16x16x32_f16 a[228:231], v[0:3], v[76:79], a[228:231]
	v_mfma_f32_16x16x32_f16 a[220:223], v[16:19], v[72:75], a[220:223]
	v_mfma_f32_16x16x32_f16 a[212:215], v[12:15], v[72:75], a[212:215]
	v_mfma_f32_16x16x32_f16 a[204:207], v[8:11], v[72:75], a[204:207]
	v_mfma_f32_16x16x32_f16 a[196:199], v[0:3], v[72:75], a[196:199]
	v_mfma_f32_16x16x32_f16 a[188:191], v[16:19], v[52:55], a[188:191]
	v_mfma_f32_16x16x32_f16 a[180:183], v[12:15], v[52:55], a[180:183]
	v_mfma_f32_16x16x32_f16 a[172:175], v[8:11], v[52:55], a[172:175]
	v_mfma_f32_16x16x32_f16 a[164:167], v[0:3], v[52:55], a[164:167]
	v_mfma_f32_16x16x32_f16 a[156:159], v[16:19], v[44:47], a[156:159]
	v_mfma_f32_16x16x32_f16 a[148:151], v[12:15], v[44:47], a[148:151]
	v_mfma_f32_16x16x32_f16 a[140:143], v[8:11], v[44:47], a[140:143]
	v_mfma_f32_16x16x32_f16 a[132:135], v[0:3], v[44:47], a[132:135]
	v_mfma_f32_16x16x32_f16 a[124:127], v[16:19], v[48:51], a[124:127]
	v_mfma_f32_16x16x32_f16 a[116:119], v[12:15], v[48:51], a[116:119]
	v_mfma_f32_16x16x32_f16 a[108:111], v[8:11], v[48:51], a[108:111]
	v_mfma_f32_16x16x32_f16 a[100:103], v[0:3], v[48:51], a[100:103]
	s_waitcnt lgkmcnt(13)
	v_mfma_f32_16x16x32_f16 a[92:95], v[16:19], v[40:43], a[92:95]
	v_mfma_f32_16x16x32_f16 a[84:87], v[12:15], v[40:43], a[84:87]
	v_mfma_f32_16x16x32_f16 a[76:79], v[8:11], v[40:43], a[76:79]
	v_mfma_f32_16x16x32_f16 a[68:71], v[0:3], v[40:43], a[68:71]
	v_mfma_f32_16x16x32_f16 a[60:63], v[16:19], v[4:7], a[60:63]
	v_mfma_f32_16x16x32_f16 a[52:55], v[12:15], v[4:7], a[52:55]
	v_mfma_f32_16x16x32_f16 a[44:47], v[8:11], v[4:7], a[44:47]
	v_mfma_f32_16x16x32_f16 a[36:39], v[0:3], v[4:7], a[36:39]
	s_waitcnt lgkmcnt(12)
	v_mfma_f32_16x16x32_f16 a[28:31], v[16:19], v[32:35], a[28:31]
	v_mfma_f32_16x16x32_f16 a[24:27], v[12:15], v[32:35], a[24:27]
	v_mfma_f32_16x16x32_f16 a[20:23], v[8:11], v[32:35], a[20:23]
	v_mfma_f32_16x16x32_f16 a[12:15], v[0:3], v[32:35], a[12:15]
	v_add_u32_e32 v0, v20, v101
	ds_write_b128 v21, v[110:113] offset:36864
	ds_write_b128 v21, v[118:121] offset:41472
	ds_write_b128 v21, v[126:129] offset:46080
	ds_write_b128 v21, v[134:137] offset:50688
	ds_write_b128 v21, v[142:145] offset:55296
	ds_write_b128 v21, v[150:153] offset:59904
	ds_write_b128 v21, v[158:161] offset:64512
	s_waitcnt vmcnt(0)
	ds_write_b128 v0, v[166:169]
	ds_read_b128 v[36:39], v56 offset:64
	ds_read_b128 v[28:31], v56 offset:2368
	ds_read_b128 v[24:27], v56 offset:4672
	ds_read_b128 v[20:23], v56 offset:6976
	ds_read_b128 v[16:19], v56 offset:9280
	ds_read_b128 v[12:15], v56 offset:11584
	ds_read_b128 v[8:11], v56 offset:13888
	ds_read_b128 v[0:3], v56 offset:16192
	ds_read_b128 v[56:59], v92 offset:36928
	ds_read_b128 v[60:63], v92 offset:39232
	ds_read_b128 v[64:67], v92 offset:41536
	ds_read_b128 v[68:71], v92 offset:43840
	s_cmp_gt_u32 s10, 29
	s_cbranch_scc1 .Lgw11_nl
; #define MMA_BLK(afx, bfx, nh_) _Pragma("unroll") for (int mi = 0; mi < 8; ++mi) _Pragma("unroll") for (int ni = 0; ni < 4; ++ni) mfma16_acc(acc[mi][(nh_) * 4 + ni], bfx[ni], afx[mi])
; template <class Epi>
; __device__ __forceinline__ void gemm_run(const GemmArgs g, Epi epi, char* smem) {
;     ...
;       MMA_BLK(afA, bfB, 1);
;       __builtin_amdgcn_sched_barrier(0);
;       if (kt + 2 < nk) {
;         const int ko = (kt + 2) * 64;
; #pragma unroll
;         for (int i = 0; i < 8; ++i) { ra[i] = __builtin_amdgcn_raw_buffer_load_b128(Ars, aoff, i * astep + ko * 2, 0); rb[i] = __builtin_amdgcn_raw_buffer_load_b128(Brs, boff, i * bstep + ko * 2, 0); }
;       }
	s_waitcnt lgkmcnt(14)
	v_mfma_f32_16x16x32_f16 a[248:251], v[170:173], v[76:79], a[248:251]
	v_mfma_f32_16x16x32_f16 a[240:243], v[88:91], v[76:79], a[240:243]
	v_mfma_f32_16x16x32_f16 a[232:235], v[84:87], v[76:79], a[232:235]
	s_add_i32 s15, s3, 0xfff20000
	v_mfma_f32_16x16x32_f16 a[224:227], v[80:83], v[76:79], a[224:227]
	s_mov_b32 s10, s54
	v_mfma_f32_16x16x32_f16 a[216:219], v[170:173], v[72:75], a[216:219]
	s_mov_b32 s11, s55
	v_mfma_f32_16x16x32_f16 a[208:211], v[88:91], v[72:75], a[208:211]
	buffer_load_dwordx4 v[106:109], v94, s[52:55], s15 offen
	v_mfma_f32_16x16x32_f16 a[200:203], v[84:87], v[72:75], a[200:203]
	buffer_load_dwordx4 v[110:113], v94, s[8:11], s15 offen
	v_mfma_f32_16x16x32_f16 a[192:195], v[80:83], v[72:75], a[192:195]
	s_add_i32 s15, s3, 0xfff40000
	v_mfma_f32_16x16x32_f16 a[184:187], v[170:173], v[52:55], a[184:187]
	buffer_load_dwordx4 v[114:117], v94, s[52:55], s15 offen
	v_mfma_f32_16x16x32_f16 a[176:179], v[88:91], v[52:55], a[176:179]
	buffer_load_dwordx4 v[118:121], v94, s[8:11], s15 offen
	v_mfma_f32_16x16x32_f16 a[168:171], v[84:87], v[52:55], a[168:171]
	s_add_i32 s15, s3, 0xfff60000
	v_mfma_f32_16x16x32_f16 a[160:163], v[80:83], v[52:55], a[160:163]
	buffer_load_dwordx4 v[122:125], v94, s[52:55], s15 offen
	v_mfma_f32_16x16x32_f16 a[152:155], v[170:173], v[44:47], a[152:155]
	buffer_load_dwordx4 v[126:129], v94, s[8:11], s15 offen
	v_mfma_f32_16x16x32_f16 a[144:147], v[88:91], v[44:47], a[144:147]
	s_add_i32 s15, s3, 0xfff80000
	v_mfma_f32_16x16x32_f16 a[136:139], v[84:87], v[44:47], a[136:139]
	buffer_load_dwordx4 v[130:133], v94, s[52:55], s15 offen
	v_mfma_f32_16x16x32_f16 a[128:131], v[80:83], v[44:47], a[128:131]
	buffer_load_dwordx4 v[134:137], v94, s[8:11], s15 offen
	v_mfma_f32_16x16x32_f16 a[120:123], v[170:173], v[48:51], a[120:123]
	s_add_i32 s15, s3, 0xfffa0000
	v_mfma_f32_16x16x32_f16 a[112:115], v[88:91], v[48:51], a[112:115]
	buffer_load_dwordx4 v[138:141], v94, s[52:55], s15 offen
	v_mfma_f32_16x16x32_f16 a[104:107], v[84:87], v[48:51], a[104:107]
	buffer_load_dwordx4 v[142:145], v94, s[8:11], s15 offen
	v_mfma_f32_16x16x32_f16 a[96:99], v[80:83], v[48:51], a[96:99]
	s_add_i32 s15, s3, 0xfffc0000
	v_mfma_f32_16x16x32_f16 a[88:91], v[170:173], v[40:43], a[88:91]
	buffer_load_dwordx4 v[146:149], v94, s[52:55], s15 offen
	v_mfma_f32_16x16x32_f16 a[80:83], v[88:91], v[40:43], a[80:83]
	buffer_load_dwordx4 v[150:153], v94, s[8:11], s15 offen
	v_mfma_f32_16x16x32_f16 a[72:75], v[84:87], v[40:43], a[72:75]
	s_add_i32 s15, s3, 0xfffe0000
	v_mfma_f32_16x16x32_f16 a[64:67], v[80:83], v[40:43], a[64:67]
	buffer_load_dwordx4 v[154:157], v94, s[52:55], s15 offen
	v_mfma_f32_16x16x32_f16 a[56:59], v[170:173], v[4:7], a[56:59]
	buffer_load_dwordx4 v[158:161], v94, s[8:11], s15 offen
	v_mfma_f32_16x16x32_f16 a[48:51], v[88:91], v[4:7], a[48:51]
	buffer_load_dwordx4 v[162:165], v94, s[52:55], s3 offen
	v_mfma_f32_16x16x32_f16 a[40:43], v[84:87], v[4:7], a[40:43]
	buffer_load_dwordx4 v[166:169], v94, s[8:11], s3 offen
	v_mfma_f32_16x16x32_f16 a[32:35], v[80:83], v[4:7], a[32:35]
	v_mfma_f32_16x16x32_f16 a[16:19], v[170:173], v[32:35], a[16:19]
	v_mfma_f32_16x16x32_f16 a[8:11], v[88:91], v[32:35], a[8:11]
	v_mfma_f32_16x16x32_f16 a[4:7], v[84:87], v[32:35], a[4:7]
	v_mfma_f32_16x16x32_f16 a[0:3], v[80:83], v[32:35], a[0:3]
	s_branch .LBB0_1200
.Lgw11_nl:
	s_waitcnt lgkmcnt(14)
	v_mfma_f32_16x16x32_f16 a[248:251], v[170:173], v[76:79], a[248:251]
	v_mfma_f32_16x16x32_f16 a[240:243], v[88:91], v[76:79], a[240:243]
	v_mfma_f32_16x16x32_f16 a[232:235], v[84:87], v[76:79], a[232:235]
	v_mfma_f32_16x16x32_f16 a[224:227], v[80:83], v[76:79], a[224:227]
	v_mfma_f32_16x16x32_f16 a[216:219], v[170:173], v[72:75], a[216:219]
	v_mfma_f32_16x16x32_f16 a[208:211], v[88:91], v[72:75], a[208:211]
	v_mfma_f32_16x16x32_f16 a[200:203], v[84:87], v[72:75], a[200:203]
	v_mfma_f32_16x16x32_f16 a[192:195], v[80:83], v[72:75], a[192:195]
	v_mfma_f32_16x16x32_f16 a[184:187], v[170:173], v[52:55], a[184:187]
	v_mfma_f32_16x16x32_f16 a[176:179], v[88:91], v[52:55], a[176:179]
	v_mfma_f32_16x16x32_f16 a[168:171], v[84:87], v[52:55], a[168:171]
	v_mfma_f32_16x16x32_f16 a[160:163], v[80:83], v[52:55], a[160:163]
	v_mfma_f32_16x16x32_f16 a[152:155], v[170:173], v[44:47], a[152:155]
	v_mfma_f32_16x16x32_f16 a[144:147], v[88:91], v[44:47], a[144:147]
	v_mfma_f32_16x16x32_f16 a[136:139], v[84:87], v[44:47], a[136:139]
	v_mfma_f32_16x16x32_f16 a[128:131], v[80:83], v[44:47], a[128:131]
	v_mfma_f32_16x16x32_f16 a[120:123], v[170:173], v[48:51], a[120:123]
	v_mfma_f32_16x16x32_f16 a[112:115], v[88:91], v[48:51], a[112:115]
	v_mfma_f32_16x16x32_f16 a[104:107], v[84:87], v[48:51], a[104:107]
	v_mfma_f32_16x16x32_f16 a[96:99], v[80:83], v[48:51], a[96:99]
	v_mfma_f32_16x16x32_f16 a[88:91], v[170:173], v[40:43], a[88:91]
	v_mfma_f32_16x16x32_f16 a[80:83], v[88:91], v[40:43], a[80:83]
	v_mfma_f32_16x16x32_f16 a[72:75], v[84:87], v[40:43], a[72:75]
	v_mfma_f32_16x16x32_f16 a[64:67], v[80:83], v[40:43], a[64:67]
	v_mfma_f32_16x16x32_f16 a[56:59], v[170:173], v[4:7], a[56:59]
	v_mfma_f32_16x16x32_f16 a[48:51], v[88:91], v[4:7], a[48:51]
	v_mfma_f32_16x16x32_f16 a[40:43], v[84:87], v[4:7], a[40:43]
	v_mfma_f32_16x16x32_f16 a[32:35], v[80:83], v[4:7], a[32:35]
	v_mfma_f32_16x16x32_f16 a[16:19], v[170:173], v[32:35], a[16:19]
	v_mfma_f32_16x16x32_f16 a[8:11], v[88:91], v[32:35], a[8:11]
	v_mfma_f32_16x16x32_f16 a[4:7], v[84:87], v[32:35], a[4:7]
	v_mfma_f32_16x16x32_f16 a[0:3], v[80:83], v[32:35], a[0:3]
	s_branch .LBB0_1200

; #define LD_AF(dst, ks_) _Pragma("unroll") for (int i = 0; i < 8; ++i) dst[i] = *(const h8*)(sA + i * 16 * G_LD + (ks_) * 32)
; #define LD_BF(dst, ks_, nh_) _Pragma("unroll") for (int i = 0; i < 4; ++i) dst[i] = *(const h8*)(sB + ((nh_) * 4 + i) * 16 * G_LD + (ks_) * 32)
; #define MMA_BLK(afx, bfx, nh_) _Pragma("unroll") for (int mi = 0; mi < 8; ++mi) _Pragma("unroll") for (int ni = 0; ni < 4; ++ni) mfma16_acc(acc[mi][(nh_) * 4 + ni], bfx[ni], afx[mi])
; template <class Epi>
; __device__ __forceinline__ void gemm_run(const GemmArgs g, Epi epi, char* smem) {
;     ...
;       const hf* sA = sbase + (kt & 1) * G_STAGE + (wm * 128 + fr) * G_LD + fqs;
;       const hf* sB = sbase + (kt & 1) * G_STAGE + (256 + wn * 128 + fr) * G_LD + fqs;
;       hf* st = sbase + ((kt + 1) & 1) * G_STAGE;
;       h8 afA[8], afB[8], bfA[4], bfB[4];
;     ...
;       LD_AF(afA, 0); LD_BF(bfA, 0, 0);
;       if (kt + 1 < nk) {
; #pragma unroll
;         for (int i = 0; i < 8; ++i) *(u4*)(st + (lr + 32 * i) * G_LD + lcw) = ra[i];
;       }
;       __builtin_amdgcn_sched_barrier(0);
;       LD_BF(bfB, 0, 1);
;       MMA_BLK(afA, bfA, 0);
;       __builtin_amdgcn_sched_barrier(0);
;       if (kt + 1 < nk) {
; #pragma unroll
;         for (int i = 0; i < 8; ++i) *(u4*)(st + (256 + lr + 32 * i) * G_LD + lcw) = rb[i];
;       }
;       LD_AF(afB, 1); LD_BF(bfA, 1, 0);
.LBB0_1623:
	s_bitcmp1_b32 s21, 0
	s_cselect_b32 s15, 0x12000, 0
	s_add_i32 s15, s15, 16
	v_add3_u32 v104, s15, v96, v103
	v_add3_u32 v64, s15, v95, v103
	ds_read_b128 v[36:39], v104 offset:36864
	ds_read_b128 v[56:59], v64
	ds_read_b128 v[32:35], v104 offset:39168
	ds_read_b128 v[24:27], v104 offset:41472
	ds_read_b128 v[16:19], v104 offset:43776
	ds_read_b128 v[44:47], v64 offset:2304
	ds_read_b128 v[28:31], v64 offset:4608
	ds_read_b128 v[12:15], v64 offset:6912
	ds_read_b128 v[4:7], v64 offset:9216
	ds_read_b128 v[0:3], v64 offset:11520
	ds_read_b128 v[8:11], v64 offset:13824
	ds_read_b128 v[20:23], v64 offset:16128
	s_mov_b32 s14, s21
	s_add_i32 s21, s21, 1
	s_bitcmp1_b32 s21, 0
	s_cselect_b32 s77, 0x12000, 0
	v_add_u32_e32 v40, s77, v93
	v_add_u32_e32 v41, v40, v98
	s_waitcnt vmcnt(15)
	ds_write_b128 v41, v[106:109]
	s_waitcnt vmcnt(14)
	ds_write_b128 v41, v[110:113] offset:4608
	s_waitcnt vmcnt(11)
	ds_write_b128 v41, v[118:121] offset:9216
	s_waitcnt vmcnt(10)
	ds_write_b128 v41, v[126:129] offset:13824
	s_waitcnt vmcnt(7)
	ds_write_b128 v41, v[134:137] offset:18432
	s_waitcnt vmcnt(6)
	ds_write_b128 v41, v[142:145] offset:23040
	s_waitcnt vmcnt(3)
	ds_write_b128 v41, v[146:149] offset:27648
	s_waitcnt vmcnt(2)
	ds_write_b128 v41, v[154:157] offset:32256
	ds_read_b128 v[170:173], v104 offset:46080
	ds_read_b128 v[88:91], v104 offset:48384
	ds_read_b128 v[84:87], v104 offset:50688
	ds_read_b128 v[80:83], v104 offset:52992
	s_waitcnt lgkmcnt(14)
	v_mfma_f32_16x16x32_f16 a[140:143], v[36:39], v[56:59], a[140:143]
	v_mfma_f32_16x16x32_f16 a[136:139], v[32:35], v[56:59], a[136:139]
	v_mfma_f32_16x16x32_f16 a[128:131], v[24:27], v[56:59], a[128:131]
	v_mfma_f32_16x16x32_f16 a[120:123], v[16:19], v[56:59], a[120:123]
	v_mfma_f32_16x16x32_f16 a[156:159], v[36:39], v[44:47], a[156:159]
	v_mfma_f32_16x16x32_f16 a[152:155], v[32:35], v[44:47], a[152:155]
	v_mfma_f32_16x16x32_f16 a[148:151], v[24:27], v[44:47], a[148:151]
	v_mfma_f32_16x16x32_f16 a[144:147], v[16:19], v[44:47], a[144:147]
	v_mfma_f32_16x16x32_f16 a[108:111], v[36:39], v[28:31], a[108:111]
	v_mfma_f32_16x16x32_f16 a[104:107], v[32:35], v[28:31], a[104:107]
	v_mfma_f32_16x16x32_f16 a[100:103], v[24:27], v[28:31], a[100:103]
	v_mfma_f32_16x16x32_f16 a[96:99], v[16:19], v[28:31], a[96:99]
	v_mfma_f32_16x16x32_f16 a[76:79], v[36:39], v[12:15], a[76:79]
	v_mfma_f32_16x16x32_f16 a[72:75], v[32:35], v[12:15], a[72:75]
	v_mfma_f32_16x16x32_f16 a[68:71], v[24:27], v[12:15], a[68:71]
	v_mfma_f32_16x16x32_f16 a[64:67], v[16:19], v[12:15], a[64:67]
	v_mfma_f32_16x16x32_f16 a[60:63], v[36:39], v[4:7], a[60:63]
	v_mfma_f32_16x16x32_f16 a[56:59], v[32:35], v[4:7], a[56:59]
	v_mfma_f32_16x16x32_f16 a[52:55], v[24:27], v[4:7], a[52:55]
	v_mfma_f32_16x16x32_f16 a[48:51], v[16:19], v[4:7], a[48:51]
	v_mfma_f32_16x16x32_f16 a[44:47], v[36:39], v[0:3], a[44:47]
	v_mfma_f32_16x16x32_f16 a[40:43], v[32:35], v[0:3], a[40:43]
	v_mfma_f32_16x16x32_f16 a[36:39], v[24:27], v[0:3], a[36:39]
	v_mfma_f32_16x16x32_f16 a[32:35], v[16:19], v[0:3], a[32:35]
	s_waitcnt lgkmcnt(13)
	v_mfma_f32_16x16x32_f16 a[28:31], v[36:39], v[8:11], a[28:31]
	v_mfma_f32_16x16x32_f16 a[24:27], v[32:35], v[8:11], a[24:27]
	v_mfma_f32_16x16x32_f16 a[20:23], v[24:27], v[8:11], a[20:23]
	v_mfma_f32_16x16x32_f16 a[16:19], v[16:19], v[8:11], a[16:19]
	s_waitcnt lgkmcnt(12)
	v_mfma_f32_16x16x32_f16 a[12:15], v[36:39], v[20:23], a[12:15]
	v_mfma_f32_16x16x32_f16 a[8:11], v[32:35], v[20:23], a[8:11]
	v_mfma_f32_16x16x32_f16 a[4:7], v[24:27], v[20:23], a[4:7]
	v_mfma_f32_16x16x32_f16 a[0:3], v[16:19], v[20:23], a[0:3]
	v_add_u32_e32 v16, v40, v99
	s_waitcnt vmcnt(7)
	ds_write_b128 v41, v[114:117] offset:36864
	s_waitcnt vmcnt(6)
	ds_write_b128 v41, v[122:125] offset:41472
	s_waitcnt vmcnt(5)
	ds_write_b128 v41, v[130:133] offset:46080
	s_waitcnt vmcnt(4)
	ds_write_b128 v41, v[138:141] offset:50688
	s_waitcnt vmcnt(3)
	ds_write_b128 v41, v[150:153] offset:55296
	s_waitcnt vmcnt(2)
	ds_write_b128 v41, v[158:161] offset:59904
	s_waitcnt vmcnt(1)
	ds_write_b128 v41, v[162:165] offset:64512
	s_waitcnt vmcnt(0)
	ds_write_b128 v16, v[166:169]
	ds_read_b128 v[60:63], v64 offset:64
	ds_read_b128 v[52:55], v64 offset:2368
	ds_read_b128 v[48:51], v64 offset:4672
	ds_read_b128 v[40:43], v64 offset:6976
	ds_read_b128 v[36:39], v64 offset:9280
	ds_read_b128 v[32:35], v64 offset:11584
	ds_read_b128 v[24:27], v64 offset:13888
	ds_read_b128 v[16:19], v64 offset:16192
	ds_read_b128 v[64:67], v104 offset:36928
	ds_read_b128 v[68:71], v104 offset:39232
	ds_read_b128 v[72:75], v104 offset:41536
	ds_read_b128 v[76:79], v104 offset:43840
	s_cmp_gt_u32 s14, 5
	s_cbranch_scc1 .Lgw12_nl
; #define MMA_BLK(afx, bfx, nh_) _Pragma("unroll") for (int mi = 0; mi < 8; ++mi) _Pragma("unroll") for (int ni = 0; ni < 4; ++ni) mfma16_acc(acc[mi][(nh_) * 4 + ni], bfx[ni], afx[mi])
; template <class Epi>
; __device__ __forceinline__ void gemm_run(const GemmArgs g, Epi epi, char* smem) {
;     ...
;       MMA_BLK(afA, bfB, 1);
;       __builtin_amdgcn_sched_barrier(0);
;       if (kt + 2 < nk) {
;         const int ko = (kt + 2) * 64;
; #pragma unroll
;         for (int i = 0; i < 8; ++i) { ra[i] = __builtin_amdgcn_raw_buffer_load_b128(Ars, aoff, i * astep + ko * 2, 0); rb[i] = __builtin_amdgcn_raw_buffer_load_b128(Brs, boff, i * bstep + ko * 2, 0); }
;       }
	s_waitcnt lgkmcnt(14)
	v_mfma_f32_16x16x32_f16 a[252:255], v[170:173], v[56:59], a[252:255]
	v_mfma_f32_16x16x32_f16 a[248:251], v[88:91], v[56:59], a[248:251]
	v_mfma_f32_16x16x32_f16 a[244:247], v[84:87], v[56:59], a[244:247]
	s_add_i32 s77, s19, 0xfffc8000
	v_mfma_f32_16x16x32_f16 a[240:243], v[80:83], v[56:59], a[240:243]
	s_mov_b32 s14, s10
	v_mfma_f32_16x16x32_f16 a[236:239], v[170:173], v[44:47], a[236:239]
	s_mov_b32 s15, s11
	v_mfma_f32_16x16x32_f16 a[232:235], v[88:91], v[44:47], a[232:235]
	s_add_i32 s82, s19, 0xfffd0000
	v_mfma_f32_16x16x32_f16 a[228:231], v[84:87], v[44:47], a[228:231]
	buffer_load_dwordx4 v[106:109], v92, s[8:11], s77 offen
	v_mfma_f32_16x16x32_f16 a[224:227], v[80:83], v[44:47], a[224:227]
	buffer_load_dwordx4 v[110:113], v92, s[8:11], s82 offen
	v_mfma_f32_16x16x32_f16 a[220:223], v[170:173], v[28:31], a[220:223]
	buffer_load_dwordx4 v[114:117], v92, s[12:15], s77 offen
	v_mfma_f32_16x16x32_f16 a[216:219], v[88:91], v[28:31], a[216:219]
	buffer_load_dwordx4 v[122:125], v92, s[12:15], s82 offen
	v_mfma_f32_16x16x32_f16 a[212:215], v[84:87], v[28:31], a[212:215]
	s_add_i32 s77, s19, 0xfffd8000
	v_mfma_f32_16x16x32_f16 a[208:211], v[80:83], v[28:31], a[208:211]
	s_add_i32 s82, s19, 0xfffe0000
	v_mfma_f32_16x16x32_f16 a[204:207], v[170:173], v[12:15], a[204:207]
	buffer_load_dwordx4 v[118:121], v92, s[8:11], s77 offen
	v_mfma_f32_16x16x32_f16 a[200:203], v[88:91], v[12:15], a[200:203]
	buffer_load_dwordx4 v[126:129], v92, s[8:11], s82 offen
	v_mfma_f32_16x16x32_f16 a[196:199], v[84:87], v[12:15], a[196:199]
	buffer_load_dwordx4 v[130:133], v92, s[12:15], s77 offen
	v_mfma_f32_16x16x32_f16 a[192:195], v[80:83], v[12:15], a[192:195]
	buffer_load_dwordx4 v[138:141], v92, s[12:15], s82 offen
	v_mfma_f32_16x16x32_f16 a[188:191], v[170:173], v[4:7], a[188:191]
	s_add_i32 s77, s19, 0xfffe8000
	v_mfma_f32_16x16x32_f16 a[184:187], v[88:91], v[4:7], a[184:187]
	s_add_i32 s82, s19, 0xffff0000
	v_mfma_f32_16x16x32_f16 a[180:183], v[84:87], v[4:7], a[180:183]
	buffer_load_dwordx4 v[134:137], v92, s[8:11], s77 offen
	v_mfma_f32_16x16x32_f16 a[176:179], v[80:83], v[4:7], a[176:179]
	buffer_load_dwordx4 v[142:145], v92, s[8:11], s82 offen
	v_mfma_f32_16x16x32_f16 a[172:175], v[170:173], v[0:3], a[172:175]
	buffer_load_dwordx4 v[150:153], v92, s[12:15], s77 offen
	v_mfma_f32_16x16x32_f16 a[168:171], v[88:91], v[0:3], a[168:171]
	buffer_load_dwordx4 v[158:161], v92, s[12:15], s82 offen
	v_mfma_f32_16x16x32_f16 a[164:167], v[84:87], v[0:3], a[164:167]
	s_add_i32 s77, s19, 0xffff8000
	v_mfma_f32_16x16x32_f16 a[160:163], v[80:83], v[0:3], a[160:163]
	buffer_load_dwordx4 v[146:149], v92, s[8:11], s77 offen
	v_mfma_f32_16x16x32_f16 a[132:135], v[170:173], v[8:11], a[132:135]
	buffer_load_dwordx4 v[154:157], v92, s[8:11], s19 offen
	v_mfma_f32_16x16x32_f16 a[124:127], v[88:91], v[8:11], a[124:127]
	buffer_load_dwordx4 v[162:165], v92, s[12:15], s77 offen
	v_mfma_f32_16x16x32_f16 a[116:119], v[84:87], v[8:11], a[116:119]
	buffer_load_dwordx4 v[166:169], v92, s[12:15], s19 offen
	v_mfma_f32_16x16x32_f16 a[112:115], v[80:83], v[8:11], a[112:115]
	v_mfma_f32_16x16x32_f16 a[92:95], v[170:173], v[20:23], a[92:95]
	v_mfma_f32_16x16x32_f16 a[88:91], v[88:91], v[20:23], a[88:91]
	v_mfma_f32_16x16x32_f16 a[84:87], v[84:87], v[20:23], a[84:87]
	v_mfma_f32_16x16x32_f16 a[80:83], v[80:83], v[20:23], a[80:83]
	s_branch .LBB0_1622
.Lgw12_nl:
	s_waitcnt lgkmcnt(14)
	v_mfma_f32_16x16x32_f16 a[252:255], v[170:173], v[56:59], a[252:255]
	v_mfma_f32_16x16x32_f16 a[248:251], v[88:91], v[56:59], a[248:251]
	v_mfma_f32_16x16x32_f16 a[244:247], v[84:87], v[56:59], a[244:247]
	v_mfma_f32_16x16x32_f16 a[240:243], v[80:83], v[56:59], a[240:243]
	v_mfma_f32_16x16x32_f16 a[236:239], v[170:173], v[44:47], a[236:239]
	v_mfma_f32_16x16x32_f16 a[232:235], v[88:91], v[44:47], a[232:235]
	v_mfma_f32_16x16x32_f16 a[228:231], v[84:87], v[44:47], a[228:231]
	v_mfma_f32_16x16x32_f16 a[224:227], v[80:83], v[44:47], a[224:227]
	v_mfma_f32_16x16x32_f16 a[220:223], v[170:173], v[28:31], a[220:223]
	v_mfma_f32_16x16x32_f16 a[216:219], v[88:91], v[28:31], a[216:219]
	v_mfma_f32_16x16x32_f16 a[212:215], v[84:87], v[28:31], a[212:215]
	v_mfma_f32_16x16x32_f16 a[208:211], v[80:83], v[28:31], a[208:211]
	v_mfma_f32_16x16x32_f16 a[204:207], v[170:173], v[12:15], a[204:207]
	v_mfma_f32_16x16x32_f16 a[200:203], v[88:91], v[12:15], a[200:203]
	v_mfma_f32_16x16x32_f16 a[196:199], v[84:87], v[12:15], a[196:199]
	v_mfma_f32_16x16x32_f16 a[192:195], v[80:83], v[12:15], a[192:195]
	v_mfma_f32_16x16x32_f16 a[188:191], v[170:173], v[4:7], a[188:191]
	v_mfma_f32_16x16x32_f16 a[184:187], v[88:91], v[4:7], a[184:187]
	v_mfma_f32_16x16x32_f16 a[180:183], v[84:87], v[4:7], a[180:183]
	v_mfma_f32_16x16x32_f16 a[176:179], v[80:83], v[4:7], a[176:179]
	v_mfma_f32_16x16x32_f16 a[172:175], v[170:173], v[0:3], a[172:175]
	v_mfma_f32_16x16x32_f16 a[168:171], v[88:91], v[0:3], a[168:171]
	v_mfma_f32_16x16x32_f16 a[164:167], v[84:87], v[0:3], a[164:167]
	v_mfma_f32_16x16x32_f16 a[160:163], v[80:83], v[0:3], a[160:163]
	v_mfma_f32_16x16x32_f16 a[132:135], v[170:173], v[8:11], a[132:135]
	v_mfma_f32_16x16x32_f16 a[124:127], v[88:91], v[8:11], a[124:127]
	v_mfma_f32_16x16x32_f16 a[116:119], v[84:87], v[8:11], a[116:119]
	v_mfma_f32_16x16x32_f16 a[112:115], v[80:83], v[8:11], a[112:115]
	v_mfma_f32_16x16x32_f16 a[92:95], v[170:173], v[20:23], a[92:95]
	v_mfma_f32_16x16x32_f16 a[88:91], v[88:91], v[20:23], a[88:91]
	v_mfma_f32_16x16x32_f16 a[84:87], v[84:87], v[20:23], a[84:87]
	v_mfma_f32_16x16x32_f16 a[80:83], v[80:83], v[20:23], a[80:83]
	s_branch .LBB0_1622

; #define LD_AF(dst, ks_) _Pragma("unroll") for (int i = 0; i < 8; ++i) dst[i] = *(const h8*)(sA + i * 16 * G_LD + (ks_) * 32)
; #define LD_BF(dst, ks_, nh_) _Pragma("unroll") for (int i = 0; i < 4; ++i) dst[i] = *(const h8*)(sB + ((nh_) * 4 + i) * 16 * G_LD + (ks_) * 32)
; #define MMA_BLK(afx, bfx, nh_) _Pragma("unroll") for (int mi = 0; mi < 8; ++mi) _Pragma("unroll") for (int ni = 0; ni < 4; ++ni) mfma16_acc(acc[mi][(nh_) * 4 + ni], bfx[ni], afx[mi])
; template <class Epi>
; __device__ __forceinline__ void gemm_run(const GemmArgs g, Epi epi, char* smem) {
;     ...
;       const hf* sA = sbase + (kt & 1) * G_STAGE + (wm * 128 + fr) * G_LD + fqs;
;       const hf* sB = sbase + (kt & 1) * G_STAGE + (256 + wn * 128 + fr) * G_LD + fqs;
;       hf* st = sbase + ((kt + 1) & 1) * G_STAGE;
;       h8 afA[8], afB[8], bfA[4], bfB[4];
;     ...
;       LD_AF(afA, 0); LD_BF(bfA, 0, 0);
;       if (kt + 1 < nk) {
; #pragma unroll
;         for (int i = 0; i < 8; ++i) *(u4*)(st + (lr + 32 * i) * G_LD + lcw) = ra[i];
;       }
;       __builtin_amdgcn_sched_barrier(0);
;       LD_BF(bfB, 0, 1);
;       MMA_BLK(afA, bfA, 0);
;       __builtin_amdgcn_sched_barrier(0);
;       if (kt + 1 < nk) {
; #pragma unroll
;         for (int i = 0; i < 8; ++i) *(u4*)(st + (256 + lr + 32 * i) * G_LD + lcw) = rb[i];
;       }
;       LD_AF(afB, 1); LD_BF(bfA, 1, 0);
.LBB0_1631:
	s_bitcmp1_b32 s15, 0
	s_cselect_b32 s11, 0x12000, 0
	s_add_i32 s11, s11, 16
	v_add3_u32 v104, s11, v96, v103
	v_add3_u32 v64, s11, v95, v103
	ds_read_b128 v[36:39], v104 offset:36864
	ds_read_b128 v[56:59], v64
	ds_read_b128 v[32:35], v104 offset:39168
	ds_read_b128 v[24:27], v104 offset:41472
	ds_read_b128 v[16:19], v104 offset:43776
	ds_read_b128 v[44:47], v64 offset:2304
	ds_read_b128 v[28:31], v64 offset:4608
	ds_read_b128 v[12:15], v64 offset:6912
	ds_read_b128 v[4:7], v64 offset:9216
	ds_read_b128 v[0:3], v64 offset:11520
	ds_read_b128 v[8:11], v64 offset:13824
	ds_read_b128 v[20:23], v64 offset:16128
	s_mov_b32 s10, s15
	s_add_i32 s15, s15, 1
	s_bitcmp1_b32 s15, 0
	s_cselect_b32 s16, 0x12000, 0
	v_add_u32_e32 v40, s16, v93
	v_add_u32_e32 v41, v40, v98
	s_waitcnt vmcnt(15)
	ds_write_b128 v41, v[106:109]
	s_waitcnt vmcnt(14)
	ds_write_b128 v41, v[110:113] offset:4608
	s_waitcnt vmcnt(11)
	ds_write_b128 v41, v[118:121] offset:9216
	s_waitcnt vmcnt(10)
	ds_write_b128 v41, v[126:129] offset:13824
	s_waitcnt vmcnt(7)
	ds_write_b128 v41, v[134:137] offset:18432
	s_waitcnt vmcnt(6)
	ds_write_b128 v41, v[142:145] offset:23040
	s_waitcnt vmcnt(3)
	ds_write_b128 v41, v[146:149] offset:27648
	s_waitcnt vmcnt(2)
	ds_write_b128 v41, v[154:157] offset:32256
	ds_read_b128 v[170:173], v104 offset:46080
	ds_read_b128 v[88:91], v104 offset:48384
	ds_read_b128 v[84:87], v104 offset:50688
	ds_read_b128 v[80:83], v104 offset:52992
	s_waitcnt lgkmcnt(14)
	v_mfma_f32_16x16x32_f16 a[252:255], v[36:39], v[56:59], a[252:255]
	v_mfma_f32_16x16x32_f16 a[236:239], v[32:35], v[56:59], a[236:239]
	v_mfma_f32_16x16x32_f16 a[228:231], v[24:27], v[56:59], a[228:231]
	v_mfma_f32_16x16x32_f16 a[224:227], v[16:19], v[56:59], a[224:227]
	v_mfma_f32_16x16x32_f16 a[212:215], v[36:39], v[44:47], a[212:215]
	v_mfma_f32_16x16x32_f16 a[204:207], v[32:35], v[44:47], a[204:207]
	v_mfma_f32_16x16x32_f16 a[196:199], v[24:27], v[44:47], a[196:199]
	v_mfma_f32_16x16x32_f16 a[192:195], v[16:19], v[44:47], a[192:195]
	v_mfma_f32_16x16x32_f16 a[180:183], v[36:39], v[28:31], a[180:183]
	v_mfma_f32_16x16x32_f16 a[172:175], v[32:35], v[28:31], a[172:175]
	v_mfma_f32_16x16x32_f16 a[164:167], v[24:27], v[28:31], a[164:167]
	v_mfma_f32_16x16x32_f16 a[160:163], v[16:19], v[28:31], a[160:163]
	v_mfma_f32_16x16x32_f16 a[148:151], v[36:39], v[12:15], a[148:151]
	v_mfma_f32_16x16x32_f16 a[140:143], v[32:35], v[12:15], a[140:143]
	v_mfma_f32_16x16x32_f16 a[132:135], v[24:27], v[12:15], a[132:135]
	v_mfma_f32_16x16x32_f16 a[128:131], v[16:19], v[12:15], a[128:131]
	v_mfma_f32_16x16x32_f16 a[116:119], v[36:39], v[4:7], a[116:119]
	v_mfma_f32_16x16x32_f16 a[108:111], v[32:35], v[4:7], a[108:111]
	v_mfma_f32_16x16x32_f16 a[100:103], v[24:27], v[4:7], a[100:103]
	v_mfma_f32_16x16x32_f16 a[96:99], v[16:19], v[4:7], a[96:99]
	v_mfma_f32_16x16x32_f16 a[84:87], v[36:39], v[0:3], a[84:87]
	v_mfma_f32_16x16x32_f16 a[76:79], v[32:35], v[0:3], a[76:79]
	v_mfma_f32_16x16x32_f16 a[68:71], v[24:27], v[0:3], a[68:71]
	v_mfma_f32_16x16x32_f16 a[64:67], v[16:19], v[0:3], a[64:67]
	s_waitcnt lgkmcnt(13)
	v_mfma_f32_16x16x32_f16 a[52:55], v[36:39], v[8:11], a[52:55]
	v_mfma_f32_16x16x32_f16 a[44:47], v[32:35], v[8:11], a[44:47]
	v_mfma_f32_16x16x32_f16 a[36:39], v[24:27], v[8:11], a[36:39]
	v_mfma_f32_16x16x32_f16 a[32:35], v[16:19], v[8:11], a[32:35]
	s_waitcnt lgkmcnt(12)
	v_mfma_f32_16x16x32_f16 a[24:27], v[36:39], v[20:23], a[24:27]
	v_mfma_f32_16x16x32_f16 a[16:19], v[32:35], v[20:23], a[16:19]
	v_mfma_f32_16x16x32_f16 a[8:11], v[24:27], v[20:23], a[8:11]
	v_mfma_f32_16x16x32_f16 a[0:3], v[16:19], v[20:23], a[0:3]
	v_add_u32_e32 v16, v40, v99
	s_waitcnt vmcnt(7)
	ds_write_b128 v41, v[114:117] offset:36864
	s_waitcnt vmcnt(6)
	ds_write_b128 v41, v[122:125] offset:41472
	s_waitcnt vmcnt(5)
	ds_write_b128 v41, v[130:133] offset:46080
	s_waitcnt vmcnt(4)
	ds_write_b128 v41, v[138:141] offset:50688
	s_waitcnt vmcnt(3)
	ds_write_b128 v41, v[150:153] offset:55296
	s_waitcnt vmcnt(2)
	ds_write_b128 v41, v[158:161] offset:59904
	s_waitcnt vmcnt(1)
	ds_write_b128 v41, v[162:165] offset:64512
	s_waitcnt vmcnt(0)
	ds_write_b128 v16, v[166:169]
	ds_read_b128 v[60:63], v64 offset:64
	ds_read_b128 v[52:55], v64 offset:2368
	ds_read_b128 v[48:51], v64 offset:4672
	ds_read_b128 v[40:43], v64 offset:6976
	ds_read_b128 v[36:39], v64 offset:9280
	ds_read_b128 v[32:35], v64 offset:11584
	ds_read_b128 v[24:27], v64 offset:13888
	ds_read_b128 v[16:19], v64 offset:16192
	ds_read_b128 v[64:67], v104 offset:36928
	ds_read_b128 v[68:71], v104 offset:39232
	ds_read_b128 v[72:75], v104 offset:41536
	ds_read_b128 v[76:79], v104 offset:43840
	s_cmp_gt_u32 s10, 1
	s_cbranch_scc1 .Lgw13_nl
; #define MMA_BLK(afx, bfx, nh_) _Pragma("unroll") for (int mi = 0; mi < 8; ++mi) _Pragma("unroll") for (int ni = 0; ni < 4; ++ni) mfma16_acc(acc[mi][(nh_) * 4 + ni], bfx[ni], afx[mi])
; template <class Epi>
; __device__ __forceinline__ void gemm_run(const GemmArgs g, Epi epi, char* smem) {
;     ...
;       MMA_BLK(afA, bfB, 1);
;       __builtin_amdgcn_sched_barrier(0);
;       if (kt + 2 < nk) {
;         const int ko = (kt + 2) * 64;
; #pragma unroll
;         for (int i = 0; i < 8; ++i) { ra[i] = __builtin_amdgcn_raw_buffer_load_b128(Ars, aoff, i * astep + ko * 2, 0); rb[i] = __builtin_amdgcn_raw_buffer_load_b128(Brs, boff, i * bstep + ko * 2, 0); }
;       }
	s_waitcnt lgkmcnt(14)
	v_mfma_f32_16x16x32_f16 a[248:251], v[170:173], v[56:59], a[248:251]
	v_mfma_f32_16x16x32_f16 a[244:247], v[88:91], v[56:59], a[244:247]
	v_mfma_f32_16x16x32_f16 a[240:243], v[84:87], v[56:59], a[240:243]
	s_add_i32 s16, s13, 0xfffe4000
	v_mfma_f32_16x16x32_f16 a[232:235], v[80:83], v[56:59], a[232:235]
	s_mov_b32 s10, s22
	v_mfma_f32_16x16x32_f16 a[220:223], v[170:173], v[44:47], a[220:223]
	s_mov_b32 s11, s23
	v_mfma_f32_16x16x32_f16 a[216:219], v[88:91], v[44:47], a[216:219]
	s_add_i32 s17, s13, 0xfffe8000
	v_mfma_f32_16x16x32_f16 a[208:211], v[84:87], v[44:47], a[208:211]
	buffer_load_dwordx4 v[106:109], v92, s[20:23], s16 offen
	v_mfma_f32_16x16x32_f16 a[200:203], v[80:83], v[44:47], a[200:203]
	buffer_load_dwordx4 v[110:113], v92, s[20:23], s17 offen
	v_mfma_f32_16x16x32_f16 a[188:191], v[170:173], v[28:31], a[188:191]
	buffer_load_dwordx4 v[114:117], v92, s[8:11], s16 offen
	v_mfma_f32_16x16x32_f16 a[184:187], v[88:91], v[28:31], a[184:187]
	buffer_load_dwordx4 v[122:125], v92, s[8:11], s17 offen
	v_mfma_f32_16x16x32_f16 a[176:179], v[84:87], v[28:31], a[176:179]
	s_add_i32 s16, s13, 0xfffec000
	v_mfma_f32_16x16x32_f16 a[168:171], v[80:83], v[28:31], a[168:171]
	s_add_i32 s17, s13, 0xffff0000
	v_mfma_f32_16x16x32_f16 a[156:159], v[170:173], v[12:15], a[156:159]
	buffer_load_dwordx4 v[118:121], v92, s[20:23], s16 offen
	v_mfma_f32_16x16x32_f16 a[152:155], v[88:91], v[12:15], a[152:155]
	buffer_load_dwordx4 v[126:129], v92, s[20:23], s17 offen
	v_mfma_f32_16x16x32_f16 a[144:147], v[84:87], v[12:15], a[144:147]
	buffer_load_dwordx4 v[130:133], v92, s[8:11], s16 offen
	v_mfma_f32_16x16x32_f16 a[136:139], v[80:83], v[12:15], a[136:139]
	buffer_load_dwordx4 v[138:141], v92, s[8:11], s17 offen
	v_mfma_f32_16x16x32_f16 a[124:127], v[170:173], v[4:7], a[124:127]
	s_add_i32 s16, s13, 0xffff4000
	v_mfma_f32_16x16x32_f16 a[120:123], v[88:91], v[4:7], a[120:123]
	s_add_i32 s17, s13, 0xffff8000
	v_mfma_f32_16x16x32_f16 a[112:115], v[84:87], v[4:7], a[112:115]
	buffer_load_dwordx4 v[134:137], v92, s[20:23], s16 offen
	v_mfma_f32_16x16x32_f16 a[104:107], v[80:83], v[4:7], a[104:107]
	buffer_load_dwordx4 v[142:145], v92, s[20:23], s17 offen
	v_mfma_f32_16x16x32_f16 a[92:95], v[170:173], v[0:3], a[92:95]
	buffer_load_dwordx4 v[150:153], v92, s[8:11], s16 offen
	v_mfma_f32_16x16x32_f16 a[88:91], v[88:91], v[0:3], a[88:91]
	buffer_load_dwordx4 v[158:161], v92, s[8:11], s17 offen
	v_mfma_f32_16x16x32_f16 a[80:83], v[84:87], v[0:3], a[80:83]
	s_add_i32 s16, s13, 0xffffc000
	v_mfma_f32_16x16x32_f16 a[72:75], v[80:83], v[0:3], a[72:75]
	buffer_load_dwordx4 v[146:149], v92, s[20:23], s16 offen
	v_mfma_f32_16x16x32_f16 a[60:63], v[170:173], v[8:11], a[60:63]
	buffer_load_dwordx4 v[154:157], v92, s[20:23], s13 offen
	v_mfma_f32_16x16x32_f16 a[56:59], v[88:91], v[8:11], a[56:59]
	buffer_load_dwordx4 v[162:165], v92, s[8:11], s16 offen
	v_mfma_f32_16x16x32_f16 a[48:51], v[84:87], v[8:11], a[48:51]
	buffer_load_dwordx4 v[166:169], v92, s[8:11], s13 offen
	v_mfma_f32_16x16x32_f16 a[40:43], v[80:83], v[8:11], a[40:43]
	v_mfma_f32_16x16x32_f16 a[28:31], v[170:173], v[20:23], a[28:31]
	v_mfma_f32_16x16x32_f16 a[20:23], v[88:91], v[20:23], a[20:23]
	v_mfma_f32_16x16x32_f16 a[12:15], v[84:87], v[20:23], a[12:15]
	v_mfma_f32_16x16x32_f16 a[4:7], v[80:83], v[20:23], a[4:7]
	s_branch .LBB0_1630
.Lgw13_nl:
	s_waitcnt lgkmcnt(14)
	v_mfma_f32_16x16x32_f16 a[248:251], v[170:173], v[56:59], a[248:251]
	v_mfma_f32_16x16x32_f16 a[244:247], v[88:91], v[56:59], a[244:247]
	v_mfma_f32_16x16x32_f16 a[240:243], v[84:87], v[56:59], a[240:243]
	v_mfma_f32_16x16x32_f16 a[232:235], v[80:83], v[56:59], a[232:235]
	v_mfma_f32_16x16x32_f16 a[220:223], v[170:173], v[44:47], a[220:223]
	v_mfma_f32_16x16x32_f16 a[216:219], v[88:91], v[44:47], a[216:219]
	v_mfma_f32_16x16x32_f16 a[208:211], v[84:87], v[44:47], a[208:211]
	v_mfma_f32_16x16x32_f16 a[200:203], v[80:83], v[44:47], a[200:203]
	v_mfma_f32_16x16x32_f16 a[188:191], v[170:173], v[28:31], a[188:191]
	v_mfma_f32_16x16x32_f16 a[184:187], v[88:91], v[28:31], a[184:187]
	v_mfma_f32_16x16x32_f16 a[176:179], v[84:87], v[28:31], a[176:179]
	v_mfma_f32_16x16x32_f16 a[168:171], v[80:83], v[28:31], a[168:171]
	v_mfma_f32_16x16x32_f16 a[156:159], v[170:173], v[12:15], a[156:159]
	v_mfma_f32_16x16x32_f16 a[152:155], v[88:91], v[12:15], a[152:155]
	v_mfma_f32_16x16x32_f16 a[144:147], v[84:87], v[12:15], a[144:147]
	v_mfma_f32_16x16x32_f16 a[136:139], v[80:83], v[12:15], a[136:139]
	v_mfma_f32_16x16x32_f16 a[124:127], v[170:173], v[4:7], a[124:127]
	v_mfma_f32_16x16x32_f16 a[120:123], v[88:91], v[4:7], a[120:123]
	v_mfma_f32_16x16x32_f16 a[112:115], v[84:87], v[4:7], a[112:115]
	v_mfma_f32_16x16x32_f16 a[104:107], v[80:83], v[4:7], a[104:107]
	v_mfma_f32_16x16x32_f16 a[92:95], v[170:173], v[0:3], a[92:95]
	v_mfma_f32_16x16x32_f16 a[88:91], v[88:91], v[0:3], a[88:91]
	v_mfma_f32_16x16x32_f16 a[80:83], v[84:87], v[0:3], a[80:83]
	v_mfma_f32_16x16x32_f16 a[72:75], v[80:83], v[0:3], a[72:75]
	v_mfma_f32_16x16x32_f16 a[60:63], v[170:173], v[8:11], a[60:63]
	v_mfma_f32_16x16x32_f16 a[56:59], v[88:91], v[8:11], a[56:59]
	v_mfma_f32_16x16x32_f16 a[48:51], v[84:87], v[8:11], a[48:51]
	v_mfma_f32_16x16x32_f16 a[40:43], v[80:83], v[8:11], a[40:43]
	v_mfma_f32_16x16x32_f16 a[28:31], v[170:173], v[20:23], a[28:31]
	v_mfma_f32_16x16x32_f16 a[20:23], v[88:91], v[20:23], a[20:23]
	v_mfma_f32_16x16x32_f16 a[12:15], v[84:87], v[20:23], a[12:15]
	v_mfma_f32_16x16x32_f16 a[4:7], v[80:83], v[20:23], a[4:7]
	s_branch .LBB0_1630

; #define LD_AF(dst, ks_) _Pragma("unroll") for (int i = 0; i < 8; ++i) dst[i] = *(const h8*)(sA + i * 16 * G_LD + (ks_) * 32)
; #define LD_BF(dst, ks_, nh_) _Pragma("unroll") for (int i = 0; i < 4; ++i) dst[i] = *(const h8*)(sB + ((nh_) * 4 + i) * 16 * G_LD + (ks_) * 32)
; #define MMA_BLK(afx, bfx, nh_) _Pragma("unroll") for (int mi = 0; mi < 8; ++mi) _Pragma("unroll") for (int ni = 0; ni < 4; ++ni) mfma16_acc(acc[mi][(nh_) * 4 + ni], bfx[ni], afx[mi])
; template <class Epi>
; __device__ __forceinline__ void gemm_run(const GemmArgs g, Epi epi, char* smem) {
;     ...
;       const hf* sA = sbase + (kt & 1) * G_STAGE + (wm * 128 + fr) * G_LD + fqs;
;       const hf* sB = sbase + (kt & 1) * G_STAGE + (256 + wn * 128 + fr) * G_LD + fqs;
;       hf* st = sbase + ((kt + 1) & 1) * G_STAGE;
;       h8 afA[8], afB[8], bfA[4], bfB[4];
;     ...
;       LD_AF(afA, 0); LD_BF(bfA, 0, 0);
;       if (kt + 1 < nk) {
; #pragma unroll
;         for (int i = 0; i < 8; ++i) *(u4*)(st + (lr + 32 * i) * G_LD + lcw) = ra[i];
;       }
;       __builtin_amdgcn_sched_barrier(0);
;       LD_BF(bfB, 0, 1);
;       MMA_BLK(afA, bfA, 0);
;       __builtin_amdgcn_sched_barrier(0);
;       if (kt + 1 < nk) {
; #pragma unroll
;         for (int i = 0; i < 8; ++i) *(u4*)(st + (256 + lr + 32 * i) * G_LD + lcw) = rb[i];
;       }
;       LD_AF(afB, 1); LD_BF(bfA, 1, 0);
.LBB0_2023:
	s_bitcmp1_b32 s23, 0
	s_cselect_b32 s15, 0x12000, 0
	s_add_i32 s15, s15, 16
	v_add3_u32 v92, s15, v132, v139
	v_add3_u32 v64, s15, v131, v139
	ds_read_b128 v[36:39], v92 offset:36864
	ds_read_b128 v[56:59], v64
	ds_read_b128 v[32:35], v92 offset:39168
	ds_read_b128 v[24:27], v92 offset:41472
	ds_read_b128 v[16:19], v92 offset:43776
	ds_read_b128 v[44:47], v64 offset:2304
	ds_read_b128 v[28:31], v64 offset:4608
	ds_read_b128 v[12:15], v64 offset:6912
	ds_read_b128 v[4:7], v64 offset:9216
	ds_read_b128 v[0:3], v64 offset:11520
	ds_read_b128 v[8:11], v64 offset:13824
	ds_read_b128 v[20:23], v64 offset:16128
	s_mov_b32 s14, s23
	s_add_i32 s23, s23, 1
	s_bitcmp1_b32 s23, 0
	s_cselect_b32 s62, 0x12000, 0
	v_add_u32_e32 v40, s62, v129
	v_add_u32_e32 v41, v40, v134
	s_waitcnt vmcnt(15)
	ds_write_b128 v41, v[94:97]
	s_waitcnt vmcnt(14)
	ds_write_b128 v41, v[98:101] offset:4608
	s_waitcnt vmcnt(11)
	ds_write_b128 v41, v[106:109] offset:9216
	s_waitcnt vmcnt(10)
	ds_write_b128 v41, v[114:117] offset:13824
	s_waitcnt vmcnt(7)
	ds_write_b128 v41, v[122:125] offset:18432
	s_waitcnt vmcnt(6)
	ds_write_b128 v41, v[144:147] offset:23040
	s_waitcnt vmcnt(3)
	ds_write_b128 v41, v[148:151] offset:27648
	s_waitcnt vmcnt(2)
	ds_write_b128 v41, v[156:159] offset:32256
	ds_read_b128 v[172:175], v92 offset:46080
	ds_read_b128 v[88:91], v92 offset:48384
	ds_read_b128 v[84:87], v92 offset:50688
	ds_read_b128 v[80:83], v92 offset:52992
	s_waitcnt lgkmcnt(14)
	v_mfma_f32_16x16x32_f16 a[208:211], v[36:39], v[56:59], a[208:211]
	v_mfma_f32_16x16x32_f16 a[200:203], v[32:35], v[56:59], a[200:203]
	v_mfma_f32_16x16x32_f16 a[196:199], v[24:27], v[56:59], a[196:199]
	v_mfma_f32_16x16x32_f16 a[192:195], v[16:19], v[56:59], a[192:195]
	v_mfma_f32_16x16x32_f16 a[188:191], v[36:39], v[44:47], a[188:191]
	v_mfma_f32_16x16x32_f16 a[184:187], v[32:35], v[44:47], a[184:187]
	v_mfma_f32_16x16x32_f16 a[180:183], v[24:27], v[44:47], a[180:183]
	v_mfma_f32_16x16x32_f16 a[176:179], v[16:19], v[44:47], a[176:179]
	v_mfma_f32_16x16x32_f16 a[156:159], v[36:39], v[28:31], a[156:159]
	v_mfma_f32_16x16x32_f16 a[152:155], v[32:35], v[28:31], a[152:155]
	v_mfma_f32_16x16x32_f16 a[148:151], v[24:27], v[28:31], a[148:151]
	v_mfma_f32_16x16x32_f16 a[144:147], v[16:19], v[28:31], a[144:147]
	v_mfma_f32_16x16x32_f16 a[124:127], v[36:39], v[12:15], a[124:127]
	v_mfma_f32_16x16x32_f16 a[120:123], v[32:35], v[12:15], a[120:123]
	v_mfma_f32_16x16x32_f16 a[116:119], v[24:27], v[12:15], a[116:119]
	v_mfma_f32_16x16x32_f16 a[112:115], v[16:19], v[12:15], a[112:115]
	v_mfma_f32_16x16x32_f16 a[92:95], v[36:39], v[4:7], a[92:95]
	v_mfma_f32_16x16x32_f16 a[88:91], v[32:35], v[4:7], a[88:91]
	v_mfma_f32_16x16x32_f16 a[84:87], v[24:27], v[4:7], a[84:87]
	v_mfma_f32_16x16x32_f16 a[80:83], v[16:19], v[4:7], a[80:83]
	v_mfma_f32_16x16x32_f16 a[60:63], v[36:39], v[0:3], a[60:63]
	v_mfma_f32_16x16x32_f16 a[56:59], v[32:35], v[0:3], a[56:59]
	v_mfma_f32_16x16x32_f16 a[52:55], v[24:27], v[0:3], a[52:55]
	v_mfma_f32_16x16x32_f16 a[48:51], v[16:19], v[0:3], a[48:51]
	s_waitcnt lgkmcnt(13)
	v_mfma_f32_16x16x32_f16 a[28:31], v[36:39], v[8:11], a[28:31]
	v_mfma_f32_16x16x32_f16 a[24:27], v[32:35], v[8:11], a[24:27]
	v_mfma_f32_16x16x32_f16 a[20:23], v[24:27], v[8:11], a[20:23]
	v_mfma_f32_16x16x32_f16 a[16:19], v[16:19], v[8:11], a[16:19]
	s_waitcnt lgkmcnt(12)
	v_mfma_f32_16x16x32_f16 a[12:15], v[36:39], v[20:23], a[12:15]
	v_mfma_f32_16x16x32_f16 a[8:11], v[32:35], v[20:23], a[8:11]
	v_mfma_f32_16x16x32_f16 a[4:7], v[24:27], v[20:23], a[4:7]
	v_mfma_f32_16x16x32_f16 a[0:3], v[16:19], v[20:23], a[0:3]
	v_add_u32_e32 v16, v40, v135
	s_waitcnt vmcnt(7)
	ds_write_b128 v41, v[102:105] offset:36864
	s_waitcnt vmcnt(6)
	ds_write_b128 v41, v[110:113] offset:41472
	s_waitcnt vmcnt(5)
	ds_write_b128 v41, v[118:121] offset:46080
	s_waitcnt vmcnt(4)
	ds_write_b128 v41, v[140:143] offset:50688
	s_waitcnt vmcnt(3)
	ds_write_b128 v41, v[152:155] offset:55296
	s_waitcnt vmcnt(2)
	ds_write_b128 v41, v[160:163] offset:59904
	s_waitcnt vmcnt(1)
	ds_write_b128 v41, v[164:167] offset:64512
	s_waitcnt vmcnt(0)
	ds_write_b128 v16, v[168:171]
	ds_read_b128 v[60:63], v64 offset:64
	ds_read_b128 v[52:55], v64 offset:2368
	ds_read_b128 v[48:51], v64 offset:4672
	ds_read_b128 v[40:43], v64 offset:6976
	ds_read_b128 v[36:39], v64 offset:9280
	ds_read_b128 v[32:35], v64 offset:11584
	ds_read_b128 v[24:27], v64 offset:13888
	ds_read_b128 v[16:19], v64 offset:16192
	ds_read_b128 v[64:67], v92 offset:36928
	ds_read_b128 v[68:71], v92 offset:39232
	ds_read_b128 v[72:75], v92 offset:41536
	ds_read_b128 v[76:79], v92 offset:43840
	s_cmp_gt_u32 s14, 29
	s_cbranch_scc1 .Lgw14_nl
; #define MMA_BLK(afx, bfx, nh_) _Pragma("unroll") for (int mi = 0; mi < 8; ++mi) _Pragma("unroll") for (int ni = 0; ni < 4; ++ni) mfma16_acc(acc[mi][(nh_) * 4 + ni], bfx[ni], afx[mi])
; template <class Epi>
; __device__ __forceinline__ void gemm_run(const GemmArgs g, Epi epi, char* smem) {
;     ...
;       MMA_BLK(afA, bfB, 1);
;       __builtin_amdgcn_sched_barrier(0);
;       if (kt + 2 < nk) {
;         const int ko = (kt + 2) * 64;
; #pragma unroll
;         for (int i = 0; i < 8; ++i) { ra[i] = __builtin_amdgcn_raw_buffer_load_b128(Ars, aoff, i * astep + ko * 2, 0); rb[i] = __builtin_amdgcn_raw_buffer_load_b128(Brs, boff, i * bstep + ko * 2, 0); }
;       }
	s_waitcnt lgkmcnt(14)
	v_mfma_f32_16x16x32_f16 a[240:243], v[172:175], v[56:59], a[240:243]
	v_mfma_f32_16x16x32_f16 a[252:255], v[88:91], v[56:59], a[252:255]
	v_mfma_f32_16x16x32_f16 a[248:251], v[84:87], v[56:59], a[248:251]
	s_add_i32 s62, s21, 0xfff20000
	v_mfma_f32_16x16x32_f16 a[244:247], v[80:83], v[56:59], a[244:247]
	s_mov_b32 s14, s10
	v_mfma_f32_16x16x32_f16 a[236:239], v[172:175], v[44:47], a[236:239]
	s_mov_b32 s15, s11
	v_mfma_f32_16x16x32_f16 a[232:235], v[88:91], v[44:47], a[232:235]
	s_add_i32 s63, s21, 0xfff40000
	v_mfma_f32_16x16x32_f16 a[228:231], v[84:87], v[44:47], a[228:231]
	buffer_load_dwordx4 v[94:97], v128, s[8:11], s62 offen
	v_mfma_f32_16x16x32_f16 a[224:227], v[80:83], v[44:47], a[224:227]
	buffer_load_dwordx4 v[98:101], v128, s[8:11], s63 offen
	v_mfma_f32_16x16x32_f16 a[220:223], v[172:175], v[28:31], a[220:223]
	buffer_load_dwordx4 v[102:105], v128, s[12:15], s62 offen
	v_mfma_f32_16x16x32_f16 a[216:219], v[88:91], v[28:31], a[216:219]
	buffer_load_dwordx4 v[110:113], v128, s[12:15], s63 offen
	v_mfma_f32_16x16x32_f16 a[212:215], v[84:87], v[28:31], a[212:215]
	s_add_i32 s62, s21, 0xfff60000
	v_mfma_f32_16x16x32_f16 a[204:207], v[80:83], v[28:31], a[204:207]
	s_add_i32 s63, s21, 0xfff80000
	v_mfma_f32_16x16x32_f16 a[172:175], v[172:175], v[12:15], a[172:175]
	buffer_load_dwordx4 v[106:109], v128, s[8:11], s62 offen
	v_mfma_f32_16x16x32_f16 a[168:171], v[88:91], v[12:15], a[168:171]
	buffer_load_dwordx4 v[114:117], v128, s[8:11], s63 offen
	v_mfma_f32_16x16x32_f16 a[164:167], v[84:87], v[12:15], a[164:167]
	buffer_load_dwordx4 v[118:121], v128, s[12:15], s62 offen
	v_mfma_f32_16x16x32_f16 a[160:163], v[80:83], v[12:15], a[160:163]
	buffer_load_dwordx4 v[140:143], v128, s[12:15], s63 offen
	v_mfma_f32_16x16x32_f16 a[140:143], v[172:175], v[4:7], a[140:143]
	s_add_i32 s62, s21, 0xfffa0000
	v_mfma_f32_16x16x32_f16 a[136:139], v[88:91], v[4:7], a[136:139]
	s_add_i32 s63, s21, 0xfffc0000
	v_mfma_f32_16x16x32_f16 a[132:135], v[84:87], v[4:7], a[132:135]
	buffer_load_dwordx4 v[122:125], v128, s[8:11], s62 offen
	v_mfma_f32_16x16x32_f16 a[128:131], v[80:83], v[4:7], a[128:131]
	buffer_load_dwordx4 v[144:147], v128, s[8:11], s63 offen
	v_mfma_f32_16x16x32_f16 a[108:111], v[172:175], v[0:3], a[108:111]
	buffer_load_dwordx4 v[152:155], v128, s[12:15], s62 offen
	v_mfma_f32_16x16x32_f16 a[104:107], v[88:91], v[0:3], a[104:107]
	buffer_load_dwordx4 v[160:163], v128, s[12:15], s63 offen
	v_mfma_f32_16x16x32_f16 a[100:103], v[84:87], v[0:3], a[100:103]
	s_add_i32 s62, s21, 0xfffe0000
	v_mfma_f32_16x16x32_f16 a[96:99], v[80:83], v[0:3], a[96:99]
	buffer_load_dwordx4 v[148:151], v128, s[8:11], s62 offen
	v_mfma_f32_16x16x32_f16 a[76:79], v[172:175], v[8:11], a[76:79]
	buffer_load_dwordx4 v[156:159], v128, s[8:11], s21 offen
	v_mfma_f32_16x16x32_f16 a[72:75], v[88:91], v[8:11], a[72:75]
	buffer_load_dwordx4 v[164:167], v128, s[12:15], s62 offen
	v_mfma_f32_16x16x32_f16 a[68:71], v[84:87], v[8:11], a[68:71]
	buffer_load_dwordx4 v[168:171], v128, s[12:15], s21 offen
	v_mfma_f32_16x16x32_f16 a[64:67], v[80:83], v[8:11], a[64:67]
	v_mfma_f32_16x16x32_f16 a[44:47], v[172:175], v[20:23], a[44:47]
	v_mfma_f32_16x16x32_f16 a[40:43], v[88:91], v[20:23], a[40:43]
	v_mfma_f32_16x16x32_f16 a[36:39], v[84:87], v[20:23], a[36:39]
	v_mfma_f32_16x16x32_f16 a[32:35], v[80:83], v[20:23], a[32:35]
	s_branch .LBB0_2022
.Lgw14_nl:
	s_waitcnt lgkmcnt(14)
	v_mfma_f32_16x16x32_f16 a[240:243], v[172:175], v[56:59], a[240:243]
	v_mfma_f32_16x16x32_f16 a[252:255], v[88:91], v[56:59], a[252:255]
	v_mfma_f32_16x16x32_f16 a[248:251], v[84:87], v[56:59], a[248:251]
	v_mfma_f32_16x16x32_f16 a[244:247], v[80:83], v[56:59], a[244:247]
	v_mfma_f32_16x16x32_f16 a[236:239], v[172:175], v[44:47], a[236:239]
	v_mfma_f32_16x16x32_f16 a[232:235], v[88:91], v[44:47], a[232:235]
	v_mfma_f32_16x16x32_f16 a[228:231], v[84:87], v[44:47], a[228:231]
	v_mfma_f32_16x16x32_f16 a[224:227], v[80:83], v[44:47], a[224:227]
	v_mfma_f32_16x16x32_f16 a[220:223], v[172:175], v[28:31], a[220:223]
	v_mfma_f32_16x16x32_f16 a[216:219], v[88:91], v[28:31], a[216:219]
	v_mfma_f32_16x16x32_f16 a[212:215], v[84:87], v[28:31], a[212:215]
	v_mfma_f32_16x16x32_f16 a[204:207], v[80:83], v[28:31], a[204:207]
	v_mfma_f32_16x16x32_f16 a[172:175], v[172:175], v[12:15], a[172:175]
	v_mfma_f32_16x16x32_f16 a[168:171], v[88:91], v[12:15], a[168:171]
	v_mfma_f32_16x16x32_f16 a[164:167], v[84:87], v[12:15], a[164:167]
	v_mfma_f32_16x16x32_f16 a[160:163], v[80:83], v[12:15], a[160:163]
	v_mfma_f32_16x16x32_f16 a[140:143], v[172:175], v[4:7], a[140:143]
	v_mfma_f32_16x16x32_f16 a[136:139], v[88:91], v[4:7], a[136:139]
	v_mfma_f32_16x16x32_f16 a[132:135], v[84:87], v[4:7], a[132:135]
	v_mfma_f32_16x16x32_f16 a[128:131], v[80:83], v[4:7], a[128:131]
	v_mfma_f32_16x16x32_f16 a[108:111], v[172:175], v[0:3], a[108:111]
	v_mfma_f32_16x16x32_f16 a[104:107], v[88:91], v[0:3], a[104:107]
	v_mfma_f32_16x16x32_f16 a[100:103], v[84:87], v[0:3], a[100:103]
	v_mfma_f32_16x16x32_f16 a[96:99], v[80:83], v[0:3], a[96:99]
	v_mfma_f32_16x16x32_f16 a[76:79], v[172:175], v[8:11], a[76:79]
	v_mfma_f32_16x16x32_f16 a[72:75], v[88:91], v[8:11], a[72:75]
	v_mfma_f32_16x16x32_f16 a[68:71], v[84:87], v[8:11], a[68:71]
	v_mfma_f32_16x16x32_f16 a[64:67], v[80:83], v[8:11], a[64:67]
	v_mfma_f32_16x16x32_f16 a[44:47], v[172:175], v[20:23], a[44:47]
	v_mfma_f32_16x16x32_f16 a[40:43], v[88:91], v[20:23], a[40:43]
	v_mfma_f32_16x16x32_f16 a[36:39], v[84:87], v[20:23], a[36:39]
	v_mfma_f32_16x16x32_f16 a[32:35], v[80:83], v[20:23], a[32:35]
	s_branch .LBB0_2022

; #define LD_AF(dst, ks_) _Pragma("unroll") for (int i = 0; i < 8; ++i) dst[i] = *(const h8*)(sA + i * 16 * G_LD + (ks_) * 32)
; #define LD_BF(dst, ks_, nh_) _Pragma("unroll") for (int i = 0; i < 4; ++i) dst[i] = *(const h8*)(sB + ((nh_) * 4 + i) * 16 * G_LD + (ks_) * 32)
; #define MMA_BLK(afx, bfx, nh_) _Pragma("unroll") for (int mi = 0; mi < 8; ++mi) _Pragma("unroll") for (int ni = 0; ni < 4; ++ni) mfma16_acc(acc[mi][(nh_) * 4 + ni], bfx[ni], afx[mi])
; template <class Epi>
; __device__ __forceinline__ void gemm_run(const GemmArgs g, Epi epi, char* smem) {
;     ...
;       const hf* sA = sbase + (kt & 1) * G_STAGE + (wm * 128 + fr) * G_LD + fqs;
;       const hf* sB = sbase + (kt & 1) * G_STAGE + (256 + wn * 128 + fr) * G_LD + fqs;
;       hf* st = sbase + ((kt + 1) & 1) * G_STAGE;
;       h8 afA[8], afB[8], bfA[4], bfB[4];
;     ...
;       LD_AF(afA, 0); LD_BF(bfA, 0, 0);
;       if (kt + 1 < nk) {
; #pragma unroll
;         for (int i = 0; i < 8; ++i) *(u4*)(st + (lr + 32 * i) * G_LD + lcw) = ra[i];
;       }
;       __builtin_amdgcn_sched_barrier(0);
;       LD_BF(bfB, 0, 1);
;       MMA_BLK(afA, bfA, 0);
;       __builtin_amdgcn_sched_barrier(0);
;       if (kt + 1 < nk) {
; #pragma unroll
;         for (int i = 0; i < 8; ++i) *(u4*)(st + (256 + lr + 32 * i) * G_LD + lcw) = rb[i];
;       }
;       LD_AF(afB, 1); LD_BF(bfA, 1, 0);
;       MMA_BLK(afA, bfB, 1);
;       __builtin_amdgcn_sched_barrier(0);
;       if (kt + 2 < nk) {
.LBB0_2052:
	s_bitcmp1_b32 s19, 0
	s_cselect_b32 s15, 0x12000, 0
	s_add_i32 s15, s15, 16
	v_add3_u32 v106, s15, v96, v105
	v_add3_u32 v64, s15, v94, v105
	ds_read_b128 v[36:39], v106 offset:36864
	ds_read_b128 v[56:59], v64
	ds_read_b128 v[32:35], v106 offset:39168
	ds_read_b128 v[24:27], v106 offset:41472
	ds_read_b128 v[16:19], v106 offset:43776
	ds_read_b128 v[44:47], v64 offset:2304
	ds_read_b128 v[28:31], v64 offset:4608
	ds_read_b128 v[12:15], v64 offset:6912
	ds_read_b128 v[4:7], v64 offset:9216
	ds_read_b128 v[0:3], v64 offset:11520
	ds_read_b128 v[8:11], v64 offset:13824
	ds_read_b128 v[20:23], v64 offset:16128
	s_mov_b32 s14, s19
	s_add_i32 s19, s19, 1
	s_bitcmp1_b32 s19, 0
	s_cselect_b32 s52, 0x12000, 0
	v_add_u32_e32 v40, s52, v93
	v_add_u32_e32 v41, v40, v98
	s_waitcnt vmcnt(15)
	ds_write_b128 v41, v[108:111]
	s_waitcnt vmcnt(14)
	ds_write_b128 v41, v[112:115] offset:4608
	s_waitcnt vmcnt(11)
	ds_write_b128 v41, v[120:123] offset:9216
	s_waitcnt vmcnt(10)
	ds_write_b128 v41, v[128:131] offset:13824
	s_waitcnt vmcnt(7)
	ds_write_b128 v41, v[136:139] offset:18432
	s_waitcnt vmcnt(6)
	ds_write_b128 v41, v[144:147] offset:23040
	s_waitcnt vmcnt(3)
	ds_write_b128 v41, v[148:151] offset:27648
	s_waitcnt vmcnt(2)
	ds_write_b128 v41, v[156:159] offset:32256
	ds_read_b128 v[172:175], v106 offset:46080
	ds_read_b128 v[88:91], v106 offset:48384
	ds_read_b128 v[84:87], v106 offset:50688
	ds_read_b128 v[80:83], v106 offset:52992
	s_waitcnt lgkmcnt(14)
	v_mfma_f32_16x16x32_f16 a[120:123], v[36:39], v[56:59], a[120:123]
	v_mfma_f32_16x16x32_f16 a[116:119], v[32:35], v[56:59], a[116:119]
	v_mfma_f32_16x16x32_f16 a[112:115], v[24:27], v[56:59], a[112:115]
	v_mfma_f32_16x16x32_f16 a[160:163], v[16:19], v[56:59], a[160:163]
	v_mfma_f32_16x16x32_f16 a[152:155], v[36:39], v[44:47], a[152:155]
	v_mfma_f32_16x16x32_f16 a[148:151], v[32:35], v[44:47], a[148:151]
	v_mfma_f32_16x16x32_f16 a[144:147], v[24:27], v[44:47], a[144:147]
	v_mfma_f32_16x16x32_f16 a[136:139], v[16:19], v[44:47], a[136:139]
	v_mfma_f32_16x16x32_f16 a[108:111], v[36:39], v[28:31], a[108:111]
	v_mfma_f32_16x16x32_f16 a[104:107], v[32:35], v[28:31], a[104:107]
	v_mfma_f32_16x16x32_f16 a[100:103], v[24:27], v[28:31], a[100:103]
	v_mfma_f32_16x16x32_f16 a[92:95], v[16:19], v[28:31], a[92:95]
	v_mfma_f32_16x16x32_f16 a[76:79], v[36:39], v[12:15], a[76:79]
	v_mfma_f32_16x16x32_f16 a[72:75], v[32:35], v[12:15], a[72:75]
	v_mfma_f32_16x16x32_f16 a[68:71], v[24:27], v[12:15], a[68:71]
	v_mfma_f32_16x16x32_f16 a[64:67], v[16:19], v[12:15], a[64:67]
	v_mfma_f32_16x16x32_f16 a[60:63], v[36:39], v[4:7], a[60:63]
	v_mfma_f32_16x16x32_f16 a[56:59], v[32:35], v[4:7], a[56:59]
	v_mfma_f32_16x16x32_f16 a[52:55], v[24:27], v[4:7], a[52:55]
	v_mfma_f32_16x16x32_f16 a[48:51], v[16:19], v[4:7], a[48:51]
	v_mfma_f32_16x16x32_f16 a[44:47], v[36:39], v[0:3], a[44:47]
	v_mfma_f32_16x16x32_f16 a[40:43], v[32:35], v[0:3], a[40:43]
	v_mfma_f32_16x16x32_f16 a[36:39], v[24:27], v[0:3], a[36:39]
	v_mfma_f32_16x16x32_f16 a[32:35], v[16:19], v[0:3], a[32:35]
	s_waitcnt lgkmcnt(13)
	v_mfma_f32_16x16x32_f16 a[28:31], v[36:39], v[8:11], a[28:31]
	v_mfma_f32_16x16x32_f16 a[24:27], v[32:35], v[8:11], a[24:27]
	v_mfma_f32_16x16x32_f16 a[20:23], v[24:27], v[8:11], a[20:23]
	v_mfma_f32_16x16x32_f16 a[16:19], v[16:19], v[8:11], a[16:19]
	s_waitcnt lgkmcnt(12)
	v_mfma_f32_16x16x32_f16 a[12:15], v[36:39], v[20:23], a[12:15]
	v_mfma_f32_16x16x32_f16 a[8:11], v[32:35], v[20:23], a[8:11]
	v_mfma_f32_16x16x32_f16 a[4:7], v[24:27], v[20:23], a[4:7]
	v_mfma_f32_16x16x32_f16 a[0:3], v[16:19], v[20:23], a[0:3]
	v_add_u32_e32 v16, v40, v99
	s_waitcnt vmcnt(7)
	ds_write_b128 v41, v[116:119] offset:36864
	s_waitcnt vmcnt(6)
	ds_write_b128 v41, v[124:127] offset:41472
	s_waitcnt vmcnt(5)
	ds_write_b128 v41, v[132:135] offset:46080
	s_waitcnt vmcnt(4)
	ds_write_b128 v41, v[140:143] offset:50688
	s_waitcnt vmcnt(3)
	ds_write_b128 v41, v[152:155] offset:55296
	s_waitcnt vmcnt(2)
	ds_write_b128 v41, v[160:163] offset:59904
	s_waitcnt vmcnt(1)
	ds_write_b128 v41, v[164:167] offset:64512
	s_waitcnt vmcnt(0)
	ds_write_b128 v16, v[168:171]
	ds_read_b128 v[60:63], v64 offset:64
	ds_read_b128 v[52:55], v64 offset:2368
	ds_read_b128 v[48:51], v64 offset:4672
	ds_read_b128 v[40:43], v64 offset:6976
	ds_read_b128 v[36:39], v64 offset:9280
	ds_read_b128 v[32:35], v64 offset:11584
	ds_read_b128 v[24:27], v64 offset:13888
	ds_read_b128 v[16:19], v64 offset:16192
	ds_read_b128 v[64:67], v106 offset:36928
	ds_read_b128 v[68:71], v106 offset:39232
	ds_read_b128 v[72:75], v106 offset:41536
	ds_read_b128 v[76:79], v106 offset:43840
	s_cmp_gt_u32 s14, 29
	s_cbranch_scc1 .Lgw15_nl
; #define MMA_BLK(afx, bfx, nh_) _Pragma("unroll") for (int mi = 0; mi < 8; ++mi) _Pragma("unroll") for (int ni = 0; ni < 4; ++ni) mfma16_acc(acc[mi][(nh_) * 4 + ni], bfx[ni], afx[mi])
; template <class Epi>
; __device__ __forceinline__ void gemm_run(const GemmArgs g, Epi epi, char* smem) {
;     ...
;       MMA_BLK(afA, bfB, 1);
;       __builtin_amdgcn_sched_barrier(0);
;       if (kt + 2 < nk) {
;         const int ko = (kt + 2) * 64;
; #pragma unroll
;         for (int i = 0; i < 8; ++i) { ra[i] = __builtin_amdgcn_raw_buffer_load_b128(Ars, aoff, i * astep + ko * 2, 0); rb[i] = __builtin_amdgcn_raw_buffer_load_b128(Brs, boff, i * bstep + ko * 2, 0); }
;       }
	s_waitcnt lgkmcnt(14)
	v_mfma_f32_16x16x32_f16 a[252:255], v[172:175], v[56:59], a[252:255]
	v_mfma_f32_16x16x32_f16 a[248:251], v[88:91], v[56:59], a[248:251]
	v_mfma_f32_16x16x32_f16 a[244:247], v[84:87], v[56:59], a[244:247]
	s_add_i32 s52, s17, 0xfff20000
	v_mfma_f32_16x16x32_f16 a[240:243], v[80:83], v[56:59], a[240:243]
	s_mov_b32 s14, s10
	v_mfma_f32_16x16x32_f16 a[236:239], v[172:175], v[44:47], a[236:239]
	s_mov_b32 s15, s11
	v_mfma_f32_16x16x32_f16 a[232:235], v[88:91], v[44:47], a[232:235]
	s_add_i32 s53, s17, 0xfff40000
	v_mfma_f32_16x16x32_f16 a[228:231], v[84:87], v[44:47], a[228:231]
	buffer_load_dwordx4 v[108:111], v92, s[8:11], s52 offen
	v_mfma_f32_16x16x32_f16 a[224:227], v[80:83], v[44:47], a[224:227]
	buffer_load_dwordx4 v[112:115], v92, s[8:11], s53 offen
	v_mfma_f32_16x16x32_f16 a[220:223], v[172:175], v[28:31], a[220:223]
	buffer_load_dwordx4 v[116:119], v92, s[12:15], s52 offen
	v_mfma_f32_16x16x32_f16 a[216:219], v[88:91], v[28:31], a[216:219]
	buffer_load_dwordx4 v[124:127], v92, s[12:15], s53 offen
	v_mfma_f32_16x16x32_f16 a[212:215], v[84:87], v[28:31], a[212:215]
	s_add_i32 s52, s17, 0xfff60000
	v_mfma_f32_16x16x32_f16 a[208:211], v[80:83], v[28:31], a[208:211]
	s_add_i32 s53, s17, 0xfff80000
	v_mfma_f32_16x16x32_f16 a[204:207], v[172:175], v[12:15], a[204:207]
	buffer_load_dwordx4 v[120:123], v92, s[8:11], s52 offen
	v_mfma_f32_16x16x32_f16 a[200:203], v[88:91], v[12:15], a[200:203]
	buffer_load_dwordx4 v[128:131], v92, s[8:11], s53 offen
	v_mfma_f32_16x16x32_f16 a[196:199], v[84:87], v[12:15], a[196:199]
	buffer_load_dwordx4 v[132:135], v92, s[12:15], s52 offen
	v_mfma_f32_16x16x32_f16 a[192:195], v[80:83], v[12:15], a[192:195]
	buffer_load_dwordx4 v[140:143], v92, s[12:15], s53 offen
	v_mfma_f32_16x16x32_f16 a[188:191], v[172:175], v[4:7], a[188:191]
	s_add_i32 s52, s17, 0xfffa0000
	v_mfma_f32_16x16x32_f16 a[184:187], v[88:91], v[4:7], a[184:187]
	s_add_i32 s53, s17, 0xfffc0000
	v_mfma_f32_16x16x32_f16 a[180:183], v[84:87], v[4:7], a[180:183]
	buffer_load_dwordx4 v[136:139], v92, s[8:11], s52 offen
	v_mfma_f32_16x16x32_f16 a[176:179], v[80:83], v[4:7], a[176:179]
	buffer_load_dwordx4 v[144:147], v92, s[8:11], s53 offen
	v_mfma_f32_16x16x32_f16 a[172:175], v[172:175], v[0:3], a[172:175]
	buffer_load_dwordx4 v[152:155], v92, s[12:15], s52 offen
	v_mfma_f32_16x16x32_f16 a[168:171], v[88:91], v[0:3], a[168:171]
	buffer_load_dwordx4 v[160:163], v92, s[12:15], s53 offen
	v_mfma_f32_16x16x32_f16 a[164:167], v[84:87], v[0:3], a[164:167]
	s_add_i32 s52, s17, 0xfffe0000
	v_mfma_f32_16x16x32_f16 a[156:159], v[80:83], v[0:3], a[156:159]
	buffer_load_dwordx4 v[148:151], v92, s[8:11], s52 offen
	v_mfma_f32_16x16x32_f16 a[140:143], v[172:175], v[8:11], a[140:143]
	buffer_load_dwordx4 v[156:159], v92, s[8:11], s17 offen
	v_mfma_f32_16x16x32_f16 a[132:135], v[88:91], v[8:11], a[132:135]
	buffer_load_dwordx4 v[164:167], v92, s[12:15], s52 offen
	v_mfma_f32_16x16x32_f16 a[128:131], v[84:87], v[8:11], a[128:131]
	buffer_load_dwordx4 v[168:171], v92, s[12:15], s17 offen
	v_mfma_f32_16x16x32_f16 a[124:127], v[80:83], v[8:11], a[124:127]
	v_mfma_f32_16x16x32_f16 a[96:99], v[172:175], v[20:23], a[96:99]
	v_mfma_f32_16x16x32_f16 a[88:91], v[88:91], v[20:23], a[88:91]
	v_mfma_f32_16x16x32_f16 a[84:87], v[84:87], v[20:23], a[84:87]
	v_mfma_f32_16x16x32_f16 a[80:83], v[80:83], v[20:23], a[80:83]
	s_branch .LBB0_2051
.Lgw15_nl:
	s_waitcnt lgkmcnt(14)
	v_mfma_f32_16x16x32_f16 a[252:255], v[172:175], v[56:59], a[252:255]
	v_mfma_f32_16x16x32_f16 a[248:251], v[88:91], v[56:59], a[248:251]
	v_mfma_f32_16x16x32_f16 a[244:247], v[84:87], v[56:59], a[244:247]
	v_mfma_f32_16x16x32_f16 a[240:243], v[80:83], v[56:59], a[240:243]
	v_mfma_f32_16x16x32_f16 a[236:239], v[172:175], v[44:47], a[236:239]
	v_mfma_f32_16x16x32_f16 a[232:235], v[88:91], v[44:47], a[232:235]
	v_mfma_f32_16x16x32_f16 a[228:231], v[84:87], v[44:47], a[228:231]
	v_mfma_f32_16x16x32_f16 a[224:227], v[80:83], v[44:47], a[224:227]
	v_mfma_f32_16x16x32_f16 a[220:223], v[172:175], v[28:31], a[220:223]
	v_mfma_f32_16x16x32_f16 a[216:219], v[88:91], v[28:31], a[216:219]
	v_mfma_f32_16x16x32_f16 a[212:215], v[84:87], v[28:31], a[212:215]
	v_mfma_f32_16x16x32_f16 a[208:211], v[80:83], v[28:31], a[208:211]
	v_mfma_f32_16x16x32_f16 a[204:207], v[172:175], v[12:15], a[204:207]
	v_mfma_f32_16x16x32_f16 a[200:203], v[88:91], v[12:15], a[200:203]
	v_mfma_f32_16x16x32_f16 a[196:199], v[84:87], v[12:15], a[196:199]
	v_mfma_f32_16x16x32_f16 a[192:195], v[80:83], v[12:15], a[192:195]
	v_mfma_f32_16x16x32_f16 a[188:191], v[172:175], v[4:7], a[188:191]
	v_mfma_f32_16x16x32_f16 a[184:187], v[88:91], v[4:7], a[184:187]
	v_mfma_f32_16x16x32_f16 a[180:183], v[84:87], v[4:7], a[180:183]
	v_mfma_f32_16x16x32_f16 a[176:179], v[80:83], v[4:7], a[176:179]
	v_mfma_f32_16x16x32_f16 a[172:175], v[172:175], v[0:3], a[172:175]
	v_mfma_f32_16x16x32_f16 a[168:171], v[88:91], v[0:3], a[168:171]
	v_mfma_f32_16x16x32_f16 a[164:167], v[84:87], v[0:3], a[164:167]
	v_mfma_f32_16x16x32_f16 a[156:159], v[80:83], v[0:3], a[156:159]
	v_mfma_f32_16x16x32_f16 a[140:143], v[172:175], v[8:11], a[140:143]
	v_mfma_f32_16x16x32_f16 a[132:135], v[88:91], v[8:11], a[132:135]
	v_mfma_f32_16x16x32_f16 a[128:131], v[84:87], v[8:11], a[128:131]
	v_mfma_f32_16x16x32_f16 a[124:127], v[80:83], v[8:11], a[124:127]
	v_mfma_f32_16x16x32_f16 a[96:99], v[172:175], v[20:23], a[96:99]
	v_mfma_f32_16x16x32_f16 a[88:91], v[88:91], v[20:23], a[88:91]
	v_mfma_f32_16x16x32_f16 a[84:87], v[84:87], v[20:23], a[84:87]
	v_mfma_f32_16x16x32_f16 a[80:83], v[80:83], v[20:23], a[80:83]
	s_branch .LBB0_2051

; #define LD_AF(dst, ks_) _Pragma("unroll") for (int i = 0; i < 8; ++i) dst[i] = *(const h8*)(sA + i * 16 * G_LD + (ks_) * 32)
; #define LD_BF(dst, ks_, nh_) _Pragma("unroll") for (int i = 0; i < 4; ++i) dst[i] = *(const h8*)(sB + ((nh_) * 4 + i) * 16 * G_LD + (ks_) * 32)
; #define MMA_BLK(afx, bfx, nh_) _Pragma("unroll") for (int mi = 0; mi < 8; ++mi) _Pragma("unroll") for (int ni = 0; ni < 4; ++ni) mfma16_acc(acc[mi][(nh_) * 4 + ni], bfx[ni], afx[mi])
; template <class Epi>
; __device__ __forceinline__ void gemm_run(const GemmArgs g, Epi epi, char* smem) {
;     ...
;       const hf* sA = sbase + (kt & 1) * G_STAGE + (wm * 128 + fr) * G_LD + fqs;
;       const hf* sB = sbase + (kt & 1) * G_STAGE + (256 + wn * 128 + fr) * G_LD + fqs;
;       hf* st = sbase + ((kt + 1) & 1) * G_STAGE;
;       h8 afA[8], afB[8], bfA[4], bfB[4];
;     ...
;       LD_AF(afA, 0); LD_BF(bfA, 0, 0);
;       if (kt + 1 < nk) {
; #pragma unroll
;         for (int i = 0; i < 8; ++i) *(u4*)(st + (lr + 32 * i) * G_LD + lcw) = ra[i];
;       }
;       __builtin_amdgcn_sched_barrier(0);
;       LD_BF(bfB, 0, 1);
;       MMA_BLK(afA, bfA, 0);
;       __builtin_amdgcn_sched_barrier(0);
;       if (kt + 1 < nk) {
; #pragma unroll
;         for (int i = 0; i < 8; ++i) *(u4*)(st + (256 + lr + 32 * i) * G_LD + lcw) = rb[i];
;       }
;       LD_AF(afB, 1); LD_BF(bfA, 1, 0);
;       MMA_BLK(afA, bfB, 1);
;       __builtin_amdgcn_sched_barrier(0);
;       if (kt + 2 < nk) {
.LBB0_2103:
	s_bitcmp1_b32 s55, 0
	s_cselect_b32 s15, 0x12000, 0
	s_add_i32 s15, s15, 16
	v_add3_u32 v92, s15, v132, v139
	v_add3_u32 v64, s15, v131, v139
	ds_read_b128 v[36:39], v92 offset:36864
	ds_read_b128 v[56:59], v64
	ds_read_b128 v[32:35], v92 offset:39168
	ds_read_b128 v[24:27], v92 offset:41472
	ds_read_b128 v[16:19], v92 offset:43776
	ds_read_b128 v[44:47], v64 offset:2304
	ds_read_b128 v[28:31], v64 offset:4608
	ds_read_b128 v[12:15], v64 offset:6912
	ds_read_b128 v[4:7], v64 offset:9216
	ds_read_b128 v[0:3], v64 offset:11520
	ds_read_b128 v[8:11], v64 offset:13824
	ds_read_b128 v[20:23], v64 offset:16128
	s_mov_b32 s14, s55
	s_add_i32 s55, s55, 1
	s_bitcmp1_b32 s55, 0
	s_cselect_b32 s58, 0x12000, 0
	v_add_u32_e32 v40, s58, v129
	v_add_u32_e32 v41, v40, v134
	s_waitcnt vmcnt(15)
	ds_write_b128 v41, v[94:97]
	s_waitcnt vmcnt(14)
	ds_write_b128 v41, v[98:101] offset:4608
	s_waitcnt vmcnt(11)
	ds_write_b128 v41, v[106:109] offset:9216
	s_waitcnt vmcnt(10)
	ds_write_b128 v41, v[114:117] offset:13824
	s_waitcnt vmcnt(7)
	ds_write_b128 v41, v[122:125] offset:18432
	s_waitcnt vmcnt(6)
	ds_write_b128 v41, v[144:147] offset:23040
	s_waitcnt vmcnt(3)
	ds_write_b128 v41, v[148:151] offset:27648
	s_waitcnt vmcnt(2)
	ds_write_b128 v41, v[156:159] offset:32256
	ds_read_b128 v[172:175], v92 offset:46080
	ds_read_b128 v[88:91], v92 offset:48384
	ds_read_b128 v[84:87], v92 offset:50688
	ds_read_b128 v[80:83], v92 offset:52992
	s_waitcnt lgkmcnt(14)
	v_mfma_f32_16x16x32_f16 a[208:211], v[36:39], v[56:59], a[208:211]
	v_mfma_f32_16x16x32_f16 a[200:203], v[32:35], v[56:59], a[200:203]
	v_mfma_f32_16x16x32_f16 a[196:199], v[24:27], v[56:59], a[196:199]
	v_mfma_f32_16x16x32_f16 a[192:195], v[16:19], v[56:59], a[192:195]
	v_mfma_f32_16x16x32_f16 a[188:191], v[36:39], v[44:47], a[188:191]
	v_mfma_f32_16x16x32_f16 a[184:187], v[32:35], v[44:47], a[184:187]
	v_mfma_f32_16x16x32_f16 a[180:183], v[24:27], v[44:47], a[180:183]
	v_mfma_f32_16x16x32_f16 a[176:179], v[16:19], v[44:47], a[176:179]
	v_mfma_f32_16x16x32_f16 a[156:159], v[36:39], v[28:31], a[156:159]
	v_mfma_f32_16x16x32_f16 a[152:155], v[32:35], v[28:31], a[152:155]
	v_mfma_f32_16x16x32_f16 a[148:151], v[24:27], v[28:31], a[148:151]
	v_mfma_f32_16x16x32_f16 a[144:147], v[16:19], v[28:31], a[144:147]
	v_mfma_f32_16x16x32_f16 a[124:127], v[36:39], v[12:15], a[124:127]
	v_mfma_f32_16x16x32_f16 a[120:123], v[32:35], v[12:15], a[120:123]
	v_mfma_f32_16x16x32_f16 a[116:119], v[24:27], v[12:15], a[116:119]
	v_mfma_f32_16x16x32_f16 a[112:115], v[16:19], v[12:15], a[112:115]
	v_mfma_f32_16x16x32_f16 a[92:95], v[36:39], v[4:7], a[92:95]
	v_mfma_f32_16x16x32_f16 a[88:91], v[32:35], v[4:7], a[88:91]
	v_mfma_f32_16x16x32_f16 a[84:87], v[24:27], v[4:7], a[84:87]
	v_mfma_f32_16x16x32_f16 a[80:83], v[16:19], v[4:7], a[80:83]
	v_mfma_f32_16x16x32_f16 a[60:63], v[36:39], v[0:3], a[60:63]
	v_mfma_f32_16x16x32_f16 a[56:59], v[32:35], v[0:3], a[56:59]
	v_mfma_f32_16x16x32_f16 a[52:55], v[24:27], v[0:3], a[52:55]
	v_mfma_f32_16x16x32_f16 a[48:51], v[16:19], v[0:3], a[48:51]
	s_waitcnt lgkmcnt(13)
	v_mfma_f32_16x16x32_f16 a[28:31], v[36:39], v[8:11], a[28:31]
	v_mfma_f32_16x16x32_f16 a[24:27], v[32:35], v[8:11], a[24:27]
	v_mfma_f32_16x16x32_f16 a[20:23], v[24:27], v[8:11], a[20:23]
	v_mfma_f32_16x16x32_f16 a[16:19], v[16:19], v[8:11], a[16:19]
	s_waitcnt lgkmcnt(12)
	v_mfma_f32_16x16x32_f16 a[12:15], v[36:39], v[20:23], a[12:15]
	v_mfma_f32_16x16x32_f16 a[8:11], v[32:35], v[20:23], a[8:11]
	v_mfma_f32_16x16x32_f16 a[4:7], v[24:27], v[20:23], a[4:7]
	v_mfma_f32_16x16x32_f16 a[0:3], v[16:19], v[20:23], a[0:3]
	v_add_u32_e32 v16, v40, v135
	s_waitcnt vmcnt(7)
	ds_write_b128 v41, v[102:105] offset:36864
	s_waitcnt vmcnt(6)
	ds_write_b128 v41, v[110:113] offset:41472
	s_waitcnt vmcnt(5)
	ds_write_b128 v41, v[118:121] offset:46080
	s_waitcnt vmcnt(4)
	ds_write_b128 v41, v[140:143] offset:50688
	s_waitcnt vmcnt(3)
	ds_write_b128 v41, v[152:155] offset:55296
	s_waitcnt vmcnt(2)
	ds_write_b128 v41, v[160:163] offset:59904
	s_waitcnt vmcnt(1)
	ds_write_b128 v41, v[164:167] offset:64512
	s_waitcnt vmcnt(0)
	ds_write_b128 v16, v[168:171]
	ds_read_b128 v[60:63], v64 offset:64
	ds_read_b128 v[52:55], v64 offset:2368
	ds_read_b128 v[48:51], v64 offset:4672
	ds_read_b128 v[40:43], v64 offset:6976
	ds_read_b128 v[36:39], v64 offset:9280
	ds_read_b128 v[32:35], v64 offset:11584
	ds_read_b128 v[24:27], v64 offset:13888
	ds_read_b128 v[16:19], v64 offset:16192
	ds_read_b128 v[64:67], v92 offset:36928
	ds_read_b128 v[68:71], v92 offset:39232
	ds_read_b128 v[72:75], v92 offset:41536
	ds_read_b128 v[76:79], v92 offset:43840
	s_cmpk_gt_u32 s14, 0x55
	s_cbranch_scc1 .Lgw16_nl
; #define MMA_BLK(afx, bfx, nh_) _Pragma("unroll") for (int mi = 0; mi < 8; ++mi) _Pragma("unroll") for (int ni = 0; ni < 4; ++ni) mfma16_acc(acc[mi][(nh_) * 4 + ni], bfx[ni], afx[mi])
; template <class Epi>
; __device__ __forceinline__ void gemm_run(const GemmArgs g, Epi epi, char* smem) {
;     ...
;       MMA_BLK(afA, bfB, 1);
;       __builtin_amdgcn_sched_barrier(0);
;       if (kt + 2 < nk) {
;         const int ko = (kt + 2) * 64;
; #pragma unroll
;         for (int i = 0; i < 8; ++i) { ra[i] = __builtin_amdgcn_raw_buffer_load_b128(Ars, aoff, i * astep + ko * 2, 0); rb[i] = __builtin_amdgcn_raw_buffer_load_b128(Brs, boff, i * bstep + ko * 2, 0); }
;       }
	s_waitcnt lgkmcnt(14)
	v_mfma_f32_16x16x32_f16 a[240:243], v[172:175], v[56:59], a[240:243]
	v_mfma_f32_16x16x32_f16 a[252:255], v[88:91], v[56:59], a[252:255]
	v_mfma_f32_16x16x32_f16 a[248:251], v[84:87], v[56:59], a[248:251]
	s_add_i32 s58, s54, 0xffd98000
	v_mfma_f32_16x16x32_f16 a[244:247], v[80:83], v[56:59], a[244:247]
	s_mov_b32 s14, s10
	v_mfma_f32_16x16x32_f16 a[236:239], v[172:175], v[44:47], a[236:239]
	s_mov_b32 s15, s11
	v_mfma_f32_16x16x32_f16 a[232:235], v[88:91], v[44:47], a[232:235]
	s_add_i32 s59, s54, 0xffdf0000
	v_mfma_f32_16x16x32_f16 a[228:231], v[84:87], v[44:47], a[228:231]
	buffer_load_dwordx4 v[94:97], v128, s[8:11], s58 offen
	v_mfma_f32_16x16x32_f16 a[224:227], v[80:83], v[44:47], a[224:227]
	buffer_load_dwordx4 v[98:101], v128, s[8:11], s59 offen
	v_mfma_f32_16x16x32_f16 a[220:223], v[172:175], v[28:31], a[220:223]
	buffer_load_dwordx4 v[102:105], v128, s[12:15], s58 offen
	v_mfma_f32_16x16x32_f16 a[216:219], v[88:91], v[28:31], a[216:219]
	buffer_load_dwordx4 v[110:113], v128, s[12:15], s59 offen
	v_mfma_f32_16x16x32_f16 a[212:215], v[84:87], v[28:31], a[212:215]
	s_add_i32 s58, s54, 0xffe48000
	v_mfma_f32_16x16x32_f16 a[204:207], v[80:83], v[28:31], a[204:207]
	s_add_i32 s59, s54, 0xffea0000
	v_mfma_f32_16x16x32_f16 a[172:175], v[172:175], v[12:15], a[172:175]
	buffer_load_dwordx4 v[106:109], v128, s[8:11], s58 offen
	v_mfma_f32_16x16x32_f16 a[168:171], v[88:91], v[12:15], a[168:171]
	buffer_load_dwordx4 v[114:117], v128, s[8:11], s59 offen
	v_mfma_f32_16x16x32_f16 a[164:167], v[84:87], v[12:15], a[164:167]
	buffer_load_dwordx4 v[118:121], v128, s[12:15], s58 offen
	v_mfma_f32_16x16x32_f16 a[160:163], v[80:83], v[12:15], a[160:163]
	buffer_load_dwordx4 v[140:143], v128, s[12:15], s59 offen
	v_mfma_f32_16x16x32_f16 a[140:143], v[172:175], v[4:7], a[140:143]
	s_add_i32 s58, s54, 0xffef8000
	v_mfma_f32_16x16x32_f16 a[136:139], v[88:91], v[4:7], a[136:139]
	s_add_i32 s59, s54, 0xfff50000
	v_mfma_f32_16x16x32_f16 a[132:135], v[84:87], v[4:7], a[132:135]
	buffer_load_dwordx4 v[122:125], v128, s[8:11], s58 offen
	v_mfma_f32_16x16x32_f16 a[128:131], v[80:83], v[4:7], a[128:131]
	buffer_load_dwordx4 v[144:147], v128, s[8:11], s59 offen
	v_mfma_f32_16x16x32_f16 a[108:111], v[172:175], v[0:3], a[108:111]
	buffer_load_dwordx4 v[152:155], v128, s[12:15], s58 offen
	v_mfma_f32_16x16x32_f16 a[104:107], v[88:91], v[0:3], a[104:107]
	buffer_load_dwordx4 v[160:163], v128, s[12:15], s59 offen
	v_mfma_f32_16x16x32_f16 a[100:103], v[84:87], v[0:3], a[100:103]
	s_add_i32 s58, s54, 0xfffa8000
	v_mfma_f32_16x16x32_f16 a[96:99], v[80:83], v[0:3], a[96:99]
	buffer_load_dwordx4 v[148:151], v128, s[8:11], s58 offen
	v_mfma_f32_16x16x32_f16 a[76:79], v[172:175], v[8:11], a[76:79]
	buffer_load_dwordx4 v[156:159], v128, s[8:11], s54 offen
	v_mfma_f32_16x16x32_f16 a[72:75], v[88:91], v[8:11], a[72:75]
	buffer_load_dwordx4 v[164:167], v128, s[12:15], s58 offen
	v_mfma_f32_16x16x32_f16 a[68:71], v[84:87], v[8:11], a[68:71]
	buffer_load_dwordx4 v[168:171], v128, s[12:15], s54 offen
	v_mfma_f32_16x16x32_f16 a[64:67], v[80:83], v[8:11], a[64:67]
	v_mfma_f32_16x16x32_f16 a[44:47], v[172:175], v[20:23], a[44:47]
	v_mfma_f32_16x16x32_f16 a[40:43], v[88:91], v[20:23], a[40:43]
	v_mfma_f32_16x16x32_f16 a[36:39], v[84:87], v[20:23], a[36:39]
	v_mfma_f32_16x16x32_f16 a[32:35], v[80:83], v[20:23], a[32:35]
	s_branch .LBB0_2102

; #define LD_AF(dst, ks_) _Pragma("unroll") for (int i = 0; i < 8; ++i) dst[i] = *(const h8*)(sA + i * 16 * G_LD + (ks_) * 32)
; #define LD_BF(dst, ks_, nh_) _Pragma("unroll") for (int i = 0; i < 4; ++i) dst[i] = *(const h8*)(sB + ((nh_) * 4 + i) * 16 * G_LD + (ks_) * 32)
; #define MMA_BLK(afx, bfx, nh_) _Pragma("unroll") for (int mi = 0; mi < 8; ++mi) _Pragma("unroll") for (int ni = 0; ni < 4; ++ni) mfma16_acc(acc[mi][(nh_) * 4 + ni], bfx[ni], afx[mi])
; template <class Epi>
; __device__ __forceinline__ void gemm_run(const GemmArgs g, Epi epi, char* smem) {
;     ...
;       const hf* sA = sbase + (kt & 1) * G_STAGE + (wm * 128 + fr) * G_LD + fqs;
;       const hf* sB = sbase + (kt & 1) * G_STAGE + (256 + wn * 128 + fr) * G_LD + fqs;
;       hf* st = sbase + ((kt + 1) & 1) * G_STAGE;
;       h8 afA[8], afB[8], bfA[4], bfB[4];
;     ...
;       LD_AF(afA, 0); LD_BF(bfA, 0, 0);
;       if (kt + 1 < nk) {
; #pragma unroll
;         for (int i = 0; i < 8; ++i) *(u4*)(st + (lr + 32 * i) * G_LD + lcw) = ra[i];
;       }
;       __builtin_amdgcn_sched_barrier(0);
;       LD_BF(bfB, 0, 1);
;       MMA_BLK(afA, bfA, 0);
;       __builtin_amdgcn_sched_barrier(0);
;       if (kt + 1 < nk) {
; #pragma unroll
;         for (int i = 0; i < 8; ++i) *(u4*)(st + (256 + lr + 32 * i) * G_LD + lcw) = rb[i];
;       }
;       LD_AF(afB, 1); LD_BF(bfA, 1, 0);
;       MMA_BLK(afA, bfB, 1);
;       __builtin_amdgcn_sched_barrier(0);
;       if (kt + 2 < nk) {
.LBB0_2109:
	s_bitcmp1_b32 s37, 0
	s_cselect_b32 s15, 0x12000, 0
	s_add_i32 s15, s15, 16
	v_add3_u32 v106, s15, v96, v105
	v_add3_u32 v64, s15, v94, v105
	ds_read_b128 v[36:39], v106 offset:36864
	ds_read_b128 v[56:59], v64
	ds_read_b128 v[32:35], v106 offset:39168
	ds_read_b128 v[24:27], v106 offset:41472
	ds_read_b128 v[16:19], v106 offset:43776
	ds_read_b128 v[44:47], v64 offset:2304
	ds_read_b128 v[28:31], v64 offset:4608
	ds_read_b128 v[12:15], v64 offset:6912
	ds_read_b128 v[4:7], v64 offset:9216
	ds_read_b128 v[0:3], v64 offset:11520
	ds_read_b128 v[8:11], v64 offset:13824
	ds_read_b128 v[20:23], v64 offset:16128
	s_mov_b32 s14, s37
	s_add_i32 s37, s37, 1
	s_bitcmp1_b32 s37, 0
	s_cselect_b32 s59, 0x12000, 0
	v_add_u32_e32 v40, s59, v93
	v_add_u32_e32 v41, v40, v98
	s_waitcnt vmcnt(15)
	ds_write_b128 v41, v[108:111]
	s_waitcnt vmcnt(14)
	ds_write_b128 v41, v[112:115] offset:4608
	s_waitcnt vmcnt(11)
	ds_write_b128 v41, v[120:123] offset:9216
	s_waitcnt vmcnt(10)
	ds_write_b128 v41, v[128:131] offset:13824
	s_waitcnt vmcnt(7)
	ds_write_b128 v41, v[136:139] offset:18432
	s_waitcnt vmcnt(6)
	ds_write_b128 v41, v[144:147] offset:23040
	s_waitcnt vmcnt(3)
	ds_write_b128 v41, v[148:151] offset:27648
	s_waitcnt vmcnt(2)
	ds_write_b128 v41, v[156:159] offset:32256
	ds_read_b128 v[172:175], v106 offset:46080
	ds_read_b128 v[88:91], v106 offset:48384
	ds_read_b128 v[84:87], v106 offset:50688
	ds_read_b128 v[80:83], v106 offset:52992
	s_waitcnt lgkmcnt(14)
	v_mfma_f32_16x16x32_f16 a[120:123], v[36:39], v[56:59], a[120:123]
	v_mfma_f32_16x16x32_f16 a[116:119], v[32:35], v[56:59], a[116:119]
	v_mfma_f32_16x16x32_f16 a[112:115], v[24:27], v[56:59], a[112:115]
	v_mfma_f32_16x16x32_f16 a[160:163], v[16:19], v[56:59], a[160:163]
	v_mfma_f32_16x16x32_f16 a[152:155], v[36:39], v[44:47], a[152:155]
	v_mfma_f32_16x16x32_f16 a[148:151], v[32:35], v[44:47], a[148:151]
	v_mfma_f32_16x16x32_f16 a[144:147], v[24:27], v[44:47], a[144:147]
	v_mfma_f32_16x16x32_f16 a[136:139], v[16:19], v[44:47], a[136:139]
	v_mfma_f32_16x16x32_f16 a[108:111], v[36:39], v[28:31], a[108:111]
	v_mfma_f32_16x16x32_f16 a[104:107], v[32:35], v[28:31], a[104:107]
	v_mfma_f32_16x16x32_f16 a[100:103], v[24:27], v[28:31], a[100:103]
	v_mfma_f32_16x16x32_f16 a[92:95], v[16:19], v[28:31], a[92:95]
	v_mfma_f32_16x16x32_f16 a[76:79], v[36:39], v[12:15], a[76:79]
	v_mfma_f32_16x16x32_f16 a[72:75], v[32:35], v[12:15], a[72:75]
	v_mfma_f32_16x16x32_f16 a[68:71], v[24:27], v[12:15], a[68:71]
	v_mfma_f32_16x16x32_f16 a[64:67], v[16:19], v[12:15], a[64:67]
	v_mfma_f32_16x16x32_f16 a[60:63], v[36:39], v[4:7], a[60:63]
	v_mfma_f32_16x16x32_f16 a[56:59], v[32:35], v[4:7], a[56:59]
	v_mfma_f32_16x16x32_f16 a[52:55], v[24:27], v[4:7], a[52:55]
	v_mfma_f32_16x16x32_f16 a[48:51], v[16:19], v[4:7], a[48:51]
	v_mfma_f32_16x16x32_f16 a[44:47], v[36:39], v[0:3], a[44:47]
	v_mfma_f32_16x16x32_f16 a[40:43], v[32:35], v[0:3], a[40:43]
	v_mfma_f32_16x16x32_f16 a[36:39], v[24:27], v[0:3], a[36:39]
	v_mfma_f32_16x16x32_f16 a[32:35], v[16:19], v[0:3], a[32:35]
	s_waitcnt lgkmcnt(13)
	v_mfma_f32_16x16x32_f16 a[28:31], v[36:39], v[8:11], a[28:31]
	v_mfma_f32_16x16x32_f16 a[24:27], v[32:35], v[8:11], a[24:27]
	v_mfma_f32_16x16x32_f16 a[20:23], v[24:27], v[8:11], a[20:23]
	v_mfma_f32_16x16x32_f16 a[16:19], v[16:19], v[8:11], a[16:19]
	s_waitcnt lgkmcnt(12)
	v_mfma_f32_16x16x32_f16 a[12:15], v[36:39], v[20:23], a[12:15]
	v_mfma_f32_16x16x32_f16 a[8:11], v[32:35], v[20:23], a[8:11]
	v_mfma_f32_16x16x32_f16 a[4:7], v[24:27], v[20:23], a[4:7]
	v_mfma_f32_16x16x32_f16 a[0:3], v[16:19], v[20:23], a[0:3]
	v_add_u32_e32 v16, v40, v99
	s_waitcnt vmcnt(7)
	ds_write_b128 v41, v[116:119] offset:36864
	s_waitcnt vmcnt(6)
	ds_write_b128 v41, v[124:127] offset:41472
	s_waitcnt vmcnt(5)
	ds_write_b128 v41, v[132:135] offset:46080
	s_waitcnt vmcnt(4)
	ds_write_b128 v41, v[140:143] offset:50688
	s_waitcnt vmcnt(3)
	ds_write_b128 v41, v[152:155] offset:55296
	s_waitcnt vmcnt(2)
	ds_write_b128 v41, v[160:163] offset:59904
	s_waitcnt vmcnt(1)
	ds_write_b128 v41, v[164:167] offset:64512
	s_waitcnt vmcnt(0)
	ds_write_b128 v16, v[168:171]
	ds_read_b128 v[60:63], v64 offset:64
	ds_read_b128 v[52:55], v64 offset:2368
	ds_read_b128 v[48:51], v64 offset:4672
	ds_read_b128 v[40:43], v64 offset:6976
	ds_read_b128 v[36:39], v64 offset:9280
	ds_read_b128 v[32:35], v64 offset:11584
	ds_read_b128 v[24:27], v64 offset:13888
	ds_read_b128 v[16:19], v64 offset:16192
	ds_read_b128 v[64:67], v106 offset:36928
	ds_read_b128 v[68:71], v106 offset:39232
	ds_read_b128 v[72:75], v106 offset:41536
	ds_read_b128 v[76:79], v106 offset:43840
	s_cmp_gt_u32 s14, 29
	s_cbranch_scc1 .Lgw17_nl
; #define MMA_BLK(afx, bfx, nh_) _Pragma("unroll") for (int mi = 0; mi < 8; ++mi) _Pragma("unroll") for (int ni = 0; ni < 4; ++ni) mfma16_acc(acc[mi][(nh_) * 4 + ni], bfx[ni], afx[mi])
; template <class Epi>
; __device__ __forceinline__ void gemm_run(const GemmArgs g, Epi epi, char* smem) {
;     ...
;       MMA_BLK(afA, bfB, 1);
;       __builtin_amdgcn_sched_barrier(0);
;       if (kt + 2 < nk) {
;         const int ko = (kt + 2) * 64;
; #pragma unroll
;         for (int i = 0; i < 8; ++i) { ra[i] = __builtin_amdgcn_raw_buffer_load_b128(Ars, aoff, i * astep + ko * 2, 0); rb[i] = __builtin_amdgcn_raw_buffer_load_b128(Brs, boff, i * bstep + ko * 2, 0); }
;       }
	s_waitcnt lgkmcnt(14)
	v_mfma_f32_16x16x32_f16 a[252:255], v[172:175], v[56:59], a[252:255]
	v_mfma_f32_16x16x32_f16 a[248:251], v[88:91], v[56:59], a[248:251]
	v_mfma_f32_16x16x32_f16 a[244:247], v[84:87], v[56:59], a[244:247]
	s_add_i32 s59, s1, 0xfff20000
	v_mfma_f32_16x16x32_f16 a[240:243], v[80:83], v[56:59], a[240:243]
	s_mov_b32 s14, s10
	v_mfma_f32_16x16x32_f16 a[236:239], v[172:175], v[44:47], a[236:239]
	s_mov_b32 s15, s11
	v_mfma_f32_16x16x32_f16 a[232:235], v[88:91], v[44:47], a[232:235]
	s_add_i32 s62, s1, 0xfff40000
	v_mfma_f32_16x16x32_f16 a[228:231], v[84:87], v[44:47], a[228:231]
	buffer_load_dwordx4 v[108:111], v92, s[8:11], s59 offen
	v_mfma_f32_16x16x32_f16 a[224:227], v[80:83], v[44:47], a[224:227]
	buffer_load_dwordx4 v[112:115], v92, s[8:11], s62 offen
	v_mfma_f32_16x16x32_f16 a[220:223], v[172:175], v[28:31], a[220:223]
	buffer_load_dwordx4 v[116:119], v92, s[12:15], s59 offen
	v_mfma_f32_16x16x32_f16 a[216:219], v[88:91], v[28:31], a[216:219]
	buffer_load_dwordx4 v[124:127], v92, s[12:15], s62 offen
	v_mfma_f32_16x16x32_f16 a[212:215], v[84:87], v[28:31], a[212:215]
	s_add_i32 s59, s1, 0xfff60000
	v_mfma_f32_16x16x32_f16 a[208:211], v[80:83], v[28:31], a[208:211]
	s_add_i32 s62, s1, 0xfff80000
	v_mfma_f32_16x16x32_f16 a[204:207], v[172:175], v[12:15], a[204:207]
	buffer_load_dwordx4 v[120:123], v92, s[8:11], s59 offen
	v_mfma_f32_16x16x32_f16 a[200:203], v[88:91], v[12:15], a[200:203]
	buffer_load_dwordx4 v[128:131], v92, s[8:11], s62 offen
	v_mfma_f32_16x16x32_f16 a[196:199], v[84:87], v[12:15], a[196:199]
	buffer_load_dwordx4 v[132:135], v92, s[12:15], s59 offen
	v_mfma_f32_16x16x32_f16 a[192:195], v[80:83], v[12:15], a[192:195]
	buffer_load_dwordx4 v[140:143], v92, s[12:15], s62 offen
	v_mfma_f32_16x16x32_f16 a[188:191], v[172:175], v[4:7], a[188:191]
	s_add_i32 s59, s1, 0xfffa0000
	v_mfma_f32_16x16x32_f16 a[184:187], v[88:91], v[4:7], a[184:187]
	s_add_i32 s62, s1, 0xfffc0000
	v_mfma_f32_16x16x32_f16 a[180:183], v[84:87], v[4:7], a[180:183]
	buffer_load_dwordx4 v[136:139], v92, s[8:11], s59 offen
	v_mfma_f32_16x16x32_f16 a[176:179], v[80:83], v[4:7], a[176:179]
	buffer_load_dwordx4 v[144:147], v92, s[8:11], s62 offen
	v_mfma_f32_16x16x32_f16 a[172:175], v[172:175], v[0:3], a[172:175]
	buffer_load_dwordx4 v[152:155], v92, s[12:15], s59 offen
	v_mfma_f32_16x16x32_f16 a[168:171], v[88:91], v[0:3], a[168:171]
	buffer_load_dwordx4 v[160:163], v92, s[12:15], s62 offen
	v_mfma_f32_16x16x32_f16 a[164:167], v[84:87], v[0:3], a[164:167]
	s_add_i32 s59, s1, 0xfffe0000
	v_mfma_f32_16x16x32_f16 a[156:159], v[80:83], v[0:3], a[156:159]
	buffer_load_dwordx4 v[148:151], v92, s[8:11], s59 offen
	v_mfma_f32_16x16x32_f16 a[140:143], v[172:175], v[8:11], a[140:143]
	buffer_load_dwordx4 v[156:159], v92, s[8:11], s1 offen
	v_mfma_f32_16x16x32_f16 a[132:135], v[88:91], v[8:11], a[132:135]
	buffer_load_dwordx4 v[164:167], v92, s[12:15], s59 offen
	v_mfma_f32_16x16x32_f16 a[128:131], v[84:87], v[8:11], a[128:131]
	buffer_load_dwordx4 v[168:171], v92, s[12:15], s1 offen
	v_mfma_f32_16x16x32_f16 a[124:127], v[80:83], v[8:11], a[124:127]
	v_mfma_f32_16x16x32_f16 a[96:99], v[172:175], v[20:23], a[96:99]
	v_mfma_f32_16x16x32_f16 a[88:91], v[88:91], v[20:23], a[88:91]
	v_mfma_f32_16x16x32_f16 a[84:87], v[84:87], v[20:23], a[84:87]
	v_mfma_f32_16x16x32_f16 a[80:83], v[80:83], v[20:23], a[80:83]
	s_branch .LBB0_2108

; #define LD_AF(dst, ks_) _Pragma("unroll") for (int i = 0; i < 8; ++i) dst[i] = *(const h8*)(sA + i * 16 * G_LD + (ks_) * 32)
; #define LD_BF(dst, ks_, nh_) _Pragma("unroll") for (int i = 0; i < 4; ++i) dst[i] = *(const h8*)(sB + ((nh_) * 4 + i) * 16 * G_LD + (ks_) * 32)
; #define MMA_BLK(afx, bfx, nh_) _Pragma("unroll") for (int mi = 0; mi < 8; ++mi) _Pragma("unroll") for (int ni = 0; ni < 4; ++ni) mfma16_acc(acc[mi][(nh_) * 4 + ni], bfx[ni], afx[mi])
; template <class Epi>
; __device__ __forceinline__ void gemm_run(const GemmArgs g, Epi epi, char* smem) {
;     ...
;       const hf* sA = sbase + (kt & 1) * G_STAGE + (wm * 128 + fr) * G_LD + fqs;
;       const hf* sB = sbase + (kt & 1) * G_STAGE + (256 + wn * 128 + fr) * G_LD + fqs;
;       hf* st = sbase + ((kt + 1) & 1) * G_STAGE;
;       h8 afA[8], afB[8], bfA[4], bfB[4];
;     ...
;       LD_AF(afA, 0); LD_BF(bfA, 0, 0);
;       if (kt + 1 < nk) {
; #pragma unroll
;         for (int i = 0; i < 8; ++i) *(u4*)(st + (lr + 32 * i) * G_LD + lcw) = ra[i];
;       }
;       __builtin_amdgcn_sched_barrier(0);
;       LD_BF(bfB, 0, 1);
;       MMA_BLK(afA, bfA, 0);
;       __builtin_amdgcn_sched_barrier(0);
;       if (kt + 1 < nk) {
; #pragma unroll
;         for (int i = 0; i < 8; ++i) *(u4*)(st + (256 + lr + 32 * i) * G_LD + lcw) = rb[i];
;       }
;       LD_AF(afB, 1); LD_BF(bfA, 1, 0);
;       MMA_BLK(afA, bfB, 1);
;       __builtin_amdgcn_sched_barrier(0);
;       if (kt + 2 < nk) {
.LBB0_2160:
	s_bitcmp1_b32 s55, 0
	s_cselect_b32 s15, 0x12000, 0
	s_add_i32 s15, s15, 16
	v_add3_u32 v92, s15, v130, v137
	v_add3_u32 v64, s15, v129, v137
	ds_read_b128 v[36:39], v92 offset:36864
	ds_read_b128 v[56:59], v64
	ds_read_b128 v[32:35], v92 offset:39168
	ds_read_b128 v[24:27], v92 offset:41472
	ds_read_b128 v[16:19], v92 offset:43776
	ds_read_b128 v[44:47], v64 offset:2304
	ds_read_b128 v[28:31], v64 offset:4608
	ds_read_b128 v[12:15], v64 offset:6912
	ds_read_b128 v[4:7], v64 offset:9216
	ds_read_b128 v[0:3], v64 offset:11520
	ds_read_b128 v[8:11], v64 offset:13824
	ds_read_b128 v[20:23], v64 offset:16128
	s_mov_b32 s14, s55
	s_add_i32 s55, s55, 1
	s_bitcmp1_b32 s55, 0
	s_cselect_b32 s58, 0x12000, 0
	v_add_u32_e32 v40, s58, v127
	v_add_u32_e32 v41, v40, v132
	s_waitcnt vmcnt(15)
	ds_write_b128 v41, v[94:97]
	s_waitcnt vmcnt(14)
	ds_write_b128 v41, v[98:101] offset:4608
	s_waitcnt vmcnt(11)
	ds_write_b128 v41, v[106:109] offset:9216
	s_waitcnt vmcnt(10)
	ds_write_b128 v41, v[114:117] offset:13824
	s_waitcnt vmcnt(7)
	ds_write_b128 v41, v[122:125] offset:18432
	s_waitcnt vmcnt(6)
	ds_write_b128 v41, v[142:145] offset:23040
	s_waitcnt vmcnt(3)
	ds_write_b128 v41, v[146:149] offset:27648
	s_waitcnt vmcnt(2)
	ds_write_b128 v41, v[154:157] offset:32256
	ds_read_b128 v[170:173], v92 offset:46080
	ds_read_b128 v[88:91], v92 offset:48384
	ds_read_b128 v[84:87], v92 offset:50688
	ds_read_b128 v[80:83], v92 offset:52992
	s_waitcnt lgkmcnt(14)
	v_mfma_f32_16x16x32_f16 a[208:211], v[36:39], v[56:59], a[208:211]
	v_mfma_f32_16x16x32_f16 a[200:203], v[32:35], v[56:59], a[200:203]
	v_mfma_f32_16x16x32_f16 a[196:199], v[24:27], v[56:59], a[196:199]
	v_mfma_f32_16x16x32_f16 a[192:195], v[16:19], v[56:59], a[192:195]
	v_mfma_f32_16x16x32_f16 a[188:191], v[36:39], v[44:47], a[188:191]
	v_mfma_f32_16x16x32_f16 a[184:187], v[32:35], v[44:47], a[184:187]
	v_mfma_f32_16x16x32_f16 a[180:183], v[24:27], v[44:47], a[180:183]
	v_mfma_f32_16x16x32_f16 a[176:179], v[16:19], v[44:47], a[176:179]
	v_mfma_f32_16x16x32_f16 a[156:159], v[36:39], v[28:31], a[156:159]
	v_mfma_f32_16x16x32_f16 a[152:155], v[32:35], v[28:31], a[152:155]
	v_mfma_f32_16x16x32_f16 a[148:151], v[24:27], v[28:31], a[148:151]
	v_mfma_f32_16x16x32_f16 a[144:147], v[16:19], v[28:31], a[144:147]
	v_mfma_f32_16x16x32_f16 a[124:127], v[36:39], v[12:15], a[124:127]
	v_mfma_f32_16x16x32_f16 a[120:123], v[32:35], v[12:15], a[120:123]
	v_mfma_f32_16x16x32_f16 a[116:119], v[24:27], v[12:15], a[116:119]
	v_mfma_f32_16x16x32_f16 a[112:115], v[16:19], v[12:15], a[112:115]
	v_mfma_f32_16x16x32_f16 a[92:95], v[36:39], v[4:7], a[92:95]
	v_mfma_f32_16x16x32_f16 a[88:91], v[32:35], v[4:7], a[88:91]
	v_mfma_f32_16x16x32_f16 a[84:87], v[24:27], v[4:7], a[84:87]
	v_mfma_f32_16x16x32_f16 a[80:83], v[16:19], v[4:7], a[80:83]
	v_mfma_f32_16x16x32_f16 a[60:63], v[36:39], v[0:3], a[60:63]
	v_mfma_f32_16x16x32_f16 a[56:59], v[32:35], v[0:3], a[56:59]
	v_mfma_f32_16x16x32_f16 a[52:55], v[24:27], v[0:3], a[52:55]
	v_mfma_f32_16x16x32_f16 a[48:51], v[16:19], v[0:3], a[48:51]
	s_waitcnt lgkmcnt(13)
	v_mfma_f32_16x16x32_f16 a[28:31], v[36:39], v[8:11], a[28:31]
	v_mfma_f32_16x16x32_f16 a[24:27], v[32:35], v[8:11], a[24:27]
	v_mfma_f32_16x16x32_f16 a[20:23], v[24:27], v[8:11], a[20:23]
	v_mfma_f32_16x16x32_f16 a[16:19], v[16:19], v[8:11], a[16:19]
	s_waitcnt lgkmcnt(12)
	v_mfma_f32_16x16x32_f16 a[12:15], v[36:39], v[20:23], a[12:15]
	v_mfma_f32_16x16x32_f16 a[8:11], v[32:35], v[20:23], a[8:11]
	v_mfma_f32_16x16x32_f16 a[4:7], v[24:27], v[20:23], a[4:7]
	v_mfma_f32_16x16x32_f16 a[0:3], v[16:19], v[20:23], a[0:3]
	v_add_u32_e32 v16, v40, v133
	s_waitcnt vmcnt(7)
	ds_write_b128 v41, v[102:105] offset:36864
	s_waitcnt vmcnt(6)
	ds_write_b128 v41, v[110:113] offset:41472
	s_waitcnt vmcnt(5)
	ds_write_b128 v41, v[118:121] offset:46080
	s_waitcnt vmcnt(4)
	ds_write_b128 v41, v[138:141] offset:50688
	s_waitcnt vmcnt(3)
	ds_write_b128 v41, v[150:153] offset:55296
	s_waitcnt vmcnt(2)
	ds_write_b128 v41, v[158:161] offset:59904
	s_waitcnt vmcnt(1)
	ds_write_b128 v41, v[162:165] offset:64512
	s_waitcnt vmcnt(0)
	ds_write_b128 v16, v[166:169]
	ds_read_b128 v[60:63], v64 offset:64
	ds_read_b128 v[52:55], v64 offset:2368
	ds_read_b128 v[48:51], v64 offset:4672
	ds_read_b128 v[40:43], v64 offset:6976
	ds_read_b128 v[36:39], v64 offset:9280
	ds_read_b128 v[32:35], v64 offset:11584
	ds_read_b128 v[24:27], v64 offset:13888
	ds_read_b128 v[16:19], v64 offset:16192
	ds_read_b128 v[64:67], v92 offset:36928
	ds_read_b128 v[68:71], v92 offset:39232
	ds_read_b128 v[72:75], v92 offset:41536
	ds_read_b128 v[76:79], v92 offset:43840
	s_cmpk_gt_u32 s14, 0x55
	s_cbranch_scc1 .Lgw18_nl
; #define MMA_BLK(afx, bfx, nh_) _Pragma("unroll") for (int mi = 0; mi < 8; ++mi) _Pragma("unroll") for (int ni = 0; ni < 4; ++ni) mfma16_acc(acc[mi][(nh_) * 4 + ni], bfx[ni], afx[mi])
; template <class Epi>
; __device__ __forceinline__ void gemm_run(const GemmArgs g, Epi epi, char* smem) {
;     ...
;       MMA_BLK(afA, bfB, 1);
;       __builtin_amdgcn_sched_barrier(0);
;       if (kt + 2 < nk) {
;         const int ko = (kt + 2) * 64;
; #pragma unroll
;         for (int i = 0; i < 8; ++i) { ra[i] = __builtin_amdgcn_raw_buffer_load_b128(Ars, aoff, i * astep + ko * 2, 0); rb[i] = __builtin_amdgcn_raw_buffer_load_b128(Brs, boff, i * bstep + ko * 2, 0); }
;       }
	s_waitcnt lgkmcnt(14)
	v_mfma_f32_16x16x32_f16 a[240:243], v[170:173], v[56:59], a[240:243]
	v_mfma_f32_16x16x32_f16 a[252:255], v[88:91], v[56:59], a[252:255]
	v_mfma_f32_16x16x32_f16 a[248:251], v[84:87], v[56:59], a[248:251]
	s_add_i32 s58, s54, 0xffd98000
	v_mfma_f32_16x16x32_f16 a[244:247], v[80:83], v[56:59], a[244:247]
	s_mov_b32 s14, s10
	v_mfma_f32_16x16x32_f16 a[236:239], v[170:173], v[44:47], a[236:239]
	s_mov_b32 s15, s11
	v_mfma_f32_16x16x32_f16 a[232:235], v[88:91], v[44:47], a[232:235]
	s_add_i32 s59, s54, 0xffdf0000
	v_mfma_f32_16x16x32_f16 a[228:231], v[84:87], v[44:47], a[228:231]
	buffer_load_dwordx4 v[94:97], v126, s[8:11], s58 offen
	v_mfma_f32_16x16x32_f16 a[224:227], v[80:83], v[44:47], a[224:227]
	buffer_load_dwordx4 v[98:101], v126, s[8:11], s59 offen
	v_mfma_f32_16x16x32_f16 a[220:223], v[170:173], v[28:31], a[220:223]
	buffer_load_dwordx4 v[102:105], v126, s[12:15], s58 offen
	v_mfma_f32_16x16x32_f16 a[216:219], v[88:91], v[28:31], a[216:219]
	buffer_load_dwordx4 v[110:113], v126, s[12:15], s59 offen
	v_mfma_f32_16x16x32_f16 a[212:215], v[84:87], v[28:31], a[212:215]
	s_add_i32 s58, s54, 0xffe48000
	v_mfma_f32_16x16x32_f16 a[204:207], v[80:83], v[28:31], a[204:207]
	s_add_i32 s59, s54, 0xffea0000
	v_mfma_f32_16x16x32_f16 a[172:175], v[170:173], v[12:15], a[172:175]
	buffer_load_dwordx4 v[106:109], v126, s[8:11], s58 offen
	v_mfma_f32_16x16x32_f16 a[168:171], v[88:91], v[12:15], a[168:171]
	buffer_load_dwordx4 v[114:117], v126, s[8:11], s59 offen
	v_mfma_f32_16x16x32_f16 a[164:167], v[84:87], v[12:15], a[164:167]
	buffer_load_dwordx4 v[118:121], v126, s[12:15], s58 offen
	v_mfma_f32_16x16x32_f16 a[160:163], v[80:83], v[12:15], a[160:163]
	buffer_load_dwordx4 v[138:141], v126, s[12:15], s59 offen
	v_mfma_f32_16x16x32_f16 a[140:143], v[170:173], v[4:7], a[140:143]
	s_add_i32 s58, s54, 0xffef8000
	v_mfma_f32_16x16x32_f16 a[136:139], v[88:91], v[4:7], a[136:139]
	s_add_i32 s59, s54, 0xfff50000
	v_mfma_f32_16x16x32_f16 a[132:135], v[84:87], v[4:7], a[132:135]
	buffer_load_dwordx4 v[122:125], v126, s[8:11], s58 offen
	v_mfma_f32_16x16x32_f16 a[128:131], v[80:83], v[4:7], a[128:131]
	buffer_load_dwordx4 v[142:145], v126, s[8:11], s59 offen
	v_mfma_f32_16x16x32_f16 a[108:111], v[170:173], v[0:3], a[108:111]
	buffer_load_dwordx4 v[150:153], v126, s[12:15], s58 offen
	v_mfma_f32_16x16x32_f16 a[104:107], v[88:91], v[0:3], a[104:107]
	buffer_load_dwordx4 v[158:161], v126, s[12:15], s59 offen
	v_mfma_f32_16x16x32_f16 a[100:103], v[84:87], v[0:3], a[100:103]
	s_add_i32 s58, s54, 0xfffa8000
	v_mfma_f32_16x16x32_f16 a[96:99], v[80:83], v[0:3], a[96:99]
	buffer_load_dwordx4 v[146:149], v126, s[8:11], s58 offen
	v_mfma_f32_16x16x32_f16 a[76:79], v[170:173], v[8:11], a[76:79]
	buffer_load_dwordx4 v[154:157], v126, s[8:11], s54 offen
	v_mfma_f32_16x16x32_f16 a[72:75], v[88:91], v[8:11], a[72:75]
	buffer_load_dwordx4 v[162:165], v126, s[12:15], s58 offen
	v_mfma_f32_16x16x32_f16 a[68:71], v[84:87], v[8:11], a[68:71]
	buffer_load_dwordx4 v[166:169], v126, s[12:15], s54 offen
	v_mfma_f32_16x16x32_f16 a[64:67], v[80:83], v[8:11], a[64:67]
	v_mfma_f32_16x16x32_f16 a[44:47], v[170:173], v[20:23], a[44:47]
	v_mfma_f32_16x16x32_f16 a[40:43], v[88:91], v[20:23], a[40:43]
	v_mfma_f32_16x16x32_f16 a[36:39], v[84:87], v[20:23], a[36:39]
	v_mfma_f32_16x16x32_f16 a[32:35], v[80:83], v[20:23], a[32:35]
	s_branch .LBB0_2159
.Lgw18_nl:
	s_waitcnt lgkmcnt(14)
	v_mfma_f32_16x16x32_f16 a[240:243], v[170:173], v[56:59], a[240:243]
	v_mfma_f32_16x16x32_f16 a[252:255], v[88:91], v[56:59], a[252:255]
	v_mfma_f32_16x16x32_f16 a[248:251], v[84:87], v[56:59], a[248:251]
	v_mfma_f32_16x16x32_f16 a[244:247], v[80:83], v[56:59], a[244:247]
	v_mfma_f32_16x16x32_f16 a[236:239], v[170:173], v[44:47], a[236:239]
	v_mfma_f32_16x16x32_f16 a[232:235], v[88:91], v[44:47], a[232:235]
	v_mfma_f32_16x16x32_f16 a[228:231], v[84:87], v[44:47], a[228:231]
	v_mfma_f32_16x16x32_f16 a[224:227], v[80:83], v[44:47], a[224:227]
	v_mfma_f32_16x16x32_f16 a[220:223], v[170:173], v[28:31], a[220:223]
	v_mfma_f32_16x16x32_f16 a[216:219], v[88:91], v[28:31], a[216:219]
	v_mfma_f32_16x16x32_f16 a[212:215], v[84:87], v[28:31], a[212:215]
	v_mfma_f32_16x16x32_f16 a[204:207], v[80:83], v[28:31], a[204:207]
	v_mfma_f32_16x16x32_f16 a[172:175], v[170:173], v[12:15], a[172:175]
	v_mfma_f32_16x16x32_f16 a[168:171], v[88:91], v[12:15], a[168:171]
	v_mfma_f32_16x16x32_f16 a[164:167], v[84:87], v[12:15], a[164:167]
	v_mfma_f32_16x16x32_f16 a[160:163], v[80:83], v[12:15], a[160:163]
	v_mfma_f32_16x16x32_f16 a[140:143], v[170:173], v[4:7], a[140:143]
	v_mfma_f32_16x16x32_f16 a[136:139], v[88:91], v[4:7], a[136:139]
	v_mfma_f32_16x16x32_f16 a[132:135], v[84:87], v[4:7], a[132:135]
	v_mfma_f32_16x16x32_f16 a[128:131], v[80:83], v[4:7], a[128:131]
	v_mfma_f32_16x16x32_f16 a[108:111], v[170:173], v[0:3], a[108:111]
	v_mfma_f32_16x16x32_f16 a[104:107], v[88:91], v[0:3], a[104:107]
	v_mfma_f32_16x16x32_f16 a[100:103], v[84:87], v[0:3], a[100:103]
	v_mfma_f32_16x16x32_f16 a[96:99], v[80:83], v[0:3], a[96:99]
	v_mfma_f32_16x16x32_f16 a[76:79], v[170:173], v[8:11], a[76:79]
	v_mfma_f32_16x16x32_f16 a[72:75], v[88:91], v[8:11], a[72:75]
	v_mfma_f32_16x16x32_f16 a[68:71], v[84:87], v[8:11], a[68:71]
	v_mfma_f32_16x16x32_f16 a[64:67], v[80:83], v[8:11], a[64:67]
	v_mfma_f32_16x16x32_f16 a[44:47], v[170:173], v[20:23], a[44:47]
	v_mfma_f32_16x16x32_f16 a[40:43], v[88:91], v[20:23], a[40:43]
	v_mfma_f32_16x16x32_f16 a[36:39], v[84:87], v[20:23], a[36:39]
	v_mfma_f32_16x16x32_f16 a[32:35], v[80:83], v[20:23], a[32:35]
	s_branch .LBB0_2159

; #define LD_AF(dst, ks_) _Pragma("unroll") for (int i = 0; i < 8; ++i) dst[i] = *(const h8*)(sA + i * 16 * G_LD + (ks_) * 32)
; #define LD_BF(dst, ks_, nh_) _Pragma("unroll") for (int i = 0; i < 4; ++i) dst[i] = *(const h8*)(sB + ((nh_) * 4 + i) * 16 * G_LD + (ks_) * 32)
; #define MMA_BLK(afx, bfx, nh_) _Pragma("unroll") for (int mi = 0; mi < 8; ++mi) _Pragma("unroll") for (int ni = 0; ni < 4; ++ni) mfma16_acc(acc[mi][(nh_) * 4 + ni], bfx[ni], afx[mi])
; template <class Epi>
; __device__ __forceinline__ void gemm_run(const GemmArgs g, Epi epi, char* smem) {
;     ...
;       const hf* sA = sbase + (kt & 1) * G_STAGE + (wm * 128 + fr) * G_LD + fqs;
;       const hf* sB = sbase + (kt & 1) * G_STAGE + (256 + wn * 128 + fr) * G_LD + fqs;
;       hf* st = sbase + ((kt + 1) & 1) * G_STAGE;
;       h8 afA[8], afB[8], bfA[4], bfB[4];
;     ...
;       LD_AF(afA, 0); LD_BF(bfA, 0, 0);
;       if (kt + 1 < nk) {
; #pragma unroll
;         for (int i = 0; i < 8; ++i) *(u4*)(st + (lr + 32 * i) * G_LD + lcw) = ra[i];
;       }
;       __builtin_amdgcn_sched_barrier(0);
;       LD_BF(bfB, 0, 1);
;       MMA_BLK(afA, bfA, 0);
;       __builtin_amdgcn_sched_barrier(0);
;       if (kt + 1 < nk) {
; #pragma unroll
;         for (int i = 0; i < 8; ++i) *(u4*)(st + (256 + lr + 32 * i) * G_LD + lcw) = rb[i];
;       }
;       LD_AF(afB, 1); LD_BF(bfA, 1, 0);
;       MMA_BLK(afA, bfB, 1);
;       __builtin_amdgcn_sched_barrier(0);
;       if (kt + 2 < nk) {
.LBB0_2166:
	s_bitcmp1_b32 s5, 0
	s_mov_b32 s14, s5
	s_cselect_b32 s5, 0x12000, 0
	s_add_i32 s15, s5, 16
	v_add3_u32 v106, s15, v96, v105
	v_add3_u32 v64, s15, v94, v105
	ds_read_b128 v[36:39], v106 offset:36864
	ds_read_b128 v[56:59], v64
	ds_read_b128 v[32:35], v106 offset:39168
	ds_read_b128 v[24:27], v106 offset:41472
	ds_read_b128 v[16:19], v106 offset:43776
	ds_read_b128 v[44:47], v64 offset:2304
	ds_read_b128 v[28:31], v64 offset:4608
	ds_read_b128 v[12:15], v64 offset:6912
	ds_read_b128 v[4:7], v64 offset:9216
	ds_read_b128 v[0:3], v64 offset:11520
	ds_read_b128 v[8:11], v64 offset:13824
	ds_read_b128 v[20:23], v64 offset:16128
	s_add_i32 s5, s14, 1
	s_bitcmp1_b32 s5, 0
	s_cselect_b32 s55, 0x12000, 0
	v_add_u32_e32 v40, s55, v93
	v_add_u32_e32 v41, v40, v98
	s_waitcnt vmcnt(15)
	ds_write_b128 v41, v[108:111]
	s_waitcnt vmcnt(14)
	ds_write_b128 v41, v[112:115] offset:4608
	s_waitcnt vmcnt(11)
	ds_write_b128 v41, v[120:123] offset:9216
	s_waitcnt vmcnt(10)
	ds_write_b128 v41, v[128:131] offset:13824
	s_waitcnt vmcnt(7)
	ds_write_b128 v41, v[136:139] offset:18432
	s_waitcnt vmcnt(6)
	ds_write_b128 v41, v[144:147] offset:23040
	s_waitcnt vmcnt(3)
	ds_write_b128 v41, v[148:151] offset:27648
	s_waitcnt vmcnt(2)
	ds_write_b128 v41, v[156:159] offset:32256
	ds_read_b128 v[172:175], v106 offset:46080
	ds_read_b128 v[88:91], v106 offset:48384
	ds_read_b128 v[84:87], v106 offset:50688
	ds_read_b128 v[80:83], v106 offset:52992
	s_waitcnt lgkmcnt(14)
	v_mfma_f32_16x16x32_f16 a[120:123], v[36:39], v[56:59], a[120:123]
	v_mfma_f32_16x16x32_f16 a[116:119], v[32:35], v[56:59], a[116:119]
	v_mfma_f32_16x16x32_f16 a[112:115], v[24:27], v[56:59], a[112:115]
	v_mfma_f32_16x16x32_f16 a[160:163], v[16:19], v[56:59], a[160:163]
	v_mfma_f32_16x16x32_f16 a[152:155], v[36:39], v[44:47], a[152:155]
	v_mfma_f32_16x16x32_f16 a[148:151], v[32:35], v[44:47], a[148:151]
	v_mfma_f32_16x16x32_f16 a[144:147], v[24:27], v[44:47], a[144:147]
	v_mfma_f32_16x16x32_f16 a[136:139], v[16:19], v[44:47], a[136:139]
	v_mfma_f32_16x16x32_f16 a[108:111], v[36:39], v[28:31], a[108:111]
	v_mfma_f32_16x16x32_f16 a[104:107], v[32:35], v[28:31], a[104:107]
	v_mfma_f32_16x16x32_f16 a[100:103], v[24:27], v[28:31], a[100:103]
	v_mfma_f32_16x16x32_f16 a[92:95], v[16:19], v[28:31], a[92:95]
	v_mfma_f32_16x16x32_f16 a[76:79], v[36:39], v[12:15], a[76:79]
	v_mfma_f32_16x16x32_f16 a[72:75], v[32:35], v[12:15], a[72:75]
	v_mfma_f32_16x16x32_f16 a[68:71], v[24:27], v[12:15], a[68:71]
	v_mfma_f32_16x16x32_f16 a[64:67], v[16:19], v[12:15], a[64:67]
	v_mfma_f32_16x16x32_f16 a[60:63], v[36:39], v[4:7], a[60:63]
	v_mfma_f32_16x16x32_f16 a[56:59], v[32:35], v[4:7], a[56:59]
	v_mfma_f32_16x16x32_f16 a[52:55], v[24:27], v[4:7], a[52:55]
	v_mfma_f32_16x16x32_f16 a[48:51], v[16:19], v[4:7], a[48:51]
	v_mfma_f32_16x16x32_f16 a[44:47], v[36:39], v[0:3], a[44:47]
	v_mfma_f32_16x16x32_f16 a[40:43], v[32:35], v[0:3], a[40:43]
	v_mfma_f32_16x16x32_f16 a[36:39], v[24:27], v[0:3], a[36:39]
	v_mfma_f32_16x16x32_f16 a[32:35], v[16:19], v[0:3], a[32:35]
	s_waitcnt lgkmcnt(13)
	v_mfma_f32_16x16x32_f16 a[28:31], v[36:39], v[8:11], a[28:31]
	v_mfma_f32_16x16x32_f16 a[24:27], v[32:35], v[8:11], a[24:27]
	v_mfma_f32_16x16x32_f16 a[20:23], v[24:27], v[8:11], a[20:23]
	v_mfma_f32_16x16x32_f16 a[16:19], v[16:19], v[8:11], a[16:19]
	s_waitcnt lgkmcnt(12)
	v_mfma_f32_16x16x32_f16 a[12:15], v[36:39], v[20:23], a[12:15]
	v_mfma_f32_16x16x32_f16 a[8:11], v[32:35], v[20:23], a[8:11]
	v_mfma_f32_16x16x32_f16 a[4:7], v[24:27], v[20:23], a[4:7]
	v_mfma_f32_16x16x32_f16 a[0:3], v[16:19], v[20:23], a[0:3]
	v_add_u32_e32 v16, v40, v99
	s_waitcnt vmcnt(7)
	ds_write_b128 v41, v[116:119] offset:36864
	s_waitcnt vmcnt(6)
	ds_write_b128 v41, v[124:127] offset:41472
	s_waitcnt vmcnt(5)
	ds_write_b128 v41, v[132:135] offset:46080
	s_waitcnt vmcnt(4)
	ds_write_b128 v41, v[140:143] offset:50688
	s_waitcnt vmcnt(3)
	ds_write_b128 v41, v[152:155] offset:55296
	s_waitcnt vmcnt(2)
	ds_write_b128 v41, v[160:163] offset:59904
	s_waitcnt vmcnt(1)
	ds_write_b128 v41, v[164:167] offset:64512
	s_waitcnt vmcnt(0)
	ds_write_b128 v16, v[168:171]
	ds_read_b128 v[60:63], v64 offset:64
	ds_read_b128 v[52:55], v64 offset:2368
	ds_read_b128 v[48:51], v64 offset:4672
	ds_read_b128 v[40:43], v64 offset:6976
	ds_read_b128 v[36:39], v64 offset:9280
	ds_read_b128 v[32:35], v64 offset:11584
	ds_read_b128 v[24:27], v64 offset:13888
	ds_read_b128 v[16:19], v64 offset:16192
	ds_read_b128 v[64:67], v106 offset:36928
	ds_read_b128 v[68:71], v106 offset:39232
	ds_read_b128 v[72:75], v106 offset:41536
	ds_read_b128 v[76:79], v106 offset:43840
	s_cmp_gt_u32 s14, 29
	s_cbranch_scc1 .Lgw19_nl
; #define MMA_BLK(afx, bfx, nh_) _Pragma("unroll") for (int mi = 0; mi < 8; ++mi) _Pragma("unroll") for (int ni = 0; ni < 4; ++ni) mfma16_acc(acc[mi][(nh_) * 4 + ni], bfx[ni], afx[mi])
; template <class Epi>
; __device__ __forceinline__ void gemm_run(const GemmArgs g, Epi epi, char* smem) {
;     ...
;       MMA_BLK(afA, bfB, 1);
;       __builtin_amdgcn_sched_barrier(0);
;       if (kt + 2 < nk) {
;         const int ko = (kt + 2) * 64;
; #pragma unroll
;         for (int i = 0; i < 8; ++i) { ra[i] = __builtin_amdgcn_raw_buffer_load_b128(Ars, aoff, i * astep + ko * 2, 0); rb[i] = __builtin_amdgcn_raw_buffer_load_b128(Brs, boff, i * bstep + ko * 2, 0); }
;       }
	s_waitcnt lgkmcnt(14)
	v_mfma_f32_16x16x32_f16 a[252:255], v[172:175], v[56:59], a[252:255]
	v_mfma_f32_16x16x32_f16 a[248:251], v[88:91], v[56:59], a[248:251]
	v_mfma_f32_16x16x32_f16 a[244:247], v[84:87], v[56:59], a[244:247]
	s_add_i32 s55, s1, 0xfff20000
	v_mfma_f32_16x16x32_f16 a[240:243], v[80:83], v[56:59], a[240:243]
	s_mov_b32 s14, s10
	v_mfma_f32_16x16x32_f16 a[236:239], v[172:175], v[44:47], a[236:239]
	s_mov_b32 s15, s11
	v_mfma_f32_16x16x32_f16 a[232:235], v[88:91], v[44:47], a[232:235]
	s_add_i32 s58, s1, 0xfff40000
	v_mfma_f32_16x16x32_f16 a[228:231], v[84:87], v[44:47], a[228:231]
	buffer_load_dwordx4 v[108:111], v92, s[8:11], s55 offen
	v_mfma_f32_16x16x32_f16 a[224:227], v[80:83], v[44:47], a[224:227]
	buffer_load_dwordx4 v[112:115], v92, s[8:11], s58 offen
	v_mfma_f32_16x16x32_f16 a[220:223], v[172:175], v[28:31], a[220:223]
	buffer_load_dwordx4 v[116:119], v92, s[12:15], s55 offen
	v_mfma_f32_16x16x32_f16 a[216:219], v[88:91], v[28:31], a[216:219]
	buffer_load_dwordx4 v[124:127], v92, s[12:15], s58 offen
	v_mfma_f32_16x16x32_f16 a[212:215], v[84:87], v[28:31], a[212:215]
	s_add_i32 s55, s1, 0xfff60000
	v_mfma_f32_16x16x32_f16 a[208:211], v[80:83], v[28:31], a[208:211]
	s_add_i32 s58, s1, 0xfff80000
	v_mfma_f32_16x16x32_f16 a[204:207], v[172:175], v[12:15], a[204:207]
	buffer_load_dwordx4 v[120:123], v92, s[8:11], s55 offen
	v_mfma_f32_16x16x32_f16 a[200:203], v[88:91], v[12:15], a[200:203]
	buffer_load_dwordx4 v[128:131], v92, s[8:11], s58 offen
	v_mfma_f32_16x16x32_f16 a[196:199], v[84:87], v[12:15], a[196:199]
	buffer_load_dwordx4 v[132:135], v92, s[12:15], s55 offen
	v_mfma_f32_16x16x32_f16 a[192:195], v[80:83], v[12:15], a[192:195]
	buffer_load_dwordx4 v[140:143], v92, s[12:15], s58 offen
	v_mfma_f32_16x16x32_f16 a[188:191], v[172:175], v[4:7], a[188:191]
	s_add_i32 s55, s1, 0xfffa0000
	v_mfma_f32_16x16x32_f16 a[184:187], v[88:91], v[4:7], a[184:187]
	s_add_i32 s58, s1, 0xfffc0000
	v_mfma_f32_16x16x32_f16 a[180:183], v[84:87], v[4:7], a[180:183]
	buffer_load_dwordx4 v[136:139], v92, s[8:11], s55 offen
	v_mfma_f32_16x16x32_f16 a[176:179], v[80:83], v[4:7], a[176:179]
	buffer_load_dwordx4 v[144:147], v92, s[8:11], s58 offen
	v_mfma_f32_16x16x32_f16 a[172:175], v[172:175], v[0:3], a[172:175]
	buffer_load_dwordx4 v[152:155], v92, s[12:15], s55 offen
	v_mfma_f32_16x16x32_f16 a[168:171], v[88:91], v[0:3], a[168:171]
	buffer_load_dwordx4 v[160:163], v92, s[12:15], s58 offen
	v_mfma_f32_16x16x32_f16 a[164:167], v[84:87], v[0:3], a[164:167]
	s_add_i32 s55, s1, 0xfffe0000
	v_mfma_f32_16x16x32_f16 a[156:159], v[80:83], v[0:3], a[156:159]
	buffer_load_dwordx4 v[148:151], v92, s[8:11], s55 offen
	v_mfma_f32_16x16x32_f16 a[140:143], v[172:175], v[8:11], a[140:143]
	buffer_load_dwordx4 v[156:159], v92, s[8:11], s1 offen
	v_mfma_f32_16x16x32_f16 a[132:135], v[88:91], v[8:11], a[132:135]
	buffer_load_dwordx4 v[164:167], v92, s[12:15], s55 offen
	v_mfma_f32_16x16x32_f16 a[128:131], v[84:87], v[8:11], a[128:131]
	buffer_load_dwordx4 v[168:171], v92, s[12:15], s1 offen
	v_mfma_f32_16x16x32_f16 a[124:127], v[80:83], v[8:11], a[124:127]
	v_mfma_f32_16x16x32_f16 a[96:99], v[172:175], v[20:23], a[96:99]
	v_mfma_f32_16x16x32_f16 a[88:91], v[88:91], v[20:23], a[88:91]
	v_mfma_f32_16x16x32_f16 a[84:87], v[84:87], v[20:23], a[84:87]
	v_mfma_f32_16x16x32_f16 a[80:83], v[80:83], v[20:23], a[80:83]
	s_branch .LBB0_2165

; #define LD_AF(dst, ks_) _Pragma("unroll") for (int i = 0; i < 8; ++i) dst[i] = *(const h8*)(sA + i * 16 * G_LD + (ks_) * 32)
; #define LD_BF(dst, ks_, nh_) _Pragma("unroll") for (int i = 0; i < 4; ++i) dst[i] = *(const h8*)(sB + ((nh_) * 4 + i) * 16 * G_LD + (ks_) * 32)
; #define MMA_BLK(afx, bfx, nh_) _Pragma("unroll") for (int mi = 0; mi < 8; ++mi) _Pragma("unroll") for (int ni = 0; ni < 4; ++ni) mfma16_acc(acc[mi][(nh_) * 4 + ni], bfx[ni], afx[mi])
; template <class Epi>
; __device__ __forceinline__ void gemm_run(const GemmArgs g, Epi epi, char* smem) {
;     ...
;       const hf* sA = sbase + (kt & 1) * G_STAGE + (wm * 128 + fr) * G_LD + fqs;
;       const hf* sB = sbase + (kt & 1) * G_STAGE + (256 + wn * 128 + fr) * G_LD + fqs;
;       hf* st = sbase + ((kt + 1) & 1) * G_STAGE;
;       h8 afA[8], afB[8], bfA[4], bfB[4];
;     ...
;       LD_AF(afA, 0); LD_BF(bfA, 0, 0);
;       if (kt + 1 < nk) {
; #pragma unroll
;         for (int i = 0; i < 8; ++i) *(u4*)(st + (lr + 32 * i) * G_LD + lcw) = ra[i];
;       }
;       __builtin_amdgcn_sched_barrier(0);
;       LD_BF(bfB, 0, 1);
;       MMA_BLK(afA, bfA, 0);
;       __builtin_amdgcn_sched_barrier(0);
;       if (kt + 1 < nk) {
; #pragma unroll
;         for (int i = 0; i < 8; ++i) *(u4*)(st + (256 + lr + 32 * i) * G_LD + lcw) = rb[i];
;       }
;       LD_AF(afB, 1); LD_BF(bfA, 1, 0);
;       MMA_BLK(afA, bfB, 1);
;       __builtin_amdgcn_sched_barrier(0);
;       if (kt + 2 < nk) {
.LBB0_2217:
	s_bitcmp1_b32 s38, 0
	s_cselect_b32 s11, 0x12000, 0
	s_add_i32 s11, s11, 16
	v_add3_u32 v92, s11, v130, v137
	v_add3_u32 v64, s11, v129, v137
	ds_read_b128 v[36:39], v92 offset:36864
	ds_read_b128 v[56:59], v64
	ds_read_b128 v[32:35], v92 offset:39168
	ds_read_b128 v[24:27], v92 offset:41472
	ds_read_b128 v[16:19], v92 offset:43776
	ds_read_b128 v[44:47], v64 offset:2304
	ds_read_b128 v[28:31], v64 offset:4608
	ds_read_b128 v[12:15], v64 offset:6912
	ds_read_b128 v[4:7], v64 offset:9216
	ds_read_b128 v[0:3], v64 offset:11520
	ds_read_b128 v[8:11], v64 offset:13824
	ds_read_b128 v[20:23], v64 offset:16128
	s_mov_b32 s10, s38
	s_add_i32 s38, s38, 1
	s_bitcmp1_b32 s38, 0
	s_cselect_b32 s39, 0x12000, 0
	v_add_u32_e32 v40, s39, v127
	v_add_u32_e32 v41, v40, v132
	s_waitcnt vmcnt(15)
	ds_write_b128 v41, v[94:97]
	s_waitcnt vmcnt(14)
	ds_write_b128 v41, v[98:101] offset:4608
	s_waitcnt vmcnt(11)
	ds_write_b128 v41, v[106:109] offset:9216
	s_waitcnt vmcnt(10)
	ds_write_b128 v41, v[114:117] offset:13824
	s_waitcnt vmcnt(7)
	ds_write_b128 v41, v[122:125] offset:18432
	s_waitcnt vmcnt(6)
	ds_write_b128 v41, v[142:145] offset:23040
	s_waitcnt vmcnt(3)
	ds_write_b128 v41, v[146:149] offset:27648
	s_waitcnt vmcnt(2)
	ds_write_b128 v41, v[154:157] offset:32256
	ds_read_b128 v[170:173], v92 offset:46080
	ds_read_b128 v[88:91], v92 offset:48384
	ds_read_b128 v[84:87], v92 offset:50688
	ds_read_b128 v[80:83], v92 offset:52992
	s_waitcnt lgkmcnt(14)
	v_mfma_f32_16x16x32_f16 a[208:211], v[36:39], v[56:59], a[208:211]
	v_mfma_f32_16x16x32_f16 a[200:203], v[32:35], v[56:59], a[200:203]
	v_mfma_f32_16x16x32_f16 a[196:199], v[24:27], v[56:59], a[196:199]
	v_mfma_f32_16x16x32_f16 a[192:195], v[16:19], v[56:59], a[192:195]
	v_mfma_f32_16x16x32_f16 a[188:191], v[36:39], v[44:47], a[188:191]
	v_mfma_f32_16x16x32_f16 a[184:187], v[32:35], v[44:47], a[184:187]
	v_mfma_f32_16x16x32_f16 a[180:183], v[24:27], v[44:47], a[180:183]
	v_mfma_f32_16x16x32_f16 a[176:179], v[16:19], v[44:47], a[176:179]
	v_mfma_f32_16x16x32_f16 a[156:159], v[36:39], v[28:31], a[156:159]
	v_mfma_f32_16x16x32_f16 a[152:155], v[32:35], v[28:31], a[152:155]
	v_mfma_f32_16x16x32_f16 a[148:151], v[24:27], v[28:31], a[148:151]
	v_mfma_f32_16x16x32_f16 a[144:147], v[16:19], v[28:31], a[144:147]
	v_mfma_f32_16x16x32_f16 a[124:127], v[36:39], v[12:15], a[124:127]
	v_mfma_f32_16x16x32_f16 a[120:123], v[32:35], v[12:15], a[120:123]
	v_mfma_f32_16x16x32_f16 a[116:119], v[24:27], v[12:15], a[116:119]
	v_mfma_f32_16x16x32_f16 a[112:115], v[16:19], v[12:15], a[112:115]
	v_mfma_f32_16x16x32_f16 a[92:95], v[36:39], v[4:7], a[92:95]
	v_mfma_f32_16x16x32_f16 a[88:91], v[32:35], v[4:7], a[88:91]
	v_mfma_f32_16x16x32_f16 a[84:87], v[24:27], v[4:7], a[84:87]
	v_mfma_f32_16x16x32_f16 a[80:83], v[16:19], v[4:7], a[80:83]
	v_mfma_f32_16x16x32_f16 a[60:63], v[36:39], v[0:3], a[60:63]
	v_mfma_f32_16x16x32_f16 a[56:59], v[32:35], v[0:3], a[56:59]
	v_mfma_f32_16x16x32_f16 a[52:55], v[24:27], v[0:3], a[52:55]
	v_mfma_f32_16x16x32_f16 a[48:51], v[16:19], v[0:3], a[48:51]
	s_waitcnt lgkmcnt(13)
	v_mfma_f32_16x16x32_f16 a[28:31], v[36:39], v[8:11], a[28:31]
	v_mfma_f32_16x16x32_f16 a[24:27], v[32:35], v[8:11], a[24:27]
	v_mfma_f32_16x16x32_f16 a[20:23], v[24:27], v[8:11], a[20:23]
	v_mfma_f32_16x16x32_f16 a[16:19], v[16:19], v[8:11], a[16:19]
	s_waitcnt lgkmcnt(12)
	v_mfma_f32_16x16x32_f16 a[12:15], v[36:39], v[20:23], a[12:15]
	v_mfma_f32_16x16x32_f16 a[8:11], v[32:35], v[20:23], a[8:11]
	v_mfma_f32_16x16x32_f16 a[4:7], v[24:27], v[20:23], a[4:7]
	v_mfma_f32_16x16x32_f16 a[0:3], v[16:19], v[20:23], a[0:3]
	v_add_u32_e32 v16, v40, v133
	s_waitcnt vmcnt(7)
	ds_write_b128 v41, v[102:105] offset:36864
	s_waitcnt vmcnt(6)
	ds_write_b128 v41, v[110:113] offset:41472
	s_waitcnt vmcnt(5)
	ds_write_b128 v41, v[118:121] offset:46080
	s_waitcnt vmcnt(4)
	ds_write_b128 v41, v[138:141] offset:50688
	s_waitcnt vmcnt(3)
	ds_write_b128 v41, v[150:153] offset:55296
	s_waitcnt vmcnt(2)
	ds_write_b128 v41, v[158:161] offset:59904
	s_waitcnt vmcnt(1)
	ds_write_b128 v41, v[162:165] offset:64512
	s_waitcnt vmcnt(0)
	ds_write_b128 v16, v[166:169]
	ds_read_b128 v[60:63], v64 offset:64
	ds_read_b128 v[52:55], v64 offset:2368
	ds_read_b128 v[48:51], v64 offset:4672
	ds_read_b128 v[40:43], v64 offset:6976
	ds_read_b128 v[36:39], v64 offset:9280
	ds_read_b128 v[32:35], v64 offset:11584
	ds_read_b128 v[24:27], v64 offset:13888
	ds_read_b128 v[16:19], v64 offset:16192
	ds_read_b128 v[64:67], v92 offset:36928
	ds_read_b128 v[68:71], v92 offset:39232
	ds_read_b128 v[72:75], v92 offset:41536
	ds_read_b128 v[76:79], v92 offset:43840
	s_cmpk_gt_u32 s10, 0x55
	s_cbranch_scc1 .Lgw20_nl
; #define MMA_BLK(afx, bfx, nh_) _Pragma("unroll") for (int mi = 0; mi < 8; ++mi) _Pragma("unroll") for (int ni = 0; ni < 4; ++ni) mfma16_acc(acc[mi][(nh_) * 4 + ni], bfx[ni], afx[mi])
; template <class Epi>
; __device__ __forceinline__ void gemm_run(const GemmArgs g, Epi epi, char* smem) {
;     ...
;       MMA_BLK(afA, bfB, 1);
;       __builtin_amdgcn_sched_barrier(0);
;       if (kt + 2 < nk) {
;         const int ko = (kt + 2) * 64;
; #pragma unroll
;         for (int i = 0; i < 8; ++i) { ra[i] = __builtin_amdgcn_raw_buffer_load_b128(Ars, aoff, i * astep + ko * 2, 0); rb[i] = __builtin_amdgcn_raw_buffer_load_b128(Brs, boff, i * bstep + ko * 2, 0); }
;       }
	s_waitcnt lgkmcnt(14)
	v_mfma_f32_16x16x32_f16 a[240:243], v[170:173], v[56:59], a[240:243]
	v_mfma_f32_16x16x32_f16 a[252:255], v[88:91], v[56:59], a[252:255]
	v_mfma_f32_16x16x32_f16 a[248:251], v[84:87], v[56:59], a[248:251]
	s_add_i32 s39, s37, 0xffd98000
	v_mfma_f32_16x16x32_f16 a[244:247], v[80:83], v[56:59], a[244:247]
	s_mov_b32 s10, s6
	v_mfma_f32_16x16x32_f16 a[236:239], v[170:173], v[44:47], a[236:239]
	s_mov_b32 s11, s7
	v_mfma_f32_16x16x32_f16 a[232:235], v[88:91], v[44:47], a[232:235]
	s_add_i32 s40, s37, 0xffdf0000
	v_mfma_f32_16x16x32_f16 a[228:231], v[84:87], v[44:47], a[228:231]
	buffer_load_dwordx4 v[94:97], v126, s[4:7], s39 offen
	v_mfma_f32_16x16x32_f16 a[224:227], v[80:83], v[44:47], a[224:227]
	buffer_load_dwordx4 v[98:101], v126, s[4:7], s40 offen
	v_mfma_f32_16x16x32_f16 a[220:223], v[170:173], v[28:31], a[220:223]
	buffer_load_dwordx4 v[102:105], v126, s[8:11], s39 offen
	v_mfma_f32_16x16x32_f16 a[216:219], v[88:91], v[28:31], a[216:219]
	buffer_load_dwordx4 v[110:113], v126, s[8:11], s40 offen
	v_mfma_f32_16x16x32_f16 a[212:215], v[84:87], v[28:31], a[212:215]
	s_add_i32 s39, s37, 0xffe48000
	v_mfma_f32_16x16x32_f16 a[204:207], v[80:83], v[28:31], a[204:207]
	s_add_i32 s40, s37, 0xffea0000
	v_mfma_f32_16x16x32_f16 a[172:175], v[170:173], v[12:15], a[172:175]
	buffer_load_dwordx4 v[106:109], v126, s[4:7], s39 offen
	v_mfma_f32_16x16x32_f16 a[168:171], v[88:91], v[12:15], a[168:171]
	buffer_load_dwordx4 v[114:117], v126, s[4:7], s40 offen
	v_mfma_f32_16x16x32_f16 a[164:167], v[84:87], v[12:15], a[164:167]
	buffer_load_dwordx4 v[118:121], v126, s[8:11], s39 offen
	v_mfma_f32_16x16x32_f16 a[160:163], v[80:83], v[12:15], a[160:163]
	buffer_load_dwordx4 v[138:141], v126, s[8:11], s40 offen
	v_mfma_f32_16x16x32_f16 a[140:143], v[170:173], v[4:7], a[140:143]
	s_add_i32 s39, s37, 0xffef8000
	v_mfma_f32_16x16x32_f16 a[136:139], v[88:91], v[4:7], a[136:139]
	s_add_i32 s40, s37, 0xfff50000
	v_mfma_f32_16x16x32_f16 a[132:135], v[84:87], v[4:7], a[132:135]
	buffer_load_dwordx4 v[122:125], v126, s[4:7], s39 offen
	v_mfma_f32_16x16x32_f16 a[128:131], v[80:83], v[4:7], a[128:131]
	buffer_load_dwordx4 v[142:145], v126, s[4:7], s40 offen
	v_mfma_f32_16x16x32_f16 a[108:111], v[170:173], v[0:3], a[108:111]
	buffer_load_dwordx4 v[150:153], v126, s[8:11], s39 offen
	v_mfma_f32_16x16x32_f16 a[104:107], v[88:91], v[0:3], a[104:107]
	buffer_load_dwordx4 v[158:161], v126, s[8:11], s40 offen
	v_mfma_f32_16x16x32_f16 a[100:103], v[84:87], v[0:3], a[100:103]
	s_add_i32 s39, s37, 0xfffa8000
	v_mfma_f32_16x16x32_f16 a[96:99], v[80:83], v[0:3], a[96:99]
	buffer_load_dwordx4 v[146:149], v126, s[4:7], s39 offen
	v_mfma_f32_16x16x32_f16 a[76:79], v[170:173], v[8:11], a[76:79]
	buffer_load_dwordx4 v[154:157], v126, s[4:7], s37 offen
	v_mfma_f32_16x16x32_f16 a[72:75], v[88:91], v[8:11], a[72:75]
	buffer_load_dwordx4 v[162:165], v126, s[8:11], s39 offen
	v_mfma_f32_16x16x32_f16 a[68:71], v[84:87], v[8:11], a[68:71]
	buffer_load_dwordx4 v[166:169], v126, s[8:11], s37 offen
	v_mfma_f32_16x16x32_f16 a[64:67], v[80:83], v[8:11], a[64:67]
	v_mfma_f32_16x16x32_f16 a[44:47], v[170:173], v[20:23], a[44:47]
	v_mfma_f32_16x16x32_f16 a[40:43], v[88:91], v[20:23], a[40:43]
	v_mfma_f32_16x16x32_f16 a[36:39], v[84:87], v[20:23], a[36:39]
	v_mfma_f32_16x16x32_f16 a[32:35], v[80:83], v[20:23], a[32:35]
	s_branch .LBB0_2216
